# stack on v58: S5 image pitch 288 B + loop-edge increments at end of last load segment + tail MFMAs at priority 3
# speedup vs baseline: 1.0024x; 1.0004x over previous
; #define PG8_STAGE(bufoff, gbase, voff) do { _Pragma("unroll") for (int _i = 0; _i < 2; ++_i) \
;         __builtin_amdgcn_global_load_lds((const unsigned*)((const char*)(gbase) + (voff)[_i]), (PG8_LAS unsigned*)(lds + (bufoff) + ldsw + _i * 8192), 16, 0, 0); } while (0)
; #define PG8_LDA(dst, b, h) do { _Pragma("unroll") for (int m = 0; m < 4; ++m) _Pragma("unroll") for (int k = 0; k < 2; ++k) dst[m][k] = *(const PG8_LAS bf16x8*)(lds + PG8_SA(b, h) + aoff + m * 2048 + k * 1024); } while (0)
; #define PG8_LDB(dst, b, h) do { _Pragma("unroll") for (int n = 0; n < 2; ++n) _Pragma("unroll") for (int k = 0; k < 2; ++k) dst[n][k] = *(const PG8_LAS bf16x8*)(lds + PG8_SB(b, h) + boff + n * 2048 + k * 1024); } while (0)
; #define PG8_MMA(ai, bj, At, Bt) do { __builtin_amdgcn_s_setprio(1); _Pragma("unroll") for (int m = 0; m < 4; ++m) _Pragma("unroll") for (int n = 0; n < 2; ++n) _Pragma("unroll") for (int k = 0; k < 2; ++k) \
;         acc[ai][bj][m][n] = __builtin_amdgcn_mfma_f32_16x16x32_bf16(Bt[n][k], At[m][k], acc[ai][bj][m][n], 0, 0, 0); __builtin_amdgcn_s_setprio(0); } while (0)
; #define PG8_WAIT_V(n) asm volatile("s_waitcnt vmcnt(" #n ")" ::: "memory")
; #define PG8_WAIT_L(n) asm volatile("s_waitcnt lgkmcnt(" #n ")" ::: "memory")
; #define PG8_BAR __builtin_amdgcn_s_barrier()
; template <class Epi, class Sched, bool ALIGN_EPI = false, bool SP2 = false>
; __device__ __forceinline__ void gemm_phase(PG8_LAS unsigned char* lds, const Gemm g, const Sched& S, const Epi& E) {
;     ...
;             const char* a1 = cA + (size_t)(t + 1) * kstep;
;             const char* a2 = last ? nA : cA + (size_t)(t + 2) * kstep; const char* b2 = last ? nB : cB + (size_t)(t + 2) * kstep;
;             const char* a3 = a2 + kstep; const char* b3 = b2 + kstep;
;             if (last && has_next) S.a_ready(nxt);
;             if constexpr (SP2) {
;             PG8_LDB(B0, 0, 0); PG8_LDB(B1, 0, 1); PG8_SCHED; PG8_LDA(At, 0, 0); PG8_STAGE(PG8_SA(1, 1), a1 + hstep, voffA);
;             PG8_WAIT_V(8); PG8_WAIT_L(0); PG8_BAR; PG8_MMA(0, 0, At, B0); PG8_MMA(0, 1, At, B1); PG8_BAR; PG8_SCHED;
;             PG8_LDA(At, 0, 1); PG8_STAGE(PG8_SB(0, 0), b2, voffB); PG8_STAGE(PG8_SB(0, 1), b2 + hstep, voffB); PG8_STAGE(PG8_SA(0, 0), a2, voffA);
;             PG8_WAIT_V(8); PG8_WAIT_L(0); PG8_BAR; PG8_MMA(1, 0, At, B0); PG8_MMA(1, 1, At, B1); PG8_BAR; PG8_SCHED;
.LBB0_110:
	ds_read_b128 v[136:139], v161
	ds_read_b128 v[140:143], v161 offset:1024
	ds_read_b128 v[176:179], v161 offset:2048
	ds_read_b128 v[180:183], v161 offset:3072
	ds_read_b128 v[184:187], v162
	ds_read_b128 v[202:205], v162 offset:1024
	ds_read_b128 v[206:209], v162 offset:2048
	ds_read_b128 v[210:213], v162 offset:3072
	s_add_u32 s28, s52, 0xfff80080
	s_addc_u32 s29, s53, -1
	s_cmp_eq_u32 s74, 28
	s_cselect_b32 s49, s25, s29
	s_cselect_b32 s48, s34, s28
	s_cselect_b32 s29, s23, s73
	s_cselect_b32 s28, s35, s72
	v_lshl_add_u64 v[246:247], s[52:53], 0, v[128:129]
	s_add_i32 m0, s9, 0xc000
	ds_read_b128 v[214:217], v163
	ds_read_b128 v[218:221], v163 offset:1024
	ds_read_b128 v[222:225], v163 offset:2048
	ds_read_b128 v[226:229], v163 offset:3072
	ds_read_b128 v[230:233], v163 offset:4096
	ds_read_b128 v[234:237], v163 offset:5120
	ds_read_b128 v[238:241], v163 offset:6144
	ds_read_b128 v[242:245], v163 offset:7168
	global_load_lds_dwordx4 v[246:247], off
	v_lshl_add_u64 v[246:247], s[52:53], 0, v[130:131]
	s_add_i32 m0, s9, 0xe000
	s_nop 0
	global_load_lds_dwordx4 v[246:247], off
	s_waitcnt vmcnt(8)
	s_waitcnt lgkmcnt(0)
	s_barrier
	s_setprio 1
	s_waitcnt lgkmcnt(0)
	v_mfma_f32_16x16x32_bf16 v[124:127], v[136:139], v[214:217], v[124:127]
	v_mfma_f32_16x16x32_bf16 v[124:127], v[140:143], v[218:221], v[124:127]
	v_mfma_f32_16x16x32_bf16 v[120:123], v[180:183], v[218:221], v[120:123]
	v_mfma_f32_16x16x32_bf16 v[120:123], v[176:179], v[214:217], v[120:123]
	v_mfma_f32_16x16x32_bf16 v[116:119], v[184:187], v[214:217], v[116:119]
	v_mfma_f32_16x16x32_bf16 v[116:119], v[202:205], v[218:221], v[116:119]
	v_mfma_f32_16x16x32_bf16 v[112:115], v[210:213], v[218:221], v[112:115]
	v_mfma_f32_16x16x32_bf16 v[112:115], v[206:209], v[214:217], v[112:115]
	v_mfma_f32_16x16x32_bf16 v[92:95], v[206:209], v[222:225], v[92:95]
	v_mfma_f32_16x16x32_bf16 v[92:95], v[210:213], v[226:229], v[92:95]
	v_mfma_f32_16x16x32_bf16 v[100:103], v[202:205], v[226:229], v[100:103]
	v_mfma_f32_16x16x32_bf16 v[100:103], v[184:187], v[222:225], v[100:103]
	v_mfma_f32_16x16x32_bf16 v[104:107], v[176:179], v[222:225], v[104:107]
	v_mfma_f32_16x16x32_bf16 v[104:107], v[180:183], v[226:229], v[104:107]
	v_mfma_f32_16x16x32_bf16 v[108:111], v[140:143], v[226:229], v[108:111]
	v_mfma_f32_16x16x32_bf16 v[108:111], v[136:139], v[222:225], v[108:111]
	s_setprio 0
	s_setprio 1
	v_mfma_f32_16x16x32_bf16 v[96:99], v[136:139], v[230:233], v[96:99]
	v_mfma_f32_16x16x32_bf16 v[96:99], v[140:143], v[234:237], v[96:99]
	v_mfma_f32_16x16x32_bf16 v[88:91], v[180:183], v[234:237], v[88:91]
	v_mfma_f32_16x16x32_bf16 v[88:91], v[176:179], v[230:233], v[88:91]
	v_mfma_f32_16x16x32_bf16 v[84:87], v[184:187], v[230:233], v[84:87]
	v_mfma_f32_16x16x32_bf16 v[84:87], v[202:205], v[234:237], v[84:87]
	v_mfma_f32_16x16x32_bf16 v[76:79], v[210:213], v[234:237], v[76:79]
	v_mfma_f32_16x16x32_bf16 v[76:79], v[206:209], v[230:233], v[76:79]
	v_mfma_f32_16x16x32_bf16 v[64:67], v[206:209], v[238:241], v[64:67]
	v_mfma_f32_16x16x32_bf16 v[64:67], v[210:213], v[242:245], v[64:67]
	v_mfma_f32_16x16x32_bf16 v[68:71], v[202:205], v[242:245], v[68:71]
	v_mfma_f32_16x16x32_bf16 v[68:71], v[184:187], v[238:241], v[68:71]
	v_mfma_f32_16x16x32_bf16 v[72:75], v[176:179], v[238:241], v[72:75]
	v_mfma_f32_16x16x32_bf16 v[72:75], v[180:183], v[242:245], v[72:75]
	s_setprio 3
	s_barrier
	v_mfma_f32_16x16x32_bf16 v[80:83], v[140:143], v[242:245], v[80:83]
	v_mfma_f32_16x16x32_bf16 v[80:83], v[136:139], v[238:241], v[80:83]
	s_setprio 0
	s_add_i32 s75, s63, s45
	v_lshl_add_u64 v[246:247], s[28:29], 0, v[166:167]
	s_mov_b32 m0, s75
	ds_read_b128 v[214:217], v163 offset:16384
	ds_read_b128 v[218:221], v163 offset:17408
	ds_read_b128 v[222:225], v163 offset:18432
	ds_read_b128 v[226:229], v163 offset:19456
	ds_read_b128 v[230:233], v163 offset:20480
	ds_read_b128 v[234:237], v163 offset:21504
	ds_read_b128 v[238:241], v163 offset:22528
	ds_read_b128 v[242:245], v163 offset:23552
	global_load_lds_dwordx4 v[246:247], off
	s_add_i32 m0, s75, 0x2000
	s_add_u32 s76, s28, 0x80000
	v_lshl_add_u64 v[248:249], s[28:29], 0, v[170:171]
	s_addc_u32 s77, s29, 0
	s_add_i32 s75, s64, s45
	global_load_lds_dwordx4 v[248:249], off
	v_lshl_add_u64 v[250:251], s[76:77], 0, v[166:167]
	s_mov_b32 m0, s75
	v_lshl_add_u64 v[252:253], s[48:49], 0, v[168:169]
	global_load_lds_dwordx4 v[250:251], off
	v_lshl_add_u64 v[250:251], s[76:77], 0, v[170:171]
	s_add_i32 m0, s75, 0x2000
	s_nop 0
	global_load_lds_dwordx4 v[250:251], off
	v_lshl_add_u64 v[250:251], s[48:49], 0, v[164:165]
	s_mov_b32 m0, s9
	s_nop 0
	global_load_lds_dwordx4 v[250:251], off
	s_mov_b32 m0, s57
	s_nop 0
	global_load_lds_dwordx4 v[252:253], off
	s_waitcnt vmcnt(8)
	s_waitcnt lgkmcnt(0)
	s_barrier
; #define PG8_STAGE(bufoff, gbase, voff) do { _Pragma("unroll") for (int _i = 0; _i < 2; ++_i) \
;         __builtin_amdgcn_global_load_lds((const unsigned*)((const char*)(gbase) + (voff)[_i]), (PG8_LAS unsigned*)(lds + (bufoff) + ldsw + _i * 8192), 16, 0, 0); } while (0)
; #define PG8_LDA(dst, b, h) do { _Pragma("unroll") for (int m = 0; m < 4; ++m) _Pragma("unroll") for (int k = 0; k < 2; ++k) dst[m][k] = *(const PG8_LAS bf16x8*)(lds + PG8_SA(b, h) + aoff + m * 2048 + k * 1024); } while (0)
; #define PG8_LDB(dst, b, h) do { _Pragma("unroll") for (int n = 0; n < 2; ++n) _Pragma("unroll") for (int k = 0; k < 2; ++k) dst[n][k] = *(const PG8_LAS bf16x8*)(lds + PG8_SB(b, h) + boff + n * 2048 + k * 1024); } while (0)
; #define PG8_MMA(ai, bj, At, Bt) do { __builtin_amdgcn_s_setprio(1); _Pragma("unroll") for (int m = 0; m < 4; ++m) _Pragma("unroll") for (int n = 0; n < 2; ++n) _Pragma("unroll") for (int k = 0; k < 2; ++k) \
;         acc[ai][bj][m][n] = __builtin_amdgcn_mfma_f32_16x16x32_bf16(Bt[n][k], At[m][k], acc[ai][bj][m][n], 0, 0, 0); __builtin_amdgcn_s_setprio(0); } while (0)
; #define PG8_WAIT_V(n) asm volatile("s_waitcnt vmcnt(" #n ")" ::: "memory")
; #define PG8_WAIT_L(n) asm volatile("s_waitcnt lgkmcnt(" #n ")" ::: "memory")
; #define PG8_BAR __builtin_amdgcn_s_barrier()
; #define PG8_SCHED __builtin_amdgcn_sched_barrier(0)
; template <class Epi, class Sched, bool ALIGN_EPI = false, bool SP2 = false>
; __device__ __forceinline__ void gemm_phase(PG8_LAS unsigned char* lds, const Gemm g, const Sched& S, const Epi& E) {
;     ...
;             PG8_WAIT_V(8); PG8_WAIT_L(0); PG8_BAR; PG8_MMA(1, 0, At, B0); PG8_MMA(1, 1, At, B1); PG8_BAR; PG8_SCHED;
;             PG8_LDB(B0, 1, 0); PG8_LDB(B1, 1, 1); PG8_SCHED; PG8_LDA(At, 1, 0); PG8_STAGE(PG8_SA(0, 1), a2 + hstep, voffA);
;             PG8_WAIT_V(8); PG8_WAIT_L(0); PG8_BAR; PG8_MMA(0, 0, At, B0); PG8_MMA(0, 1, At, B1); PG8_BAR; PG8_SCHED;
	s_setprio 1
	s_waitcnt lgkmcnt(0)
	v_mfma_f32_16x16x32_bf16 v[60:63], v[136:139], v[214:217], v[60:63]
	v_mfma_f32_16x16x32_bf16 v[60:63], v[140:143], v[218:221], v[60:63]
	v_mfma_f32_16x16x32_bf16 v[56:59], v[180:183], v[218:221], v[56:59]
	v_mfma_f32_16x16x32_bf16 v[56:59], v[176:179], v[214:217], v[56:59]
	v_mfma_f32_16x16x32_bf16 v[52:55], v[184:187], v[214:217], v[52:55]
	v_mfma_f32_16x16x32_bf16 v[52:55], v[202:205], v[218:221], v[52:55]
	v_mfma_f32_16x16x32_bf16 v[44:47], v[210:213], v[218:221], v[44:47]
	v_mfma_f32_16x16x32_bf16 v[44:47], v[206:209], v[214:217], v[44:47]
	v_mfma_f32_16x16x32_bf16 v[28:31], v[206:209], v[222:225], v[28:31]
	v_mfma_f32_16x16x32_bf16 v[28:31], v[210:213], v[226:229], v[28:31]
	v_mfma_f32_16x16x32_bf16 v[36:39], v[202:205], v[226:229], v[36:39]
	v_mfma_f32_16x16x32_bf16 v[36:39], v[184:187], v[222:225], v[36:39]
	v_mfma_f32_16x16x32_bf16 v[40:43], v[176:179], v[222:225], v[40:43]
	v_mfma_f32_16x16x32_bf16 v[40:43], v[180:183], v[226:229], v[40:43]
	v_mfma_f32_16x16x32_bf16 v[48:51], v[140:143], v[226:229], v[48:51]
	v_mfma_f32_16x16x32_bf16 v[48:51], v[136:139], v[222:225], v[48:51]
	s_setprio 0
	s_setprio 1
	v_mfma_f32_16x16x32_bf16 v[32:35], v[136:139], v[230:233], v[32:35]
	v_mfma_f32_16x16x32_bf16 v[32:35], v[140:143], v[234:237], v[32:35]
	v_mfma_f32_16x16x32_bf16 v[24:27], v[180:183], v[234:237], v[24:27]
	v_mfma_f32_16x16x32_bf16 v[24:27], v[176:179], v[230:233], v[24:27]
	v_mfma_f32_16x16x32_bf16 v[20:23], v[184:187], v[230:233], v[20:23]
	v_mfma_f32_16x16x32_bf16 v[20:23], v[202:205], v[234:237], v[20:23]
	v_mfma_f32_16x16x32_bf16 v[16:19], v[210:213], v[234:237], v[16:19]
	v_mfma_f32_16x16x32_bf16 v[16:19], v[206:209], v[230:233], v[16:19]
	v_mfma_f32_16x16x32_bf16 v[0:3], v[206:209], v[238:241], v[0:3]
	v_mfma_f32_16x16x32_bf16 v[0:3], v[210:213], v[242:245], v[0:3]
	v_mfma_f32_16x16x32_bf16 v[4:7], v[202:205], v[242:245], v[4:7]
	v_mfma_f32_16x16x32_bf16 v[4:7], v[184:187], v[238:241], v[4:7]
	v_mfma_f32_16x16x32_bf16 v[8:11], v[176:179], v[238:241], v[8:11]
	v_mfma_f32_16x16x32_bf16 v[8:11], v[180:183], v[242:245], v[8:11]
	s_setprio 3
	s_barrier
	v_mfma_f32_16x16x32_bf16 v[12:15], v[140:143], v[242:245], v[12:15]
	v_mfma_f32_16x16x32_bf16 v[12:15], v[136:139], v[238:241], v[12:15]
	s_setprio 0
	s_add_i32 s75, 0, 0x18000
	v_add_u32_e32 v144, s75, v151
	s_add_i32 s76, 0, 0x1c000
	ds_read_b128 v[136:139], v144
	ds_read_b128 v[140:143], v144 offset:1024
	ds_read_b128 v[176:179], v144 offset:2048
	ds_read_b128 v[180:183], v144 offset:3072
	v_add_u32_e32 v144, s76, v151
	ds_read_b128 v[184:187], v144
	ds_read_b128 v[202:205], v144 offset:1024
	ds_read_b128 v[206:209], v144 offset:2048
	ds_read_b128 v[210:213], v144 offset:3072
	s_add_u32 s48, s48, 0x80000
	s_addc_u32 s49, s49, 0
	s_mov_b32 m0, s58
	v_lshl_add_u64 v[200:201], s[48:49], 0, v[164:165]
	ds_read_b128 v[214:217], v163 offset:32768
	ds_read_b128 v[218:221], v163 offset:33792
	ds_read_b128 v[222:225], v163 offset:34816
	ds_read_b128 v[226:229], v163 offset:35840
	ds_read_b128 v[230:233], v163 offset:36864
	ds_read_b128 v[234:237], v163 offset:37888
	ds_read_b128 v[238:241], v163 offset:38912
	ds_read_b128 v[242:245], v163 offset:39936
	global_load_lds_dwordx4 v[200:201], off
	v_lshl_add_u64 v[200:201], s[48:49], 0, v[168:169]
	s_mov_b32 m0, s59
	s_nop 0
	global_load_lds_dwordx4 v[200:201], off
	s_waitcnt vmcnt(8)
	s_waitcnt lgkmcnt(0)
	s_barrier
	s_setprio 1
	s_waitcnt lgkmcnt(0)
	v_mfma_f32_16x16x32_bf16 v[124:127], v[136:139], v[214:217], v[124:127]
	v_mfma_f32_16x16x32_bf16 v[124:127], v[140:143], v[218:221], v[124:127]
	v_mfma_f32_16x16x32_bf16 v[120:123], v[180:183], v[218:221], v[120:123]
	v_mfma_f32_16x16x32_bf16 v[120:123], v[176:179], v[214:217], v[120:123]
	v_mfma_f32_16x16x32_bf16 v[116:119], v[184:187], v[214:217], v[116:119]
	v_mfma_f32_16x16x32_bf16 v[116:119], v[202:205], v[218:221], v[116:119]
	v_mfma_f32_16x16x32_bf16 v[112:115], v[210:213], v[218:221], v[112:115]
	v_mfma_f32_16x16x32_bf16 v[112:115], v[206:209], v[214:217], v[112:115]
	v_mfma_f32_16x16x32_bf16 v[92:95], v[206:209], v[222:225], v[92:95]
	v_mfma_f32_16x16x32_bf16 v[92:95], v[210:213], v[226:229], v[92:95]
	v_mfma_f32_16x16x32_bf16 v[100:103], v[202:205], v[226:229], v[100:103]
	v_mfma_f32_16x16x32_bf16 v[100:103], v[184:187], v[222:225], v[100:103]
	v_mfma_f32_16x16x32_bf16 v[104:107], v[176:179], v[222:225], v[104:107]
	v_mfma_f32_16x16x32_bf16 v[104:107], v[180:183], v[226:229], v[104:107]
	v_mfma_f32_16x16x32_bf16 v[108:111], v[140:143], v[226:229], v[108:111]
	v_mfma_f32_16x16x32_bf16 v[108:111], v[136:139], v[222:225], v[108:111]
	s_setprio 0
	s_setprio 1
	v_mfma_f32_16x16x32_bf16 v[96:99], v[136:139], v[230:233], v[96:99]
	v_mfma_f32_16x16x32_bf16 v[96:99], v[140:143], v[234:237], v[96:99]
	v_mfma_f32_16x16x32_bf16 v[88:91], v[180:183], v[234:237], v[88:91]
	v_mfma_f32_16x16x32_bf16 v[88:91], v[176:179], v[230:233], v[88:91]
	v_mfma_f32_16x16x32_bf16 v[84:87], v[184:187], v[230:233], v[84:87]
	v_mfma_f32_16x16x32_bf16 v[84:87], v[202:205], v[234:237], v[84:87]
	v_mfma_f32_16x16x32_bf16 v[76:79], v[210:213], v[234:237], v[76:79]
	v_mfma_f32_16x16x32_bf16 v[76:79], v[206:209], v[230:233], v[76:79]
	v_mfma_f32_16x16x32_bf16 v[64:67], v[206:209], v[238:241], v[64:67]
	v_mfma_f32_16x16x32_bf16 v[64:67], v[210:213], v[242:245], v[64:67]
	v_mfma_f32_16x16x32_bf16 v[68:71], v[202:205], v[242:245], v[68:71]
	v_mfma_f32_16x16x32_bf16 v[68:71], v[184:187], v[238:241], v[68:71]
	v_mfma_f32_16x16x32_bf16 v[72:75], v[176:179], v[238:241], v[72:75]
	v_mfma_f32_16x16x32_bf16 v[72:75], v[180:183], v[242:245], v[72:75]
	s_setprio 3
	s_barrier
; #define PG8_STAGE(bufoff, gbase, voff) do { _Pragma("unroll") for (int _i = 0; _i < 2; ++_i) \
;         __builtin_amdgcn_global_load_lds((const unsigned*)((const char*)(gbase) + (voff)[_i]), (PG8_LAS unsigned*)(lds + (bufoff) + ldsw + _i * 8192), 16, 0, 0); } while (0)
; #define PG8_LDA(dst, b, h) do { _Pragma("unroll") for (int m = 0; m < 4; ++m) _Pragma("unroll") for (int k = 0; k < 2; ++k) dst[m][k] = *(const PG8_LAS bf16x8*)(lds + PG8_SA(b, h) + aoff + m * 2048 + k * 1024); } while (0)
; #define PG8_MMA(ai, bj, At, Bt) do { __builtin_amdgcn_s_setprio(1); _Pragma("unroll") for (int m = 0; m < 4; ++m) _Pragma("unroll") for (int n = 0; n < 2; ++n) _Pragma("unroll") for (int k = 0; k < 2; ++k) \
;         acc[ai][bj][m][n] = __builtin_amdgcn_mfma_f32_16x16x32_bf16(Bt[n][k], At[m][k], acc[ai][bj][m][n], 0, 0, 0); __builtin_amdgcn_s_setprio(0); } while (0)
; #define PG8_WAIT_V(n) asm volatile("s_waitcnt vmcnt(" #n ")" ::: "memory")
; #define PG8_WAIT_L(n) asm volatile("s_waitcnt lgkmcnt(" #n ")" ::: "memory")
; #define PG8_BAR __builtin_amdgcn_s_barrier()
; #define PG8_SCHED __builtin_amdgcn_sched_barrier(0)
; template <class Epi, class Sched, bool ALIGN_EPI = false, bool SP2 = false>
; __device__ __forceinline__ void gemm_phase(PG8_LAS unsigned char* lds, const Gemm g, const Sched& S, const Epi& E) {
;     ...
;         for (int t = 0; t < nt; t += 2) {
;     ...
;             PG8_LDA(At, 1, 1); PG8_STAGE(PG8_SB(1, 0), b3, voffB); PG8_STAGE(PG8_SB(1, 1), b3 + hstep, voffB); PG8_STAGE(PG8_SA(1, 0), a3, voffA);
;             PG8_WAIT_V(8); PG8_WAIT_L(0); PG8_BAR; PG8_MMA(1, 0, At, B0); PG8_MMA(1, 1, At, B1); PG8_BAR; PG8_SCHED;
	v_mfma_f32_16x16x32_bf16 v[80:83], v[140:143], v[242:245], v[80:83]
	v_mfma_f32_16x16x32_bf16 v[80:83], v[136:139], v[238:241], v[80:83]
	s_setprio 0
	s_add_i32 s48, s75, s45
	v_lshl_add_u64 v[200:201], v[246:247], 0, s[18:19]
	s_mov_b32 m0, s48
	ds_read_b128 v[214:217], v163 offset:49152
	ds_read_b128 v[218:221], v163 offset:50176
	ds_read_b128 v[222:225], v163 offset:51200
	ds_read_b128 v[226:229], v163 offset:52224
	ds_read_b128 v[230:233], v163 offset:53248
	ds_read_b128 v[234:237], v163 offset:54272
	ds_read_b128 v[238:241], v163 offset:55296
	ds_read_b128 v[242:245], v163 offset:56320
	global_load_lds_dwordx4 v[200:201], off
	s_add_i32 m0, s48, 0x2000
	s_add_u32 s28, s28, 0x80080
	v_lshl_add_u64 v[200:201], v[248:249], 0, s[18:19]
	s_addc_u32 s29, s29, 0
	s_add_i32 s48, s76, s45
	global_load_lds_dwordx4 v[200:201], off
	v_lshl_add_u64 v[200:201], s[28:29], 0, v[166:167]
	s_mov_b32 m0, s48
	s_nop 0
	global_load_lds_dwordx4 v[200:201], off
	v_lshl_add_u64 v[200:201], s[28:29], 0, v[170:171]
	s_add_i32 m0, s48, 0x2000
	s_nop 0
	global_load_lds_dwordx4 v[200:201], off
	v_lshl_add_u64 v[200:201], v[250:251], 0, s[18:19]
	s_mov_b32 m0, s61
	s_nop 0
	global_load_lds_dwordx4 v[200:201], off
	v_lshl_add_u64 v[200:201], v[252:253], 0, s[18:19]
	s_mov_b32 m0, s62
	s_nop 0
	global_load_lds_dwordx4 v[200:201], off
	s_add_i32 s74, s74, 2
	s_add_u32 s52, s52, 0x100
	s_addc_u32 s53, s53, 0
	s_add_u32 s72, s72, 0x100
	s_addc_u32 s73, s73, 0
	s_waitcnt vmcnt(8)
	s_waitcnt lgkmcnt(0)
	s_barrier
	s_setprio 1
	s_waitcnt lgkmcnt(0)
	v_mfma_f32_16x16x32_bf16 v[60:63], v[136:139], v[214:217], v[60:63]
	v_mfma_f32_16x16x32_bf16 v[60:63], v[140:143], v[218:221], v[60:63]
	v_mfma_f32_16x16x32_bf16 v[56:59], v[180:183], v[218:221], v[56:59]
	v_mfma_f32_16x16x32_bf16 v[56:59], v[176:179], v[214:217], v[56:59]
	v_mfma_f32_16x16x32_bf16 v[52:55], v[184:187], v[214:217], v[52:55]
	v_mfma_f32_16x16x32_bf16 v[52:55], v[202:205], v[218:221], v[52:55]
	v_mfma_f32_16x16x32_bf16 v[44:47], v[210:213], v[218:221], v[44:47]
	v_mfma_f32_16x16x32_bf16 v[44:47], v[206:209], v[214:217], v[44:47]
	v_mfma_f32_16x16x32_bf16 v[28:31], v[206:209], v[222:225], v[28:31]
	v_mfma_f32_16x16x32_bf16 v[28:31], v[210:213], v[226:229], v[28:31]
	v_mfma_f32_16x16x32_bf16 v[36:39], v[202:205], v[226:229], v[36:39]
	v_mfma_f32_16x16x32_bf16 v[36:39], v[184:187], v[222:225], v[36:39]
	v_mfma_f32_16x16x32_bf16 v[40:43], v[176:179], v[222:225], v[40:43]
	v_mfma_f32_16x16x32_bf16 v[40:43], v[180:183], v[226:229], v[40:43]
	v_mfma_f32_16x16x32_bf16 v[48:51], v[140:143], v[226:229], v[48:51]
	v_mfma_f32_16x16x32_bf16 v[48:51], v[136:139], v[222:225], v[48:51]
	s_setprio 0
	s_setprio 1
	v_mfma_f32_16x16x32_bf16 v[32:35], v[136:139], v[230:233], v[32:35]
	v_mfma_f32_16x16x32_bf16 v[32:35], v[140:143], v[234:237], v[32:35]
	v_mfma_f32_16x16x32_bf16 v[24:27], v[180:183], v[234:237], v[24:27]
	v_mfma_f32_16x16x32_bf16 v[24:27], v[176:179], v[230:233], v[24:27]
	v_mfma_f32_16x16x32_bf16 v[20:23], v[184:187], v[230:233], v[20:23]
	v_mfma_f32_16x16x32_bf16 v[20:23], v[202:205], v[234:237], v[20:23]
	v_mfma_f32_16x16x32_bf16 v[16:19], v[210:213], v[234:237], v[16:19]
	v_mfma_f32_16x16x32_bf16 v[16:19], v[206:209], v[230:233], v[16:19]
	v_mfma_f32_16x16x32_bf16 v[0:3], v[206:209], v[238:241], v[0:3]
	v_mfma_f32_16x16x32_bf16 v[0:3], v[210:213], v[242:245], v[0:3]
	v_mfma_f32_16x16x32_bf16 v[4:7], v[202:205], v[242:245], v[4:7]
	v_mfma_f32_16x16x32_bf16 v[4:7], v[184:187], v[238:241], v[4:7]
	v_mfma_f32_16x16x32_bf16 v[8:11], v[176:179], v[238:241], v[8:11]
	v_mfma_f32_16x16x32_bf16 v[8:11], v[180:183], v[242:245], v[8:11]
	s_setprio 3
	s_barrier
	v_mfma_f32_16x16x32_bf16 v[12:15], v[140:143], v[242:245], v[12:15]
	v_mfma_f32_16x16x32_bf16 v[12:15], v[136:139], v[238:241], v[12:15]
	s_setprio 0
	s_cmp_gt_u32 s74, 29
	s_cbranch_scc0 .LBB0_110
	s_and_b64 vcc, exec, s[20:21]
	s_cbranch_vccz .LBB0_113
	s_barrier

; #define PG8_STAGE(bufoff, gbase, voff) do { _Pragma("unroll") for (int _i = 0; _i < 2; ++_i) \
;         __builtin_amdgcn_global_load_lds((const unsigned*)((const char*)(gbase) + (voff)[_i]), (PG8_LAS unsigned*)(lds + (bufoff) + ldsw + _i * 8192), 16, 0, 0); } while (0)
; #define PG8_LDA(dst, b, h) do { _Pragma("unroll") for (int m = 0; m < 4; ++m) _Pragma("unroll") for (int k = 0; k < 2; ++k) dst[m][k] = *(const PG8_LAS bf16x8*)(lds + PG8_SA(b, h) + aoff + m * 2048 + k * 1024); } while (0)
; #define PG8_LDB(dst, b, h) do { _Pragma("unroll") for (int n = 0; n < 2; ++n) _Pragma("unroll") for (int k = 0; k < 2; ++k) dst[n][k] = *(const PG8_LAS bf16x8*)(lds + PG8_SB(b, h) + boff + n * 2048 + k * 1024); } while (0)
; #define PG8_MMA(ai, bj, At, Bt) do { __builtin_amdgcn_s_setprio(1); _Pragma("unroll") for (int m = 0; m < 4; ++m) _Pragma("unroll") for (int n = 0; n < 2; ++n) _Pragma("unroll") for (int k = 0; k < 2; ++k) \
;         acc[ai][bj][m][n] = __builtin_amdgcn_mfma_f32_16x16x32_bf16(Bt[n][k], At[m][k], acc[ai][bj][m][n], 0, 0, 0); __builtin_amdgcn_s_setprio(0); } while (0)
; #define PG8_WAIT_V(n) asm volatile("s_waitcnt vmcnt(" #n ")" ::: "memory")
; #define PG8_WAIT_L(n) asm volatile("s_waitcnt lgkmcnt(" #n ")" ::: "memory")
; #define PG8_BAR __builtin_amdgcn_s_barrier()
; template <class Epi, class Sched, bool ALIGN_EPI = false, bool SP2 = false>
; __device__ __forceinline__ void gemm_phase(PG8_LAS unsigned char* lds, const Gemm g, const Sched& S, const Epi& E) {
;     ...
;             const char* a1 = cA + (size_t)(t + 1) * kstep;
;             const char* a2 = last ? nA : cA + (size_t)(t + 2) * kstep; const char* b2 = last ? nB : cB + (size_t)(t + 2) * kstep;
;             const char* a3 = a2 + kstep; const char* b3 = b2 + kstep;
;             if (last && has_next) S.a_ready(nxt);
;             if constexpr (SP2) {
;             PG8_LDB(B0, 0, 0); PG8_LDB(B1, 0, 1); PG8_SCHED; PG8_LDA(At, 0, 0); PG8_STAGE(PG8_SA(1, 1), a1 + hstep, voffA);
;             PG8_WAIT_V(8); PG8_WAIT_L(0); PG8_BAR; PG8_MMA(0, 0, At, B0); PG8_MMA(0, 1, At, B1); PG8_BAR; PG8_SCHED;
;             PG8_LDA(At, 0, 1); PG8_STAGE(PG8_SB(0, 0), b2, voffB); PG8_STAGE(PG8_SB(0, 1), b2 + hstep, voffB); PG8_STAGE(PG8_SA(0, 0), a2, voffA);
;             PG8_WAIT_V(8); PG8_WAIT_L(0); PG8_BAR; PG8_MMA(1, 0, At, B0); PG8_MMA(1, 1, At, B1); PG8_BAR; PG8_SCHED;
.LBB0_177:
	ds_read_b128 v[80:83], v171
	ds_read_b128 v[84:87], v171 offset:1024
	ds_read_b128 v[92:95], v171 offset:2048
	ds_read_b128 v[100:103], v171 offset:3072
	ds_read_b128 v[144:147], v206
	ds_read_b128 v[148:151], v206 offset:1024
	ds_read_b128 v[152:155], v206 offset:2048
	ds_read_b128 v[156:159], v206 offset:3072
	s_add_u32 s28, s72, 0xffea0080
	s_addc_u32 s29, s73, -1
	s_cmpk_eq_i32 s76, 0x54
	s_cselect_b32 s49, s69, s29
	s_cselect_b32 s48, s68, s28
	s_cselect_b32 s29, s71, s35
	s_cselect_b32 s28, s70, s34
	v_lshl_add_u64 v[234:235], s[72:73], 0, v[174:175]
	s_add_i32 m0, s40, 0xc000
	ds_read_b128 v[180:183], v207
	ds_read_b128 v[184:187], v207 offset:1024
	ds_read_b128 v[210:213], v207 offset:2048
	ds_read_b128 v[214:217], v207 offset:3072
	ds_read_b128 v[218:221], v207 offset:4096
	ds_read_b128 v[222:225], v207 offset:5120
	ds_read_b128 v[226:229], v207 offset:6144
	ds_read_b128 v[230:233], v207 offset:7168
	global_load_lds_dwordx4 v[234:235], off
	v_lshl_add_u64 v[234:235], s[72:73], 0, v[176:177]
	s_add_i32 m0, s40, 0xe000
	s_nop 0
	global_load_lds_dwordx4 v[234:235], off
	s_waitcnt vmcnt(8)
	s_waitcnt lgkmcnt(0)
	s_barrier
	s_setprio 1
	s_waitcnt lgkmcnt(0)
	v_mfma_f32_16x16x32_bf16 v[140:143], v[80:83], v[180:183], v[140:143]
	v_mfma_f32_16x16x32_bf16 v[140:143], v[84:87], v[184:187], v[140:143]
	v_mfma_f32_16x16x32_bf16 v[136:139], v[100:103], v[184:187], v[136:139]
	v_mfma_f32_16x16x32_bf16 v[136:139], v[92:95], v[180:183], v[136:139]
	v_mfma_f32_16x16x32_bf16 v[132:135], v[144:147], v[180:183], v[132:135]
	v_mfma_f32_16x16x32_bf16 v[132:135], v[148:151], v[184:187], v[132:135]
	v_mfma_f32_16x16x32_bf16 v[128:131], v[156:159], v[184:187], v[128:131]
	v_mfma_f32_16x16x32_bf16 v[128:131], v[152:155], v[180:183], v[128:131]
	v_mfma_f32_16x16x32_bf16 v[112:115], v[152:155], v[210:213], v[112:115]
	v_mfma_f32_16x16x32_bf16 v[112:115], v[156:159], v[214:217], v[112:115]
	v_mfma_f32_16x16x32_bf16 v[116:119], v[148:151], v[214:217], v[116:119]
	v_mfma_f32_16x16x32_bf16 v[116:119], v[144:147], v[210:213], v[116:119]
	v_mfma_f32_16x16x32_bf16 v[120:123], v[92:95], v[210:213], v[120:123]
	v_mfma_f32_16x16x32_bf16 v[120:123], v[100:103], v[214:217], v[120:123]
	v_mfma_f32_16x16x32_bf16 v[124:127], v[84:87], v[214:217], v[124:127]
	v_mfma_f32_16x16x32_bf16 v[124:127], v[80:83], v[210:213], v[124:127]
	s_setprio 0
	s_setprio 1
	v_mfma_f32_16x16x32_bf16 v[108:111], v[80:83], v[218:221], v[108:111]
	v_mfma_f32_16x16x32_bf16 v[108:111], v[84:87], v[222:225], v[108:111]
	v_mfma_f32_16x16x32_bf16 v[104:107], v[100:103], v[222:225], v[104:107]
	v_mfma_f32_16x16x32_bf16 v[104:107], v[92:95], v[218:221], v[104:107]
	v_mfma_f32_16x16x32_bf16 v[96:99], v[144:147], v[218:221], v[96:99]
	v_mfma_f32_16x16x32_bf16 v[96:99], v[148:151], v[222:225], v[96:99]
	v_mfma_f32_16x16x32_bf16 v[88:91], v[156:159], v[222:225], v[88:91]
	v_mfma_f32_16x16x32_bf16 v[88:91], v[152:155], v[218:221], v[88:91]
	v_mfma_f32_16x16x32_bf16 v[64:67], v[152:155], v[226:229], v[64:67]
	v_mfma_f32_16x16x32_bf16 v[64:67], v[156:159], v[230:233], v[64:67]
	v_mfma_f32_16x16x32_bf16 v[68:71], v[148:151], v[230:233], v[68:71]
	v_mfma_f32_16x16x32_bf16 v[68:71], v[144:147], v[226:229], v[68:71]
	v_mfma_f32_16x16x32_bf16 v[72:75], v[92:95], v[226:229], v[72:75]
	v_mfma_f32_16x16x32_bf16 v[72:75], v[100:103], v[230:233], v[72:75]
	s_setprio 3
	s_barrier
	v_mfma_f32_16x16x32_bf16 v[76:79], v[84:87], v[230:233], v[76:79]
	v_mfma_f32_16x16x32_bf16 v[76:79], v[80:83], v[226:229], v[76:79]
	s_setprio 0
	s_add_i32 s77, s61, s13
	v_lshl_add_u64 v[234:235], s[28:29], 0, v[160:161]
	s_mov_b32 m0, s77
	ds_read_b128 v[180:183], v207 offset:16384
	ds_read_b128 v[184:187], v207 offset:17408
	ds_read_b128 v[210:213], v207 offset:18432
	ds_read_b128 v[214:217], v207 offset:19456
	ds_read_b128 v[218:221], v207 offset:20480
	ds_read_b128 v[222:225], v207 offset:21504
	ds_read_b128 v[226:229], v207 offset:22528
	ds_read_b128 v[230:233], v207 offset:23552
	global_load_lds_dwordx4 v[234:235], off
	s_add_i32 m0, s77, 0x2000
	s_add_u32 s78, s28, 0x160000
	v_lshl_add_u64 v[236:237], s[28:29], 0, v[162:163]
	s_addc_u32 s79, s29, 0
	s_add_i32 s77, s62, s13
	global_load_lds_dwordx4 v[236:237], off
	v_lshl_add_u64 v[238:239], s[78:79], 0, v[160:161]
	s_mov_b32 m0, s77
	v_lshl_add_u64 v[240:241], s[48:49], 0, v[162:163]
	global_load_lds_dwordx4 v[238:239], off
	v_lshl_add_u64 v[238:239], s[78:79], 0, v[162:163]
	s_add_i32 m0, s77, 0x2000
	s_nop 0
	global_load_lds_dwordx4 v[238:239], off
	v_lshl_add_u64 v[238:239], s[48:49], 0, v[160:161]
	s_mov_b32 m0, s40
	s_nop 0
	global_load_lds_dwordx4 v[238:239], off
	s_mov_b32 m0, s41
	s_nop 0
	global_load_lds_dwordx4 v[240:241], off
	s_waitcnt vmcnt(8)
	s_waitcnt lgkmcnt(0)
	s_barrier
; #define PG8_STAGE(bufoff, gbase, voff) do { _Pragma("unroll") for (int _i = 0; _i < 2; ++_i) \
;         __builtin_amdgcn_global_load_lds((const unsigned*)((const char*)(gbase) + (voff)[_i]), (PG8_LAS unsigned*)(lds + (bufoff) + ldsw + _i * 8192), 16, 0, 0); } while (0)
; #define PG8_LDA(dst, b, h) do { _Pragma("unroll") for (int m = 0; m < 4; ++m) _Pragma("unroll") for (int k = 0; k < 2; ++k) dst[m][k] = *(const PG8_LAS bf16x8*)(lds + PG8_SA(b, h) + aoff + m * 2048 + k * 1024); } while (0)
; #define PG8_LDB(dst, b, h) do { _Pragma("unroll") for (int n = 0; n < 2; ++n) _Pragma("unroll") for (int k = 0; k < 2; ++k) dst[n][k] = *(const PG8_LAS bf16x8*)(lds + PG8_SB(b, h) + boff + n * 2048 + k * 1024); } while (0)
; #define PG8_MMA(ai, bj, At, Bt) do { __builtin_amdgcn_s_setprio(1); _Pragma("unroll") for (int m = 0; m < 4; ++m) _Pragma("unroll") for (int n = 0; n < 2; ++n) _Pragma("unroll") for (int k = 0; k < 2; ++k) \
;         acc[ai][bj][m][n] = __builtin_amdgcn_mfma_f32_16x16x32_bf16(Bt[n][k], At[m][k], acc[ai][bj][m][n], 0, 0, 0); __builtin_amdgcn_s_setprio(0); } while (0)
; #define PG8_WAIT_V(n) asm volatile("s_waitcnt vmcnt(" #n ")" ::: "memory")
; #define PG8_WAIT_L(n) asm volatile("s_waitcnt lgkmcnt(" #n ")" ::: "memory")
; #define PG8_BAR __builtin_amdgcn_s_barrier()
; #define PG8_SCHED __builtin_amdgcn_sched_barrier(0)
; template <class Epi, class Sched, bool ALIGN_EPI = false, bool SP2 = false>
; __device__ __forceinline__ void gemm_phase(PG8_LAS unsigned char* lds, const Gemm g, const Sched& S, const Epi& E) {
;     ...
;             PG8_WAIT_V(8); PG8_WAIT_L(0); PG8_BAR; PG8_MMA(1, 0, At, B0); PG8_MMA(1, 1, At, B1); PG8_BAR; PG8_SCHED;
;             PG8_LDB(B0, 1, 0); PG8_LDB(B1, 1, 1); PG8_SCHED; PG8_LDA(At, 1, 0); PG8_STAGE(PG8_SA(0, 1), a2 + hstep, voffA);
;             PG8_WAIT_V(8); PG8_WAIT_L(0); PG8_BAR; PG8_MMA(0, 0, At, B0); PG8_MMA(0, 1, At, B1); PG8_BAR; PG8_SCHED;
	s_setprio 1
	s_waitcnt lgkmcnt(0)
	v_mfma_f32_16x16x32_bf16 v[60:63], v[80:83], v[180:183], v[60:63]
	v_mfma_f32_16x16x32_bf16 v[60:63], v[84:87], v[184:187], v[60:63]
	v_mfma_f32_16x16x32_bf16 v[56:59], v[100:103], v[184:187], v[56:59]
	v_mfma_f32_16x16x32_bf16 v[56:59], v[92:95], v[180:183], v[56:59]
	v_mfma_f32_16x16x32_bf16 v[52:55], v[144:147], v[180:183], v[52:55]
	v_mfma_f32_16x16x32_bf16 v[52:55], v[148:151], v[184:187], v[52:55]
	v_mfma_f32_16x16x32_bf16 v[48:51], v[156:159], v[184:187], v[48:51]
	v_mfma_f32_16x16x32_bf16 v[48:51], v[152:155], v[180:183], v[48:51]
	v_mfma_f32_16x16x32_bf16 v[32:35], v[152:155], v[210:213], v[32:35]
	v_mfma_f32_16x16x32_bf16 v[32:35], v[156:159], v[214:217], v[32:35]
	v_mfma_f32_16x16x32_bf16 v[36:39], v[148:151], v[214:217], v[36:39]
	v_mfma_f32_16x16x32_bf16 v[36:39], v[144:147], v[210:213], v[36:39]
	v_mfma_f32_16x16x32_bf16 v[40:43], v[92:95], v[210:213], v[40:43]
	v_mfma_f32_16x16x32_bf16 v[40:43], v[100:103], v[214:217], v[40:43]
	v_mfma_f32_16x16x32_bf16 v[44:47], v[84:87], v[214:217], v[44:47]
	v_mfma_f32_16x16x32_bf16 v[44:47], v[80:83], v[210:213], v[44:47]
	s_setprio 0
	s_setprio 1
	v_mfma_f32_16x16x32_bf16 v[28:31], v[80:83], v[218:221], v[28:31]
	v_mfma_f32_16x16x32_bf16 v[28:31], v[84:87], v[222:225], v[28:31]
	v_mfma_f32_16x16x32_bf16 v[24:27], v[100:103], v[222:225], v[24:27]
	v_mfma_f32_16x16x32_bf16 v[24:27], v[92:95], v[218:221], v[24:27]
	v_mfma_f32_16x16x32_bf16 v[20:23], v[144:147], v[218:221], v[20:23]
	v_mfma_f32_16x16x32_bf16 v[20:23], v[148:151], v[222:225], v[20:23]
	v_mfma_f32_16x16x32_bf16 v[16:19], v[156:159], v[222:225], v[16:19]
	v_mfma_f32_16x16x32_bf16 v[16:19], v[152:155], v[218:221], v[16:19]
	v_mfma_f32_16x16x32_bf16 v[0:3], v[152:155], v[226:229], v[0:3]
	v_mfma_f32_16x16x32_bf16 v[0:3], v[156:159], v[230:233], v[0:3]
	v_mfma_f32_16x16x32_bf16 v[4:7], v[148:151], v[230:233], v[4:7]
	v_mfma_f32_16x16x32_bf16 v[4:7], v[144:147], v[226:229], v[4:7]
	v_mfma_f32_16x16x32_bf16 v[8:11], v[92:95], v[226:229], v[8:11]
	v_mfma_f32_16x16x32_bf16 v[8:11], v[100:103], v[230:233], v[8:11]
	s_setprio 3
	s_barrier
	v_mfma_f32_16x16x32_bf16 v[12:15], v[84:87], v[230:233], v[12:15]
	v_mfma_f32_16x16x32_bf16 v[12:15], v[80:83], v[226:229], v[12:15]
	s_setprio 0
	s_add_i32 s77, 0, 0x18000
	s_add_i32 s78, 0, 0x1c000
	v_add_u32_e32 v100, s77, v167
	v_add_u32_e32 v156, s78, v167
	ds_read_b128 v[80:83], v100
	ds_read_b128 v[84:87], v100 offset:1024
	ds_read_b128 v[92:95], v100 offset:2048
	ds_read_b128 v[100:103], v100 offset:3072
	ds_read_b128 v[144:147], v156
	ds_read_b128 v[148:151], v156 offset:1024
	ds_read_b128 v[152:155], v156 offset:2048
	ds_read_b128 v[156:159], v156 offset:3072
	s_add_u32 s48, s48, 0x160000
	s_addc_u32 s49, s49, 0
	s_mov_b32 m0, s44
	v_lshl_add_u64 v[242:243], s[48:49], 0, v[160:161]
	ds_read_b128 v[180:183], v207 offset:32768
	ds_read_b128 v[184:187], v207 offset:33792
	ds_read_b128 v[210:213], v207 offset:34816
	ds_read_b128 v[214:217], v207 offset:35840
	ds_read_b128 v[218:221], v207 offset:36864
	ds_read_b128 v[222:225], v207 offset:37888
	ds_read_b128 v[226:229], v207 offset:38912
	ds_read_b128 v[230:233], v207 offset:39936
	global_load_lds_dwordx4 v[242:243], off
	v_lshl_add_u64 v[242:243], s[48:49], 0, v[162:163]
	s_mov_b32 m0, s45
	s_nop 0
	global_load_lds_dwordx4 v[242:243], off
	s_waitcnt vmcnt(8)
	s_waitcnt lgkmcnt(0)
	s_barrier
	s_setprio 1
	s_waitcnt lgkmcnt(0)
	v_mfma_f32_16x16x32_bf16 v[140:143], v[80:83], v[180:183], v[140:143]
	v_mfma_f32_16x16x32_bf16 v[140:143], v[84:87], v[184:187], v[140:143]
	v_mfma_f32_16x16x32_bf16 v[136:139], v[100:103], v[184:187], v[136:139]
	v_mfma_f32_16x16x32_bf16 v[136:139], v[92:95], v[180:183], v[136:139]
	v_mfma_f32_16x16x32_bf16 v[132:135], v[144:147], v[180:183], v[132:135]
	v_mfma_f32_16x16x32_bf16 v[132:135], v[148:151], v[184:187], v[132:135]
	v_mfma_f32_16x16x32_bf16 v[128:131], v[156:159], v[184:187], v[128:131]
	v_mfma_f32_16x16x32_bf16 v[128:131], v[152:155], v[180:183], v[128:131]
	v_mfma_f32_16x16x32_bf16 v[112:115], v[152:155], v[210:213], v[112:115]
	v_mfma_f32_16x16x32_bf16 v[112:115], v[156:159], v[214:217], v[112:115]
	v_mfma_f32_16x16x32_bf16 v[116:119], v[148:151], v[214:217], v[116:119]
	v_mfma_f32_16x16x32_bf16 v[116:119], v[144:147], v[210:213], v[116:119]
	v_mfma_f32_16x16x32_bf16 v[120:123], v[92:95], v[210:213], v[120:123]
	v_mfma_f32_16x16x32_bf16 v[120:123], v[100:103], v[214:217], v[120:123]
	v_mfma_f32_16x16x32_bf16 v[124:127], v[84:87], v[214:217], v[124:127]
	v_mfma_f32_16x16x32_bf16 v[124:127], v[80:83], v[210:213], v[124:127]
	s_setprio 0
	s_setprio 1
	v_mfma_f32_16x16x32_bf16 v[108:111], v[80:83], v[218:221], v[108:111]
	v_mfma_f32_16x16x32_bf16 v[108:111], v[84:87], v[222:225], v[108:111]
	v_mfma_f32_16x16x32_bf16 v[104:107], v[100:103], v[222:225], v[104:107]
	v_mfma_f32_16x16x32_bf16 v[104:107], v[92:95], v[218:221], v[104:107]
	v_mfma_f32_16x16x32_bf16 v[96:99], v[144:147], v[218:221], v[96:99]
	v_mfma_f32_16x16x32_bf16 v[96:99], v[148:151], v[222:225], v[96:99]
	v_mfma_f32_16x16x32_bf16 v[88:91], v[156:159], v[222:225], v[88:91]
	v_mfma_f32_16x16x32_bf16 v[88:91], v[152:155], v[218:221], v[88:91]
	v_mfma_f32_16x16x32_bf16 v[64:67], v[152:155], v[226:229], v[64:67]
	v_mfma_f32_16x16x32_bf16 v[64:67], v[156:159], v[230:233], v[64:67]
	v_mfma_f32_16x16x32_bf16 v[68:71], v[148:151], v[230:233], v[68:71]
	v_mfma_f32_16x16x32_bf16 v[68:71], v[144:147], v[226:229], v[68:71]
	v_mfma_f32_16x16x32_bf16 v[72:75], v[92:95], v[226:229], v[72:75]
	v_mfma_f32_16x16x32_bf16 v[72:75], v[100:103], v[230:233], v[72:75]
	s_setprio 3
	s_barrier
; #define PG8_STAGE(bufoff, gbase, voff) do { _Pragma("unroll") for (int _i = 0; _i < 2; ++_i) \
;         __builtin_amdgcn_global_load_lds((const unsigned*)((const char*)(gbase) + (voff)[_i]), (PG8_LAS unsigned*)(lds + (bufoff) + ldsw + _i * 8192), 16, 0, 0); } while (0)
; #define PG8_LDA(dst, b, h) do { _Pragma("unroll") for (int m = 0; m < 4; ++m) _Pragma("unroll") for (int k = 0; k < 2; ++k) dst[m][k] = *(const PG8_LAS bf16x8*)(lds + PG8_SA(b, h) + aoff + m * 2048 + k * 1024); } while (0)
; #define PG8_MMA(ai, bj, At, Bt) do { __builtin_amdgcn_s_setprio(1); _Pragma("unroll") for (int m = 0; m < 4; ++m) _Pragma("unroll") for (int n = 0; n < 2; ++n) _Pragma("unroll") for (int k = 0; k < 2; ++k) \
;         acc[ai][bj][m][n] = __builtin_amdgcn_mfma_f32_16x16x32_bf16(Bt[n][k], At[m][k], acc[ai][bj][m][n], 0, 0, 0); __builtin_amdgcn_s_setprio(0); } while (0)
; #define PG8_WAIT_V(n) asm volatile("s_waitcnt vmcnt(" #n ")" ::: "memory")
; #define PG8_WAIT_L(n) asm volatile("s_waitcnt lgkmcnt(" #n ")" ::: "memory")
; #define PG8_BAR __builtin_amdgcn_s_barrier()
; #define PG8_SCHED __builtin_amdgcn_sched_barrier(0)
; template <class Epi, class Sched, bool ALIGN_EPI = false, bool SP2 = false>
; __device__ __forceinline__ void gemm_phase(PG8_LAS unsigned char* lds, const Gemm g, const Sched& S, const Epi& E) {
;     ...
;         for (int t = 0; t < nt; t += 2) {
;     ...
;             PG8_LDA(At, 1, 1); PG8_STAGE(PG8_SB(1, 0), b3, voffB); PG8_STAGE(PG8_SB(1, 1), b3 + hstep, voffB); PG8_STAGE(PG8_SA(1, 0), a3, voffA);
;             PG8_WAIT_V(8); PG8_WAIT_L(0); PG8_BAR; PG8_MMA(1, 0, At, B0); PG8_MMA(1, 1, At, B1); PG8_BAR; PG8_SCHED;
	v_mfma_f32_16x16x32_bf16 v[76:79], v[84:87], v[230:233], v[76:79]
	v_mfma_f32_16x16x32_bf16 v[76:79], v[80:83], v[226:229], v[76:79]
	s_setprio 0
	s_add_i32 s48, s77, s13
	v_lshl_add_u64 v[234:235], v[234:235], 0, s[50:51]
	s_mov_b32 m0, s48
	ds_read_b128 v[180:183], v207 offset:49152
	ds_read_b128 v[184:187], v207 offset:50176
	ds_read_b128 v[210:213], v207 offset:51200
	ds_read_b128 v[214:217], v207 offset:52224
	ds_read_b128 v[218:221], v207 offset:53248
	ds_read_b128 v[222:225], v207 offset:54272
	ds_read_b128 v[226:229], v207 offset:55296
	ds_read_b128 v[230:233], v207 offset:56320
	global_load_lds_dwordx4 v[234:235], off
	s_add_i32 m0, s48, 0x2000
	s_add_u32 s28, s28, 0x160080
	v_lshl_add_u64 v[234:235], v[236:237], 0, s[50:51]
	s_addc_u32 s29, s29, 0
	s_add_i32 s48, s78, s13
	global_load_lds_dwordx4 v[234:235], off
	v_lshl_add_u64 v[234:235], s[28:29], 0, v[160:161]
	s_mov_b32 m0, s48
	s_nop 0
	global_load_lds_dwordx4 v[234:235], off
	v_lshl_add_u64 v[234:235], s[28:29], 0, v[162:163]
	s_add_i32 m0, s48, 0x2000
	s_nop 0
	global_load_lds_dwordx4 v[234:235], off
	v_lshl_add_u64 v[234:235], v[238:239], 0, s[50:51]
	s_mov_b32 m0, s56
	s_nop 0
	global_load_lds_dwordx4 v[234:235], off
	v_lshl_add_u64 v[234:235], v[240:241], 0, s[50:51]
	s_mov_b32 m0, s57
	s_nop 0
	global_load_lds_dwordx4 v[234:235], off
	s_add_i32 s76, s76, 2
	s_add_u32 s72, s72, 0x100
	s_addc_u32 s73, s73, 0
	s_add_u32 s34, s34, 0x100
	s_addc_u32 s35, s35, 0
	s_waitcnt vmcnt(8)
	s_waitcnt lgkmcnt(0)
	s_barrier
	s_setprio 1
	s_waitcnt lgkmcnt(0)
	v_mfma_f32_16x16x32_bf16 v[60:63], v[80:83], v[180:183], v[60:63]
	v_mfma_f32_16x16x32_bf16 v[60:63], v[84:87], v[184:187], v[60:63]
	v_mfma_f32_16x16x32_bf16 v[56:59], v[100:103], v[184:187], v[56:59]
	v_mfma_f32_16x16x32_bf16 v[56:59], v[92:95], v[180:183], v[56:59]
	v_mfma_f32_16x16x32_bf16 v[52:55], v[144:147], v[180:183], v[52:55]
	v_mfma_f32_16x16x32_bf16 v[52:55], v[148:151], v[184:187], v[52:55]
	v_mfma_f32_16x16x32_bf16 v[48:51], v[156:159], v[184:187], v[48:51]
	v_mfma_f32_16x16x32_bf16 v[48:51], v[152:155], v[180:183], v[48:51]
	v_mfma_f32_16x16x32_bf16 v[32:35], v[152:155], v[210:213], v[32:35]
	v_mfma_f32_16x16x32_bf16 v[32:35], v[156:159], v[214:217], v[32:35]
	v_mfma_f32_16x16x32_bf16 v[36:39], v[148:151], v[214:217], v[36:39]
	v_mfma_f32_16x16x32_bf16 v[36:39], v[144:147], v[210:213], v[36:39]
	v_mfma_f32_16x16x32_bf16 v[40:43], v[92:95], v[210:213], v[40:43]
	v_mfma_f32_16x16x32_bf16 v[40:43], v[100:103], v[214:217], v[40:43]
	v_mfma_f32_16x16x32_bf16 v[44:47], v[84:87], v[214:217], v[44:47]
	v_mfma_f32_16x16x32_bf16 v[44:47], v[80:83], v[210:213], v[44:47]
	s_setprio 0
	s_setprio 1
	v_mfma_f32_16x16x32_bf16 v[28:31], v[80:83], v[218:221], v[28:31]
	v_mfma_f32_16x16x32_bf16 v[28:31], v[84:87], v[222:225], v[28:31]
	v_mfma_f32_16x16x32_bf16 v[24:27], v[100:103], v[222:225], v[24:27]
	v_mfma_f32_16x16x32_bf16 v[24:27], v[92:95], v[218:221], v[24:27]
	v_mfma_f32_16x16x32_bf16 v[20:23], v[144:147], v[218:221], v[20:23]
	v_mfma_f32_16x16x32_bf16 v[20:23], v[148:151], v[222:225], v[20:23]
	v_mfma_f32_16x16x32_bf16 v[16:19], v[156:159], v[222:225], v[16:19]
	v_mfma_f32_16x16x32_bf16 v[16:19], v[152:155], v[218:221], v[16:19]
	v_mfma_f32_16x16x32_bf16 v[0:3], v[152:155], v[226:229], v[0:3]
	v_mfma_f32_16x16x32_bf16 v[0:3], v[156:159], v[230:233], v[0:3]
	v_mfma_f32_16x16x32_bf16 v[4:7], v[148:151], v[230:233], v[4:7]
	v_mfma_f32_16x16x32_bf16 v[4:7], v[144:147], v[226:229], v[4:7]
	v_mfma_f32_16x16x32_bf16 v[8:11], v[92:95], v[226:229], v[8:11]
	v_mfma_f32_16x16x32_bf16 v[8:11], v[100:103], v[230:233], v[8:11]
	s_setprio 3
	s_barrier
	v_mfma_f32_16x16x32_bf16 v[12:15], v[84:87], v[230:233], v[12:15]
	v_mfma_f32_16x16x32_bf16 v[12:15], v[80:83], v[226:229], v[12:15]
	s_setprio 0
	s_cmpk_gt_u32 s76, 0x55
	s_cbranch_scc0 .LBB0_177
	s_and_b64 vcc, exec, s[52:53]
	s_cbranch_vccz .LBB0_180
	s_barrier

; #define PG8_STAGE(bufoff, gbase, voff) do { _Pragma("unroll") for (int _i = 0; _i < 2; ++_i) \
;         __builtin_amdgcn_global_load_lds((const unsigned*)((const char*)(gbase) + (voff)[_i]), (PG8_LAS unsigned*)(lds + (bufoff) + ldsw + _i * 8192), 16, 0, 0); } while (0)
; #define PG8_LDA(dst, b, h) do { _Pragma("unroll") for (int m = 0; m < 4; ++m) _Pragma("unroll") for (int k = 0; k < 2; ++k) dst[m][k] = *(const PG8_LAS bf16x8*)(lds + PG8_SA(b, h) + aoff + m * 2048 + k * 1024); } while (0)
; #define PG8_LDB(dst, b, h) do { _Pragma("unroll") for (int n = 0; n < 2; ++n) _Pragma("unroll") for (int k = 0; k < 2; ++k) dst[n][k] = *(const PG8_LAS bf16x8*)(lds + PG8_SB(b, h) + boff + n * 2048 + k * 1024); } while (0)
; #define PG8_MMA(ai, bj, At, Bt) do { __builtin_amdgcn_s_setprio(1); _Pragma("unroll") for (int m = 0; m < 4; ++m) _Pragma("unroll") for (int n = 0; n < 2; ++n) _Pragma("unroll") for (int k = 0; k < 2; ++k) \
;         acc[ai][bj][m][n] = __builtin_amdgcn_mfma_f32_16x16x32_bf16(Bt[n][k], At[m][k], acc[ai][bj][m][n], 0, 0, 0); __builtin_amdgcn_s_setprio(0); } while (0)
; #define PG8_WAIT_V(n) asm volatile("s_waitcnt vmcnt(" #n ")" ::: "memory")
; #define PG8_WAIT_L(n) asm volatile("s_waitcnt lgkmcnt(" #n ")" ::: "memory")
; #define PG8_BAR __builtin_amdgcn_s_barrier()
; template <class Epi, class Sched, bool ALIGN_EPI = false, bool SP2 = false>
; __device__ __forceinline__ void gemm_phase(PG8_LAS unsigned char* lds, const Gemm g, const Sched& S, const Epi& E) {
;     ...
;             const char* a1 = cA + (size_t)(t + 1) * kstep;
;             const char* a2 = last ? nA : cA + (size_t)(t + 2) * kstep; const char* b2 = last ? nB : cB + (size_t)(t + 2) * kstep;
;             const char* a3 = a2 + kstep; const char* b3 = b2 + kstep;
;             if (last && has_next) S.a_ready(nxt);
;             if constexpr (SP2) {
;             PG8_LDB(B0, 0, 0); PG8_LDB(B1, 0, 1); PG8_SCHED; PG8_LDA(At, 0, 0); PG8_STAGE(PG8_SA(1, 1), a1 + hstep, voffA);
;             PG8_WAIT_V(8); PG8_WAIT_L(0); PG8_BAR; PG8_MMA(0, 0, At, B0); PG8_MMA(0, 1, At, B1); PG8_BAR; PG8_SCHED;
;             PG8_LDA(At, 0, 1); PG8_STAGE(PG8_SB(0, 0), b2, voffB); PG8_STAGE(PG8_SB(0, 1), b2 + hstep, voffB); PG8_STAGE(PG8_SA(0, 0), a2, voffA);
;             PG8_WAIT_V(8); PG8_WAIT_L(0); PG8_BAR; PG8_MMA(1, 0, At, B0); PG8_MMA(1, 1, At, B1); PG8_BAR; PG8_SCHED;
.LBB0_231:
	ds_read_b128 v[142:145], v153
	ds_read_b128 v[146:149], v153 offset:1024
	ds_read_b128 v[174:177], v153 offset:2048
	ds_read_b128 v[178:181], v153 offset:3072
	ds_read_b128 v[182:185], v154
	ds_read_b128 v[206:209], v154 offset:1024
	ds_read_b128 v[210:213], v154 offset:2048
	ds_read_b128 v[214:217], v154 offset:3072
	s_add_u32 s28, s84, 0xfff80080
	s_addc_u32 s29, s85, -1
	s_cmp_eq_u32 s97, 28
	s_cselect_b32 s49, s34, s29
	s_cselect_b32 s48, s35, s28
	s_cselect_b32 s29, s75, s96
	s_cselect_b32 s28, s77, s95
	v_lshl_add_u64 v[158:159], s[84:85], 0, v[134:135]
	s_add_i32 m0, s56, 0xc000
	ds_read_b128 v[218:221], v155
	ds_read_b128 v[222:225], v155 offset:1024
	ds_read_b128 v[226:229], v155 offset:2048
	ds_read_b128 v[230:233], v155 offset:3072
	ds_read_b128 v[234:237], v155 offset:4096
	ds_read_b128 v[238:241], v155 offset:5120
	ds_read_b128 v[242:245], v155 offset:6144
	ds_read_b128 v[246:249], v155 offset:7168
	global_load_lds_dwordx4 v[158:159], off
	v_lshl_add_u64 v[158:159], s[84:85], 0, v[136:137]
	s_add_i32 m0, s56, 0xe000
	s_nop 0
	global_load_lds_dwordx4 v[158:159], off
	s_waitcnt vmcnt(8)
	s_waitcnt lgkmcnt(0)
	s_barrier
	s_setprio 1
	s_waitcnt lgkmcnt(0)
	v_mfma_f32_16x16x32_bf16 v[124:127], v[142:145], v[218:221], v[124:127]
	v_mfma_f32_16x16x32_bf16 v[124:127], v[146:149], v[222:225], v[124:127]
	v_mfma_f32_16x16x32_bf16 v[120:123], v[178:181], v[222:225], v[120:123]
	v_mfma_f32_16x16x32_bf16 v[120:123], v[174:177], v[218:221], v[120:123]
	v_mfma_f32_16x16x32_bf16 v[116:119], v[182:185], v[218:221], v[116:119]
	v_mfma_f32_16x16x32_bf16 v[116:119], v[206:209], v[222:225], v[116:119]
	v_mfma_f32_16x16x32_bf16 v[112:115], v[214:217], v[222:225], v[112:115]
	v_mfma_f32_16x16x32_bf16 v[112:115], v[210:213], v[218:221], v[112:115]
	v_mfma_f32_16x16x32_bf16 v[96:99], v[210:213], v[226:229], v[96:99]
	v_mfma_f32_16x16x32_bf16 v[96:99], v[214:217], v[230:233], v[96:99]
	v_mfma_f32_16x16x32_bf16 v[100:103], v[206:209], v[230:233], v[100:103]
	v_mfma_f32_16x16x32_bf16 v[100:103], v[182:185], v[226:229], v[100:103]
	v_mfma_f32_16x16x32_bf16 v[104:107], v[174:177], v[226:229], v[104:107]
	v_mfma_f32_16x16x32_bf16 v[104:107], v[178:181], v[230:233], v[104:107]
	v_mfma_f32_16x16x32_bf16 v[108:111], v[146:149], v[230:233], v[108:111]
	v_mfma_f32_16x16x32_bf16 v[108:111], v[142:145], v[226:229], v[108:111]
	s_setprio 0
	s_setprio 1
	v_mfma_f32_16x16x32_bf16 v[92:95], v[142:145], v[234:237], v[92:95]
	v_mfma_f32_16x16x32_bf16 v[92:95], v[146:149], v[238:241], v[92:95]
	v_mfma_f32_16x16x32_bf16 v[88:91], v[178:181], v[238:241], v[88:91]
	v_mfma_f32_16x16x32_bf16 v[88:91], v[174:177], v[234:237], v[88:91]
	v_mfma_f32_16x16x32_bf16 v[84:87], v[182:185], v[234:237], v[84:87]
	v_mfma_f32_16x16x32_bf16 v[84:87], v[206:209], v[238:241], v[84:87]
	v_mfma_f32_16x16x32_bf16 v[80:83], v[214:217], v[238:241], v[80:83]
	v_mfma_f32_16x16x32_bf16 v[80:83], v[210:213], v[234:237], v[80:83]
	v_mfma_f32_16x16x32_bf16 v[64:67], v[210:213], v[242:245], v[64:67]
	v_mfma_f32_16x16x32_bf16 v[64:67], v[214:217], v[246:249], v[64:67]
	v_mfma_f32_16x16x32_bf16 v[68:71], v[206:209], v[246:249], v[68:71]
	v_mfma_f32_16x16x32_bf16 v[68:71], v[182:185], v[242:245], v[68:71]
	v_mfma_f32_16x16x32_bf16 v[72:75], v[174:177], v[242:245], v[72:75]
	v_mfma_f32_16x16x32_bf16 v[72:75], v[178:181], v[246:249], v[72:75]
	s_setprio 3
	s_barrier
	v_mfma_f32_16x16x32_bf16 v[76:79], v[146:149], v[246:249], v[76:79]
	v_mfma_f32_16x16x32_bf16 v[76:79], v[142:145], v[242:245], v[76:79]
	s_setprio 0
	s_add_i32 vcc_lo, s83, s13
	v_lshl_add_u64 v[158:159], s[28:29], 0, v[166:167]
	s_mov_b32 m0, vcc_lo
	ds_read_b128 v[218:221], v155 offset:16384
	ds_read_b128 v[222:225], v155 offset:17408
	ds_read_b128 v[226:229], v155 offset:18432
	ds_read_b128 v[230:233], v155 offset:19456
	ds_read_b128 v[234:237], v155 offset:20480
	ds_read_b128 v[238:241], v155 offset:21504
	ds_read_b128 v[242:245], v155 offset:22528
	ds_read_b128 v[246:249], v155 offset:23552
	global_load_lds_dwordx4 v[158:159], off
	s_add_i32 m0, vcc_lo, 0x2000
	s_add_u32 vcc_lo, s28, 0x80000
	v_lshl_add_u64 v[186:187], s[28:29], 0, v[170:171]
	s_addc_u32 vcc_hi, s29, 0
	s_add_i32 s44, s90, s13
	global_load_lds_dwordx4 v[186:187], off
	v_lshl_add_u64 v[250:251], vcc, 0, v[166:167]
	s_mov_b32 m0, s44
	v_lshl_add_u64 v[252:253], s[48:49], 0, v[168:169]
	global_load_lds_dwordx4 v[250:251], off
	v_lshl_add_u64 v[250:251], vcc, 0, v[170:171]
	s_add_i32 m0, s44, 0x2000
	s_nop 0
	global_load_lds_dwordx4 v[250:251], off
	v_lshl_add_u64 v[250:251], s[48:49], 0, v[164:165]
	s_mov_b32 m0, s56
	s_nop 0
	global_load_lds_dwordx4 v[250:251], off
	s_mov_b32 m0, s57
	s_nop 0
	global_load_lds_dwordx4 v[252:253], off
	s_waitcnt vmcnt(8)
	s_waitcnt lgkmcnt(0)
	s_barrier
; #define PG8_STAGE(bufoff, gbase, voff) do { _Pragma("unroll") for (int _i = 0; _i < 2; ++_i) \
;         __builtin_amdgcn_global_load_lds((const unsigned*)((const char*)(gbase) + (voff)[_i]), (PG8_LAS unsigned*)(lds + (bufoff) + ldsw + _i * 8192), 16, 0, 0); } while (0)
; #define PG8_LDA(dst, b, h) do { _Pragma("unroll") for (int m = 0; m < 4; ++m) _Pragma("unroll") for (int k = 0; k < 2; ++k) dst[m][k] = *(const PG8_LAS bf16x8*)(lds + PG8_SA(b, h) + aoff + m * 2048 + k * 1024); } while (0)
; #define PG8_LDB(dst, b, h) do { _Pragma("unroll") for (int n = 0; n < 2; ++n) _Pragma("unroll") for (int k = 0; k < 2; ++k) dst[n][k] = *(const PG8_LAS bf16x8*)(lds + PG8_SB(b, h) + boff + n * 2048 + k * 1024); } while (0)
; #define PG8_MMA(ai, bj, At, Bt) do { __builtin_amdgcn_s_setprio(1); _Pragma("unroll") for (int m = 0; m < 4; ++m) _Pragma("unroll") for (int n = 0; n < 2; ++n) _Pragma("unroll") for (int k = 0; k < 2; ++k) \
;         acc[ai][bj][m][n] = __builtin_amdgcn_mfma_f32_16x16x32_bf16(Bt[n][k], At[m][k], acc[ai][bj][m][n], 0, 0, 0); __builtin_amdgcn_s_setprio(0); } while (0)
; #define PG8_WAIT_V(n) asm volatile("s_waitcnt vmcnt(" #n ")" ::: "memory")
; #define PG8_WAIT_L(n) asm volatile("s_waitcnt lgkmcnt(" #n ")" ::: "memory")
; #define PG8_BAR __builtin_amdgcn_s_barrier()
; #define PG8_SCHED __builtin_amdgcn_sched_barrier(0)
; template <class Epi, class Sched, bool ALIGN_EPI = false, bool SP2 = false>
; __device__ __forceinline__ void gemm_phase(PG8_LAS unsigned char* lds, const Gemm g, const Sched& S, const Epi& E) {
;     ...
;             PG8_WAIT_V(8); PG8_WAIT_L(0); PG8_BAR; PG8_MMA(1, 0, At, B0); PG8_MMA(1, 1, At, B1); PG8_BAR; PG8_SCHED;
;             PG8_LDB(B0, 1, 0); PG8_LDB(B1, 1, 1); PG8_SCHED; PG8_LDA(At, 1, 0); PG8_STAGE(PG8_SA(0, 1), a2 + hstep, voffA);
;             PG8_WAIT_V(8); PG8_WAIT_L(0); PG8_BAR; PG8_MMA(0, 0, At, B0); PG8_MMA(0, 1, At, B1); PG8_BAR; PG8_SCHED;
	s_setprio 1
	s_waitcnt lgkmcnt(0)
	v_mfma_f32_16x16x32_bf16 v[60:63], v[142:145], v[218:221], v[60:63]
	v_mfma_f32_16x16x32_bf16 v[60:63], v[146:149], v[222:225], v[60:63]
	v_mfma_f32_16x16x32_bf16 v[56:59], v[178:181], v[222:225], v[56:59]
	v_mfma_f32_16x16x32_bf16 v[56:59], v[174:177], v[218:221], v[56:59]
	v_mfma_f32_16x16x32_bf16 v[52:55], v[182:185], v[218:221], v[52:55]
	v_mfma_f32_16x16x32_bf16 v[52:55], v[206:209], v[222:225], v[52:55]
	v_mfma_f32_16x16x32_bf16 v[48:51], v[214:217], v[222:225], v[48:51]
	v_mfma_f32_16x16x32_bf16 v[48:51], v[210:213], v[218:221], v[48:51]
	v_mfma_f32_16x16x32_bf16 v[32:35], v[210:213], v[226:229], v[32:35]
	v_mfma_f32_16x16x32_bf16 v[32:35], v[214:217], v[230:233], v[32:35]
	v_mfma_f32_16x16x32_bf16 v[36:39], v[206:209], v[230:233], v[36:39]
	v_mfma_f32_16x16x32_bf16 v[36:39], v[182:185], v[226:229], v[36:39]
	v_mfma_f32_16x16x32_bf16 v[40:43], v[174:177], v[226:229], v[40:43]
	v_mfma_f32_16x16x32_bf16 v[40:43], v[178:181], v[230:233], v[40:43]
	v_mfma_f32_16x16x32_bf16 v[44:47], v[146:149], v[230:233], v[44:47]
	v_mfma_f32_16x16x32_bf16 v[44:47], v[142:145], v[226:229], v[44:47]
	s_setprio 0
	s_setprio 1
	v_mfma_f32_16x16x32_bf16 v[28:31], v[142:145], v[234:237], v[28:31]
	v_mfma_f32_16x16x32_bf16 v[28:31], v[146:149], v[238:241], v[28:31]
	v_mfma_f32_16x16x32_bf16 v[24:27], v[178:181], v[238:241], v[24:27]
	v_mfma_f32_16x16x32_bf16 v[24:27], v[174:177], v[234:237], v[24:27]
	v_mfma_f32_16x16x32_bf16 v[20:23], v[182:185], v[234:237], v[20:23]
	v_mfma_f32_16x16x32_bf16 v[20:23], v[206:209], v[238:241], v[20:23]
	v_mfma_f32_16x16x32_bf16 v[16:19], v[214:217], v[238:241], v[16:19]
	v_mfma_f32_16x16x32_bf16 v[16:19], v[210:213], v[234:237], v[16:19]
	v_mfma_f32_16x16x32_bf16 v[0:3], v[210:213], v[242:245], v[0:3]
	v_mfma_f32_16x16x32_bf16 v[0:3], v[214:217], v[246:249], v[0:3]
	v_mfma_f32_16x16x32_bf16 v[4:7], v[206:209], v[246:249], v[4:7]
	v_mfma_f32_16x16x32_bf16 v[4:7], v[182:185], v[242:245], v[4:7]
	v_mfma_f32_16x16x32_bf16 v[8:11], v[174:177], v[242:245], v[8:11]
	v_mfma_f32_16x16x32_bf16 v[8:11], v[178:181], v[246:249], v[8:11]
	s_setprio 3
	s_barrier
	v_mfma_f32_16x16x32_bf16 v[12:15], v[146:149], v[246:249], v[12:15]
	v_mfma_f32_16x16x32_bf16 v[12:15], v[142:145], v[242:245], v[12:15]
	s_setprio 0
	s_add_i32 s44, 0, 0x18000
	v_add_u32_e32 v161, s44, v151
	s_add_i32 s45, 0, 0x1c000
	ds_read_b128 v[142:145], v161
	ds_read_b128 v[146:149], v161 offset:1024
	ds_read_b128 v[174:177], v161 offset:2048
	ds_read_b128 v[178:181], v161 offset:3072
	v_add_u32_e32 v161, s45, v151
	ds_read_b128 v[182:185], v161
	ds_read_b128 v[206:209], v161 offset:1024
	ds_read_b128 v[210:213], v161 offset:2048
	ds_read_b128 v[214:217], v161 offset:3072
	s_add_u32 s48, s48, 0x80000
	s_addc_u32 s49, s49, 0
	s_mov_b32 m0, s60
	v_lshl_add_u64 v[200:201], s[48:49], 0, v[164:165]
	ds_read_b128 v[218:221], v155 offset:32768
	ds_read_b128 v[222:225], v155 offset:33792
	ds_read_b128 v[226:229], v155 offset:34816
	ds_read_b128 v[230:233], v155 offset:35840
	ds_read_b128 v[234:237], v155 offset:36864
	ds_read_b128 v[238:241], v155 offset:37888
	ds_read_b128 v[242:245], v155 offset:38912
	ds_read_b128 v[246:249], v155 offset:39936
	global_load_lds_dwordx4 v[200:201], off
	v_lshl_add_u64 v[200:201], s[48:49], 0, v[168:169]
	s_mov_b32 m0, s61
	s_nop 0
	global_load_lds_dwordx4 v[200:201], off
	s_waitcnt vmcnt(8)
	s_waitcnt lgkmcnt(0)
	s_barrier
	s_setprio 1
	s_waitcnt lgkmcnt(0)
	v_mfma_f32_16x16x32_bf16 v[124:127], v[142:145], v[218:221], v[124:127]
	v_mfma_f32_16x16x32_bf16 v[124:127], v[146:149], v[222:225], v[124:127]
	v_mfma_f32_16x16x32_bf16 v[120:123], v[178:181], v[222:225], v[120:123]
	v_mfma_f32_16x16x32_bf16 v[120:123], v[174:177], v[218:221], v[120:123]
	v_mfma_f32_16x16x32_bf16 v[116:119], v[182:185], v[218:221], v[116:119]
	v_mfma_f32_16x16x32_bf16 v[116:119], v[206:209], v[222:225], v[116:119]
	v_mfma_f32_16x16x32_bf16 v[112:115], v[214:217], v[222:225], v[112:115]
	v_mfma_f32_16x16x32_bf16 v[112:115], v[210:213], v[218:221], v[112:115]
	v_mfma_f32_16x16x32_bf16 v[96:99], v[210:213], v[226:229], v[96:99]
	v_mfma_f32_16x16x32_bf16 v[96:99], v[214:217], v[230:233], v[96:99]
	v_mfma_f32_16x16x32_bf16 v[100:103], v[206:209], v[230:233], v[100:103]
	v_mfma_f32_16x16x32_bf16 v[100:103], v[182:185], v[226:229], v[100:103]
	v_mfma_f32_16x16x32_bf16 v[104:107], v[174:177], v[226:229], v[104:107]
	v_mfma_f32_16x16x32_bf16 v[104:107], v[178:181], v[230:233], v[104:107]
	v_mfma_f32_16x16x32_bf16 v[108:111], v[146:149], v[230:233], v[108:111]
	v_mfma_f32_16x16x32_bf16 v[108:111], v[142:145], v[226:229], v[108:111]
	s_setprio 0
	s_setprio 1
	v_mfma_f32_16x16x32_bf16 v[92:95], v[142:145], v[234:237], v[92:95]
	v_mfma_f32_16x16x32_bf16 v[92:95], v[146:149], v[238:241], v[92:95]
	v_mfma_f32_16x16x32_bf16 v[88:91], v[178:181], v[238:241], v[88:91]
	v_mfma_f32_16x16x32_bf16 v[88:91], v[174:177], v[234:237], v[88:91]
	v_mfma_f32_16x16x32_bf16 v[84:87], v[182:185], v[234:237], v[84:87]
	v_mfma_f32_16x16x32_bf16 v[84:87], v[206:209], v[238:241], v[84:87]
	v_mfma_f32_16x16x32_bf16 v[80:83], v[214:217], v[238:241], v[80:83]
	v_mfma_f32_16x16x32_bf16 v[80:83], v[210:213], v[234:237], v[80:83]
	v_mfma_f32_16x16x32_bf16 v[64:67], v[210:213], v[242:245], v[64:67]
	v_mfma_f32_16x16x32_bf16 v[64:67], v[214:217], v[246:249], v[64:67]
	v_mfma_f32_16x16x32_bf16 v[68:71], v[206:209], v[246:249], v[68:71]
	v_mfma_f32_16x16x32_bf16 v[68:71], v[182:185], v[242:245], v[68:71]
	v_mfma_f32_16x16x32_bf16 v[72:75], v[174:177], v[242:245], v[72:75]
	v_mfma_f32_16x16x32_bf16 v[72:75], v[178:181], v[246:249], v[72:75]
	s_setprio 3
	s_barrier
; #define PG8_STAGE(bufoff, gbase, voff) do { _Pragma("unroll") for (int _i = 0; _i < 2; ++_i) \
;         __builtin_amdgcn_global_load_lds((const unsigned*)((const char*)(gbase) + (voff)[_i]), (PG8_LAS unsigned*)(lds + (bufoff) + ldsw + _i * 8192), 16, 0, 0); } while (0)
; #define PG8_LDA(dst, b, h) do { _Pragma("unroll") for (int m = 0; m < 4; ++m) _Pragma("unroll") for (int k = 0; k < 2; ++k) dst[m][k] = *(const PG8_LAS bf16x8*)(lds + PG8_SA(b, h) + aoff + m * 2048 + k * 1024); } while (0)
; #define PG8_MMA(ai, bj, At, Bt) do { __builtin_amdgcn_s_setprio(1); _Pragma("unroll") for (int m = 0; m < 4; ++m) _Pragma("unroll") for (int n = 0; n < 2; ++n) _Pragma("unroll") for (int k = 0; k < 2; ++k) \
;         acc[ai][bj][m][n] = __builtin_amdgcn_mfma_f32_16x16x32_bf16(Bt[n][k], At[m][k], acc[ai][bj][m][n], 0, 0, 0); __builtin_amdgcn_s_setprio(0); } while (0)
; #define PG8_WAIT_V(n) asm volatile("s_waitcnt vmcnt(" #n ")" ::: "memory")
; #define PG8_WAIT_L(n) asm volatile("s_waitcnt lgkmcnt(" #n ")" ::: "memory")
; #define PG8_BAR __builtin_amdgcn_s_barrier()
; #define PG8_SCHED __builtin_amdgcn_sched_barrier(0)
;     __device__ __forceinline__ void operator()(const f32x4 (&acc)[2][2][4][2], const Unit& u, int wr, int wc, int fr, int fq) const {
;         const int row0 = u.pm * BM + wr * 64 + fr;
;         if (u.pn < 8) {
; template <class Epi, class Sched, bool ALIGN_EPI = false, bool SP2 = false>
; __device__ __forceinline__ void gemm_phase(PG8_LAS unsigned char* lds, const Gemm g, const Sched& S, const Epi& E) {
;     ...
;             PG8_LDA(At, 1, 1); PG8_STAGE(PG8_SB(1, 0), b3, voffB); PG8_STAGE(PG8_SB(1, 1), b3 + hstep, voffB); PG8_STAGE(PG8_SA(1, 0), a3, voffA);
;             PG8_WAIT_V(8); PG8_WAIT_L(0); PG8_BAR; PG8_MMA(1, 0, At, B0); PG8_MMA(1, 1, At, B1); PG8_BAR; PG8_SCHED;
	v_mfma_f32_16x16x32_bf16 v[76:79], v[146:149], v[246:249], v[76:79]
	v_mfma_f32_16x16x32_bf16 v[76:79], v[142:145], v[242:245], v[76:79]
	s_setprio 0
	s_add_i32 s44, s44, s13
	v_lshl_add_u64 v[158:159], v[158:159], 0, s[52:53]
	s_mov_b32 m0, s44
	ds_read_b128 v[218:221], v155 offset:49152
	ds_read_b128 v[222:225], v155 offset:50176
	ds_read_b128 v[226:229], v155 offset:51200
	ds_read_b128 v[230:233], v155 offset:52224
	ds_read_b128 v[234:237], v155 offset:53248
	ds_read_b128 v[238:241], v155 offset:54272
	ds_read_b128 v[242:245], v155 offset:55296
	ds_read_b128 v[246:249], v155 offset:56320
	global_load_lds_dwordx4 v[158:159], off
	s_add_i32 m0, s44, 0x2000
	s_add_u32 s28, s28, 0x80080
	v_lshl_add_u64 v[158:159], v[186:187], 0, s[52:53]
	s_addc_u32 s29, s29, 0
	s_add_i32 s44, s45, s13
	global_load_lds_dwordx4 v[158:159], off
	v_lshl_add_u64 v[158:159], s[28:29], 0, v[166:167]
	s_mov_b32 m0, s44
	s_nop 0
	global_load_lds_dwordx4 v[158:159], off
	v_lshl_add_u64 v[158:159], s[28:29], 0, v[170:171]
	s_add_i32 m0, s44, 0x2000
	s_nop 0
	global_load_lds_dwordx4 v[158:159], off
	v_lshl_add_u64 v[158:159], v[250:251], 0, s[52:53]
	s_mov_b32 m0, s62
	s_nop 0
	global_load_lds_dwordx4 v[158:159], off
	v_lshl_add_u64 v[158:159], v[252:253], 0, s[52:53]
	s_mov_b32 m0, s63
	s_nop 0
	global_load_lds_dwordx4 v[158:159], off
	s_add_i32 s97, s97, 2
	s_add_u32 s84, s84, 0x100
	s_addc_u32 s85, s85, 0
	s_add_u32 s95, s95, 0x100
	s_addc_u32 s96, s96, 0
	s_waitcnt vmcnt(8)
	s_waitcnt lgkmcnt(0)
	s_barrier
	s_setprio 1
	s_waitcnt lgkmcnt(0)
	v_mfma_f32_16x16x32_bf16 v[60:63], v[142:145], v[218:221], v[60:63]
	v_mfma_f32_16x16x32_bf16 v[60:63], v[146:149], v[222:225], v[60:63]
	v_mfma_f32_16x16x32_bf16 v[56:59], v[178:181], v[222:225], v[56:59]
	v_mfma_f32_16x16x32_bf16 v[56:59], v[174:177], v[218:221], v[56:59]
	v_mfma_f32_16x16x32_bf16 v[52:55], v[182:185], v[218:221], v[52:55]
	v_mfma_f32_16x16x32_bf16 v[52:55], v[206:209], v[222:225], v[52:55]
	v_mfma_f32_16x16x32_bf16 v[48:51], v[214:217], v[222:225], v[48:51]
	v_mfma_f32_16x16x32_bf16 v[48:51], v[210:213], v[218:221], v[48:51]
	v_mfma_f32_16x16x32_bf16 v[32:35], v[210:213], v[226:229], v[32:35]
	v_mfma_f32_16x16x32_bf16 v[32:35], v[214:217], v[230:233], v[32:35]
	v_mfma_f32_16x16x32_bf16 v[36:39], v[206:209], v[230:233], v[36:39]
	v_mfma_f32_16x16x32_bf16 v[36:39], v[182:185], v[226:229], v[36:39]
	v_mfma_f32_16x16x32_bf16 v[40:43], v[174:177], v[226:229], v[40:43]
	v_mfma_f32_16x16x32_bf16 v[40:43], v[178:181], v[230:233], v[40:43]
	v_mfma_f32_16x16x32_bf16 v[44:47], v[146:149], v[230:233], v[44:47]
	v_mfma_f32_16x16x32_bf16 v[44:47], v[142:145], v[226:229], v[44:47]
	s_setprio 0
	s_setprio 1
	v_mfma_f32_16x16x32_bf16 v[28:31], v[142:145], v[234:237], v[28:31]
	v_mfma_f32_16x16x32_bf16 v[28:31], v[146:149], v[238:241], v[28:31]
	v_mfma_f32_16x16x32_bf16 v[24:27], v[178:181], v[238:241], v[24:27]
	v_mfma_f32_16x16x32_bf16 v[24:27], v[174:177], v[234:237], v[24:27]
	v_mfma_f32_16x16x32_bf16 v[20:23], v[182:185], v[234:237], v[20:23]
	v_mfma_f32_16x16x32_bf16 v[20:23], v[206:209], v[238:241], v[20:23]
	v_mfma_f32_16x16x32_bf16 v[16:19], v[214:217], v[238:241], v[16:19]
	v_mfma_f32_16x16x32_bf16 v[16:19], v[210:213], v[234:237], v[16:19]
	v_mfma_f32_16x16x32_bf16 v[0:3], v[210:213], v[242:245], v[0:3]
	v_mfma_f32_16x16x32_bf16 v[0:3], v[214:217], v[246:249], v[0:3]
	v_mfma_f32_16x16x32_bf16 v[4:7], v[206:209], v[246:249], v[4:7]
	v_mfma_f32_16x16x32_bf16 v[4:7], v[182:185], v[242:245], v[4:7]
	v_mfma_f32_16x16x32_bf16 v[8:11], v[174:177], v[242:245], v[8:11]
	v_mfma_f32_16x16x32_bf16 v[8:11], v[178:181], v[246:249], v[8:11]
	s_setprio 3
	s_barrier
	v_mfma_f32_16x16x32_bf16 v[12:15], v[146:149], v[246:249], v[12:15]
	v_mfma_f32_16x16x32_bf16 v[12:15], v[142:145], v[242:245], v[12:15]
	s_setprio 0
	s_cmp_gt_u32 s97, 29
	s_cbranch_scc0 .LBB0_231
	s_and_b64 vcc, exec, s[72:73]
	s_cbranch_vccz .LBB0_236
	s_barrier
	v_lshl_add_u32 v142, s82, 8, v150
	s_cmp_gt_i32 s94, 7
	s_mov_b64 s[28:29], -1
	s_cbranch_scc1 .LBB0_237

; #define PG8_STAGE(bufoff, gbase, voff) do { _Pragma("unroll") for (int _i = 0; _i < 2; ++_i) \
;         __builtin_amdgcn_global_load_lds((const unsigned*)((const char*)(gbase) + (voff)[_i]), (PG8_LAS unsigned*)(lds + (bufoff) + ldsw + _i * 8192), 16, 0, 0); } while (0)
; #define PG8_LDA(dst, b, h) do { _Pragma("unroll") for (int m = 0; m < 4; ++m) _Pragma("unroll") for (int k = 0; k < 2; ++k) dst[m][k] = *(const PG8_LAS bf16x8*)(lds + PG8_SA(b, h) + aoff + m * 2048 + k * 1024); } while (0)
; #define PG8_LDB(dst, b, h) do { _Pragma("unroll") for (int n = 0; n < 2; ++n) _Pragma("unroll") for (int k = 0; k < 2; ++k) dst[n][k] = *(const PG8_LAS bf16x8*)(lds + PG8_SB(b, h) + boff + n * 2048 + k * 1024); } while (0)
; #define PG8_MMA(ai, bj, At, Bt) do { __builtin_amdgcn_s_setprio(1); _Pragma("unroll") for (int m = 0; m < 4; ++m) _Pragma("unroll") for (int n = 0; n < 2; ++n) _Pragma("unroll") for (int k = 0; k < 2; ++k) \
;         acc[ai][bj][m][n] = __builtin_amdgcn_mfma_f32_16x16x32_bf16(Bt[n][k], At[m][k], acc[ai][bj][m][n], 0, 0, 0); __builtin_amdgcn_s_setprio(0); } while (0)
; #define PG8_WAIT_V(n) asm volatile("s_waitcnt vmcnt(" #n ")" ::: "memory")
; #define PG8_WAIT_L(n) asm volatile("s_waitcnt lgkmcnt(" #n ")" ::: "memory")
; #define PG8_BAR __builtin_amdgcn_s_barrier()
; template <class Epi, class Sched, bool ALIGN_EPI = false, bool SP2 = false>
; __device__ __forceinline__ void gemm_phase(PG8_LAS unsigned char* lds, const Gemm g, const Sched& S, const Epi& E) {
;     ...
;             const char* a1 = cA + (size_t)(t + 1) * kstep;
;             const char* a2 = last ? nA : cA + (size_t)(t + 2) * kstep; const char* b2 = last ? nB : cB + (size_t)(t + 2) * kstep;
;             const char* a3 = a2 + kstep; const char* b3 = b2 + kstep;
;             if (last && has_next) S.a_ready(nxt);
;             if constexpr (SP2) {
;             PG8_LDB(B0, 0, 0); PG8_LDB(B1, 0, 1); PG8_SCHED; PG8_LDA(At, 0, 0); PG8_STAGE(PG8_SA(1, 1), a1 + hstep, voffA);
;             PG8_WAIT_V(8); PG8_WAIT_L(0); PG8_BAR; PG8_MMA(0, 0, At, B0); PG8_MMA(0, 1, At, B1); PG8_BAR; PG8_SCHED;
;             PG8_LDA(At, 0, 1); PG8_STAGE(PG8_SB(0, 0), b2, voffB); PG8_STAGE(PG8_SB(0, 1), b2 + hstep, voffB); PG8_STAGE(PG8_SA(0, 0), a2, voffA);
;             PG8_WAIT_V(8); PG8_WAIT_L(0); PG8_BAR; PG8_MMA(1, 0, At, B0); PG8_MMA(1, 1, At, B1); PG8_BAR; PG8_SCHED;
.LBB0_362:
	ds_read_b128 v[80:83], v171
	ds_read_b128 v[84:87], v171 offset:1024
	ds_read_b128 v[92:95], v171 offset:2048
	ds_read_b128 v[100:103], v171 offset:3072
	ds_read_b128 v[144:147], v186
	ds_read_b128 v[148:151], v186 offset:1024
	ds_read_b128 v[152:155], v186 offset:2048
	ds_read_b128 v[156:159], v186 offset:3072
	s_add_u32 s28, s74, 0xfff80080
	s_addc_u32 s29, s75, -1
	s_cmp_eq_u32 s77, 28
	s_cselect_b32 s49, s23, s29
	s_cselect_b32 s48, s34, s28
	s_cselect_b32 s29, s21, s76
	s_cselect_b32 s28, s35, s73
	v_lshl_add_u64 v[200:201], s[74:75], 0, v[172:173]
	s_add_i32 m0, s38, 0xc000
	ds_read_b128 v[178:181], v187
	ds_read_b128 v[182:185], v187 offset:1024
	ds_read_b128 v[206:209], v187 offset:2048
	ds_read_b128 v[210:213], v187 offset:3072
	ds_read_b128 v[214:217], v187 offset:4096
	ds_read_b128 v[218:221], v187 offset:5120
	ds_read_b128 v[222:225], v187 offset:6144
	ds_read_b128 v[226:229], v187 offset:7168
	global_load_lds_dwordx4 v[200:201], off
	v_lshl_add_u64 v[200:201], s[74:75], 0, v[174:175]
	s_add_i32 m0, s38, 0xe000
	s_nop 0
	global_load_lds_dwordx4 v[200:201], off
	s_waitcnt vmcnt(8)
	s_waitcnt lgkmcnt(0)
	s_barrier
	s_setprio 1
	s_waitcnt lgkmcnt(0)
	v_mfma_f32_16x16x32_bf16 v[140:143], v[80:83], v[178:181], v[140:143]
	v_mfma_f32_16x16x32_bf16 v[140:143], v[84:87], v[182:185], v[140:143]
	v_mfma_f32_16x16x32_bf16 v[136:139], v[100:103], v[182:185], v[136:139]
	v_mfma_f32_16x16x32_bf16 v[136:139], v[92:95], v[178:181], v[136:139]
	v_mfma_f32_16x16x32_bf16 v[132:135], v[144:147], v[178:181], v[132:135]
	v_mfma_f32_16x16x32_bf16 v[132:135], v[148:151], v[182:185], v[132:135]
	v_mfma_f32_16x16x32_bf16 v[128:131], v[156:159], v[182:185], v[128:131]
	v_mfma_f32_16x16x32_bf16 v[128:131], v[152:155], v[178:181], v[128:131]
	v_mfma_f32_16x16x32_bf16 v[112:115], v[152:155], v[206:209], v[112:115]
	v_mfma_f32_16x16x32_bf16 v[112:115], v[156:159], v[210:213], v[112:115]
	v_mfma_f32_16x16x32_bf16 v[116:119], v[148:151], v[210:213], v[116:119]
	v_mfma_f32_16x16x32_bf16 v[116:119], v[144:147], v[206:209], v[116:119]
	v_mfma_f32_16x16x32_bf16 v[120:123], v[92:95], v[206:209], v[120:123]
	v_mfma_f32_16x16x32_bf16 v[120:123], v[100:103], v[210:213], v[120:123]
	v_mfma_f32_16x16x32_bf16 v[124:127], v[84:87], v[210:213], v[124:127]
	v_mfma_f32_16x16x32_bf16 v[124:127], v[80:83], v[206:209], v[124:127]
	s_setprio 0
	s_setprio 1
	v_mfma_f32_16x16x32_bf16 v[108:111], v[80:83], v[214:217], v[108:111]
	v_mfma_f32_16x16x32_bf16 v[108:111], v[84:87], v[218:221], v[108:111]
	v_mfma_f32_16x16x32_bf16 v[104:107], v[100:103], v[218:221], v[104:107]
	v_mfma_f32_16x16x32_bf16 v[104:107], v[92:95], v[214:217], v[104:107]
	v_mfma_f32_16x16x32_bf16 v[96:99], v[144:147], v[214:217], v[96:99]
	v_mfma_f32_16x16x32_bf16 v[96:99], v[148:151], v[218:221], v[96:99]
	v_mfma_f32_16x16x32_bf16 v[88:91], v[156:159], v[218:221], v[88:91]
	v_mfma_f32_16x16x32_bf16 v[88:91], v[152:155], v[214:217], v[88:91]
	v_mfma_f32_16x16x32_bf16 v[64:67], v[152:155], v[222:225], v[64:67]
	v_mfma_f32_16x16x32_bf16 v[64:67], v[156:159], v[226:229], v[64:67]
	v_mfma_f32_16x16x32_bf16 v[68:71], v[148:151], v[226:229], v[68:71]
	v_mfma_f32_16x16x32_bf16 v[68:71], v[144:147], v[222:225], v[68:71]
	v_mfma_f32_16x16x32_bf16 v[72:75], v[92:95], v[222:225], v[72:75]
	v_mfma_f32_16x16x32_bf16 v[72:75], v[100:103], v[226:229], v[72:75]
	s_setprio 3
	s_barrier
	v_mfma_f32_16x16x32_bf16 v[76:79], v[84:87], v[226:229], v[76:79]
	v_mfma_f32_16x16x32_bf16 v[76:79], v[80:83], v[222:225], v[76:79]
	s_setprio 0
	s_add_i32 s44, s62, s13
	v_lshl_add_u64 v[200:201], s[28:29], 0, v[164:165]
	s_mov_b32 m0, s44
	ds_read_b128 v[178:181], v187 offset:16384
	ds_read_b128 v[182:185], v187 offset:17408
	ds_read_b128 v[206:209], v187 offset:18432
	ds_read_b128 v[210:213], v187 offset:19456
	ds_read_b128 v[214:217], v187 offset:20480
	ds_read_b128 v[218:221], v187 offset:21504
	ds_read_b128 v[222:225], v187 offset:22528
	ds_read_b128 v[226:229], v187 offset:23552
	global_load_lds_dwordx4 v[200:201], off
	s_add_i32 m0, s44, 0x2000
	s_add_u32 s78, s28, 0x80000
	v_lshl_add_u64 v[230:231], s[28:29], 0, v[168:169]
	s_addc_u32 s79, s29, 0
	s_add_i32 s44, s63, s13
	global_load_lds_dwordx4 v[230:231], off
	v_lshl_add_u64 v[232:233], s[78:79], 0, v[164:165]
	s_mov_b32 m0, s44
	v_lshl_add_u64 v[234:235], s[48:49], 0, v[168:169]
	global_load_lds_dwordx4 v[232:233], off
	v_lshl_add_u64 v[232:233], s[78:79], 0, v[168:169]
	s_add_i32 m0, s44, 0x2000
	s_nop 0
	global_load_lds_dwordx4 v[232:233], off
	v_lshl_add_u64 v[232:233], s[48:49], 0, v[164:165]
	s_mov_b32 m0, s38
	s_nop 0
	global_load_lds_dwordx4 v[232:233], off
	s_mov_b32 m0, s39
	s_nop 0
	global_load_lds_dwordx4 v[234:235], off
	s_waitcnt vmcnt(8)
	s_waitcnt lgkmcnt(0)
	s_barrier
; #define PG8_STAGE(bufoff, gbase, voff) do { _Pragma("unroll") for (int _i = 0; _i < 2; ++_i) \
;         __builtin_amdgcn_global_load_lds((const unsigned*)((const char*)(gbase) + (voff)[_i]), (PG8_LAS unsigned*)(lds + (bufoff) + ldsw + _i * 8192), 16, 0, 0); } while (0)
; #define PG8_LDA(dst, b, h) do { _Pragma("unroll") for (int m = 0; m < 4; ++m) _Pragma("unroll") for (int k = 0; k < 2; ++k) dst[m][k] = *(const PG8_LAS bf16x8*)(lds + PG8_SA(b, h) + aoff + m * 2048 + k * 1024); } while (0)
; #define PG8_LDB(dst, b, h) do { _Pragma("unroll") for (int n = 0; n < 2; ++n) _Pragma("unroll") for (int k = 0; k < 2; ++k) dst[n][k] = *(const PG8_LAS bf16x8*)(lds + PG8_SB(b, h) + boff + n * 2048 + k * 1024); } while (0)
; #define PG8_MMA(ai, bj, At, Bt) do { __builtin_amdgcn_s_setprio(1); _Pragma("unroll") for (int m = 0; m < 4; ++m) _Pragma("unroll") for (int n = 0; n < 2; ++n) _Pragma("unroll") for (int k = 0; k < 2; ++k) \
;         acc[ai][bj][m][n] = __builtin_amdgcn_mfma_f32_16x16x32_bf16(Bt[n][k], At[m][k], acc[ai][bj][m][n], 0, 0, 0); __builtin_amdgcn_s_setprio(0); } while (0)
; #define PG8_WAIT_V(n) asm volatile("s_waitcnt vmcnt(" #n ")" ::: "memory")
; #define PG8_WAIT_L(n) asm volatile("s_waitcnt lgkmcnt(" #n ")" ::: "memory")
; #define PG8_BAR __builtin_amdgcn_s_barrier()
; #define PG8_SCHED __builtin_amdgcn_sched_barrier(0)
; template <class Epi, class Sched, bool ALIGN_EPI = false, bool SP2 = false>
; __device__ __forceinline__ void gemm_phase(PG8_LAS unsigned char* lds, const Gemm g, const Sched& S, const Epi& E) {
;     ...
;             PG8_WAIT_V(8); PG8_WAIT_L(0); PG8_BAR; PG8_MMA(1, 0, At, B0); PG8_MMA(1, 1, At, B1); PG8_BAR; PG8_SCHED;
;             PG8_LDB(B0, 1, 0); PG8_LDB(B1, 1, 1); PG8_SCHED; PG8_LDA(At, 1, 0); PG8_STAGE(PG8_SA(0, 1), a2 + hstep, voffA);
;             PG8_WAIT_V(8); PG8_WAIT_L(0); PG8_BAR; PG8_MMA(0, 0, At, B0); PG8_MMA(0, 1, At, B1); PG8_BAR; PG8_SCHED;
	s_setprio 1
	s_waitcnt lgkmcnt(0)
	v_mfma_f32_16x16x32_bf16 v[60:63], v[80:83], v[178:181], v[60:63]
	v_mfma_f32_16x16x32_bf16 v[60:63], v[84:87], v[182:185], v[60:63]
	v_mfma_f32_16x16x32_bf16 v[56:59], v[100:103], v[182:185], v[56:59]
	v_mfma_f32_16x16x32_bf16 v[56:59], v[92:95], v[178:181], v[56:59]
	v_mfma_f32_16x16x32_bf16 v[52:55], v[144:147], v[178:181], v[52:55]
	v_mfma_f32_16x16x32_bf16 v[52:55], v[148:151], v[182:185], v[52:55]
	v_mfma_f32_16x16x32_bf16 v[48:51], v[156:159], v[182:185], v[48:51]
	v_mfma_f32_16x16x32_bf16 v[48:51], v[152:155], v[178:181], v[48:51]
	v_mfma_f32_16x16x32_bf16 v[32:35], v[152:155], v[206:209], v[32:35]
	v_mfma_f32_16x16x32_bf16 v[32:35], v[156:159], v[210:213], v[32:35]
	v_mfma_f32_16x16x32_bf16 v[36:39], v[148:151], v[210:213], v[36:39]
	v_mfma_f32_16x16x32_bf16 v[36:39], v[144:147], v[206:209], v[36:39]
	v_mfma_f32_16x16x32_bf16 v[40:43], v[92:95], v[206:209], v[40:43]
	v_mfma_f32_16x16x32_bf16 v[40:43], v[100:103], v[210:213], v[40:43]
	v_mfma_f32_16x16x32_bf16 v[44:47], v[84:87], v[210:213], v[44:47]
	v_mfma_f32_16x16x32_bf16 v[44:47], v[80:83], v[206:209], v[44:47]
	s_setprio 0
	s_setprio 1
	v_mfma_f32_16x16x32_bf16 v[28:31], v[80:83], v[214:217], v[28:31]
	v_mfma_f32_16x16x32_bf16 v[28:31], v[84:87], v[218:221], v[28:31]
	v_mfma_f32_16x16x32_bf16 v[24:27], v[100:103], v[218:221], v[24:27]
	v_mfma_f32_16x16x32_bf16 v[24:27], v[92:95], v[214:217], v[24:27]
	v_mfma_f32_16x16x32_bf16 v[20:23], v[144:147], v[214:217], v[20:23]
	v_mfma_f32_16x16x32_bf16 v[20:23], v[148:151], v[218:221], v[20:23]
	v_mfma_f32_16x16x32_bf16 v[16:19], v[156:159], v[218:221], v[16:19]
	v_mfma_f32_16x16x32_bf16 v[16:19], v[152:155], v[214:217], v[16:19]
	v_mfma_f32_16x16x32_bf16 v[0:3], v[152:155], v[222:225], v[0:3]
	v_mfma_f32_16x16x32_bf16 v[0:3], v[156:159], v[226:229], v[0:3]
	v_mfma_f32_16x16x32_bf16 v[4:7], v[148:151], v[226:229], v[4:7]
	v_mfma_f32_16x16x32_bf16 v[4:7], v[144:147], v[222:225], v[4:7]
	v_mfma_f32_16x16x32_bf16 v[8:11], v[92:95], v[222:225], v[8:11]
	v_mfma_f32_16x16x32_bf16 v[8:11], v[100:103], v[226:229], v[8:11]
	s_setprio 3
	s_barrier
	v_mfma_f32_16x16x32_bf16 v[12:15], v[84:87], v[226:229], v[12:15]
	v_mfma_f32_16x16x32_bf16 v[12:15], v[80:83], v[222:225], v[12:15]
	s_setprio 0
	s_add_i32 s44, 0, 0x18000
	s_add_i32 s45, 0, 0x1c000
	v_add_u32_e32 v100, s44, v163
	v_add_u32_e32 v156, s45, v163
	ds_read_b128 v[80:83], v100
	ds_read_b128 v[84:87], v100 offset:1024
	ds_read_b128 v[92:95], v100 offset:2048
	ds_read_b128 v[100:103], v100 offset:3072
	ds_read_b128 v[144:147], v156
	ds_read_b128 v[148:151], v156 offset:1024
	ds_read_b128 v[152:155], v156 offset:2048
	ds_read_b128 v[156:159], v156 offset:3072
	s_add_u32 s48, s48, 0x80000
	s_addc_u32 s49, s49, 0
	s_mov_b32 m0, s40
	v_lshl_add_u64 v[236:237], s[48:49], 0, v[164:165]
	ds_read_b128 v[178:181], v187 offset:32768
	ds_read_b128 v[182:185], v187 offset:33792
	ds_read_b128 v[206:209], v187 offset:34816
	ds_read_b128 v[210:213], v187 offset:35840
	ds_read_b128 v[214:217], v187 offset:36864
	ds_read_b128 v[218:221], v187 offset:37888
	ds_read_b128 v[222:225], v187 offset:38912
	ds_read_b128 v[226:229], v187 offset:39936
	global_load_lds_dwordx4 v[236:237], off
	v_lshl_add_u64 v[236:237], s[48:49], 0, v[168:169]
	s_mov_b32 m0, s41
	s_nop 0
	global_load_lds_dwordx4 v[236:237], off
	s_waitcnt vmcnt(8)
	s_waitcnt lgkmcnt(0)
	s_barrier
	s_setprio 1
	s_waitcnt lgkmcnt(0)
	v_mfma_f32_16x16x32_bf16 v[140:143], v[80:83], v[178:181], v[140:143]
	v_mfma_f32_16x16x32_bf16 v[140:143], v[84:87], v[182:185], v[140:143]
	v_mfma_f32_16x16x32_bf16 v[136:139], v[100:103], v[182:185], v[136:139]
	v_mfma_f32_16x16x32_bf16 v[136:139], v[92:95], v[178:181], v[136:139]
	v_mfma_f32_16x16x32_bf16 v[132:135], v[144:147], v[178:181], v[132:135]
	v_mfma_f32_16x16x32_bf16 v[132:135], v[148:151], v[182:185], v[132:135]
	v_mfma_f32_16x16x32_bf16 v[128:131], v[156:159], v[182:185], v[128:131]
	v_mfma_f32_16x16x32_bf16 v[128:131], v[152:155], v[178:181], v[128:131]
	v_mfma_f32_16x16x32_bf16 v[112:115], v[152:155], v[206:209], v[112:115]
	v_mfma_f32_16x16x32_bf16 v[112:115], v[156:159], v[210:213], v[112:115]
	v_mfma_f32_16x16x32_bf16 v[116:119], v[148:151], v[210:213], v[116:119]
	v_mfma_f32_16x16x32_bf16 v[116:119], v[144:147], v[206:209], v[116:119]
	v_mfma_f32_16x16x32_bf16 v[120:123], v[92:95], v[206:209], v[120:123]
	v_mfma_f32_16x16x32_bf16 v[120:123], v[100:103], v[210:213], v[120:123]
	v_mfma_f32_16x16x32_bf16 v[124:127], v[84:87], v[210:213], v[124:127]
	v_mfma_f32_16x16x32_bf16 v[124:127], v[80:83], v[206:209], v[124:127]
	s_setprio 0
	s_setprio 1
	v_mfma_f32_16x16x32_bf16 v[108:111], v[80:83], v[214:217], v[108:111]
	v_mfma_f32_16x16x32_bf16 v[108:111], v[84:87], v[218:221], v[108:111]
	v_mfma_f32_16x16x32_bf16 v[104:107], v[100:103], v[218:221], v[104:107]
	v_mfma_f32_16x16x32_bf16 v[104:107], v[92:95], v[214:217], v[104:107]
	v_mfma_f32_16x16x32_bf16 v[96:99], v[144:147], v[214:217], v[96:99]
	v_mfma_f32_16x16x32_bf16 v[96:99], v[148:151], v[218:221], v[96:99]
	v_mfma_f32_16x16x32_bf16 v[88:91], v[156:159], v[218:221], v[88:91]
	v_mfma_f32_16x16x32_bf16 v[88:91], v[152:155], v[214:217], v[88:91]
	v_mfma_f32_16x16x32_bf16 v[64:67], v[152:155], v[222:225], v[64:67]
	v_mfma_f32_16x16x32_bf16 v[64:67], v[156:159], v[226:229], v[64:67]
	v_mfma_f32_16x16x32_bf16 v[68:71], v[148:151], v[226:229], v[68:71]
	v_mfma_f32_16x16x32_bf16 v[68:71], v[144:147], v[222:225], v[68:71]
	v_mfma_f32_16x16x32_bf16 v[72:75], v[92:95], v[222:225], v[72:75]
	v_mfma_f32_16x16x32_bf16 v[72:75], v[100:103], v[226:229], v[72:75]
	s_setprio 3
	s_barrier
; #define PG8_STAGE(bufoff, gbase, voff) do { _Pragma("unroll") for (int _i = 0; _i < 2; ++_i) \
;         __builtin_amdgcn_global_load_lds((const unsigned*)((const char*)(gbase) + (voff)[_i]), (PG8_LAS unsigned*)(lds + (bufoff) + ldsw + _i * 8192), 16, 0, 0); } while (0)
; #define PG8_LDA(dst, b, h) do { _Pragma("unroll") for (int m = 0; m < 4; ++m) _Pragma("unroll") for (int k = 0; k < 2; ++k) dst[m][k] = *(const PG8_LAS bf16x8*)(lds + PG8_SA(b, h) + aoff + m * 2048 + k * 1024); } while (0)
; #define PG8_MMA(ai, bj, At, Bt) do { __builtin_amdgcn_s_setprio(1); _Pragma("unroll") for (int m = 0; m < 4; ++m) _Pragma("unroll") for (int n = 0; n < 2; ++n) _Pragma("unroll") for (int k = 0; k < 2; ++k) \
;         acc[ai][bj][m][n] = __builtin_amdgcn_mfma_f32_16x16x32_bf16(Bt[n][k], At[m][k], acc[ai][bj][m][n], 0, 0, 0); __builtin_amdgcn_s_setprio(0); } while (0)
; #define PG8_WAIT_V(n) asm volatile("s_waitcnt vmcnt(" #n ")" ::: "memory")
; #define PG8_WAIT_L(n) asm volatile("s_waitcnt lgkmcnt(" #n ")" ::: "memory")
; #define PG8_BAR __builtin_amdgcn_s_barrier()
; #define PG8_SCHED __builtin_amdgcn_sched_barrier(0)
; template <class Epi, class Sched, bool ALIGN_EPI = false, bool SP2 = false>
; __device__ __forceinline__ void gemm_phase(PG8_LAS unsigned char* lds, const Gemm g, const Sched& S, const Epi& E) {
;     ...
;         for (int t = 0; t < nt; t += 2) {
;     ...
;             PG8_LDA(At, 1, 1); PG8_STAGE(PG8_SB(1, 0), b3, voffB); PG8_STAGE(PG8_SB(1, 1), b3 + hstep, voffB); PG8_STAGE(PG8_SA(1, 0), a3, voffA);
;             PG8_WAIT_V(8); PG8_WAIT_L(0); PG8_BAR; PG8_MMA(1, 0, At, B0); PG8_MMA(1, 1, At, B1); PG8_BAR; PG8_SCHED;
	v_mfma_f32_16x16x32_bf16 v[76:79], v[84:87], v[226:229], v[76:79]
	v_mfma_f32_16x16x32_bf16 v[76:79], v[80:83], v[222:225], v[76:79]
	s_setprio 0
	s_add_i32 s44, s44, s13
	v_lshl_add_u64 v[200:201], v[200:201], 0, s[16:17]
	s_mov_b32 m0, s44
	ds_read_b128 v[178:181], v187 offset:49152
	ds_read_b128 v[182:185], v187 offset:50176
	ds_read_b128 v[206:209], v187 offset:51200
	ds_read_b128 v[210:213], v187 offset:52224
	ds_read_b128 v[214:217], v187 offset:53248
	ds_read_b128 v[218:221], v187 offset:54272
	ds_read_b128 v[222:225], v187 offset:55296
	ds_read_b128 v[226:229], v187 offset:56320
	global_load_lds_dwordx4 v[200:201], off
	s_add_i32 m0, s44, 0x2000
	s_add_u32 s28, s28, 0x80080
	v_lshl_add_u64 v[200:201], v[230:231], 0, s[16:17]
	s_addc_u32 s29, s29, 0
	s_add_i32 s44, s45, s13
	global_load_lds_dwordx4 v[200:201], off
	v_lshl_add_u64 v[200:201], s[28:29], 0, v[164:165]
	s_mov_b32 m0, s44
	s_nop 0
	global_load_lds_dwordx4 v[200:201], off
	v_lshl_add_u64 v[200:201], s[28:29], 0, v[168:169]
	s_add_i32 m0, s44, 0x2000
	s_nop 0
	global_load_lds_dwordx4 v[200:201], off
	v_lshl_add_u64 v[200:201], v[232:233], 0, s[16:17]
	s_mov_b32 m0, s56
	s_nop 0
	global_load_lds_dwordx4 v[200:201], off
	v_lshl_add_u64 v[200:201], v[234:235], 0, s[16:17]
	s_mov_b32 m0, s57
	s_nop 0
	global_load_lds_dwordx4 v[200:201], off
	s_add_i32 s77, s77, 2
	s_add_u32 s74, s74, 0x100
	s_addc_u32 s75, s75, 0
	s_add_u32 s73, s73, 0x100
	s_addc_u32 s76, s76, 0
	s_waitcnt vmcnt(8)
	s_waitcnt lgkmcnt(0)
	s_barrier
	s_setprio 1
	s_waitcnt lgkmcnt(0)
	v_mfma_f32_16x16x32_bf16 v[60:63], v[80:83], v[178:181], v[60:63]
	v_mfma_f32_16x16x32_bf16 v[60:63], v[84:87], v[182:185], v[60:63]
	v_mfma_f32_16x16x32_bf16 v[56:59], v[100:103], v[182:185], v[56:59]
	v_mfma_f32_16x16x32_bf16 v[56:59], v[92:95], v[178:181], v[56:59]
	v_mfma_f32_16x16x32_bf16 v[52:55], v[144:147], v[178:181], v[52:55]
	v_mfma_f32_16x16x32_bf16 v[52:55], v[148:151], v[182:185], v[52:55]
	v_mfma_f32_16x16x32_bf16 v[48:51], v[156:159], v[182:185], v[48:51]
	v_mfma_f32_16x16x32_bf16 v[48:51], v[152:155], v[178:181], v[48:51]
	v_mfma_f32_16x16x32_bf16 v[32:35], v[152:155], v[206:209], v[32:35]
	v_mfma_f32_16x16x32_bf16 v[32:35], v[156:159], v[210:213], v[32:35]
	v_mfma_f32_16x16x32_bf16 v[36:39], v[148:151], v[210:213], v[36:39]
	v_mfma_f32_16x16x32_bf16 v[36:39], v[144:147], v[206:209], v[36:39]
	v_mfma_f32_16x16x32_bf16 v[40:43], v[92:95], v[206:209], v[40:43]
	v_mfma_f32_16x16x32_bf16 v[40:43], v[100:103], v[210:213], v[40:43]
	v_mfma_f32_16x16x32_bf16 v[44:47], v[84:87], v[210:213], v[44:47]
	v_mfma_f32_16x16x32_bf16 v[44:47], v[80:83], v[206:209], v[44:47]
	s_setprio 0
	s_setprio 1
	v_mfma_f32_16x16x32_bf16 v[28:31], v[80:83], v[214:217], v[28:31]
	v_mfma_f32_16x16x32_bf16 v[28:31], v[84:87], v[218:221], v[28:31]
	v_mfma_f32_16x16x32_bf16 v[24:27], v[100:103], v[218:221], v[24:27]
	v_mfma_f32_16x16x32_bf16 v[24:27], v[92:95], v[214:217], v[24:27]
	v_mfma_f32_16x16x32_bf16 v[20:23], v[144:147], v[214:217], v[20:23]
	v_mfma_f32_16x16x32_bf16 v[20:23], v[148:151], v[218:221], v[20:23]
	v_mfma_f32_16x16x32_bf16 v[16:19], v[156:159], v[218:221], v[16:19]
	v_mfma_f32_16x16x32_bf16 v[16:19], v[152:155], v[214:217], v[16:19]
	v_mfma_f32_16x16x32_bf16 v[0:3], v[152:155], v[222:225], v[0:3]
	v_mfma_f32_16x16x32_bf16 v[0:3], v[156:159], v[226:229], v[0:3]
	v_mfma_f32_16x16x32_bf16 v[4:7], v[148:151], v[226:229], v[4:7]
	v_mfma_f32_16x16x32_bf16 v[4:7], v[144:147], v[222:225], v[4:7]
	v_mfma_f32_16x16x32_bf16 v[8:11], v[92:95], v[222:225], v[8:11]
	v_mfma_f32_16x16x32_bf16 v[8:11], v[100:103], v[226:229], v[8:11]
	s_setprio 3
	s_barrier
	v_mfma_f32_16x16x32_bf16 v[12:15], v[84:87], v[226:229], v[12:15]
	v_mfma_f32_16x16x32_bf16 v[12:15], v[80:83], v[222:225], v[12:15]
	s_setprio 0
	s_cmp_gt_u32 s77, 29
	s_cbranch_scc0 .LBB0_362
	s_and_b64 vcc, exec, s[18:19]
	s_cbranch_vccz .LBB0_365
	s_barrier

; #define PG8_STAGE(bufoff, gbase, voff) do { _Pragma("unroll") for (int _i = 0; _i < 2; ++_i) \
;         __builtin_amdgcn_global_load_lds((const unsigned*)((const char*)(gbase) + (voff)[_i]), (PG8_LAS unsigned*)(lds + (bufoff) + ldsw + _i * 8192), 16, 0, 0); } while (0)
; #define PG8_LDA(dst, b, h) do { _Pragma("unroll") for (int m = 0; m < 4; ++m) _Pragma("unroll") for (int k = 0; k < 2; ++k) dst[m][k] = *(const PG8_LAS bf16x8*)(lds + PG8_SA(b, h) + aoff + m * 2048 + k * 1024); } while (0)
; #define PG8_LDB(dst, b, h) do { _Pragma("unroll") for (int n = 0; n < 2; ++n) _Pragma("unroll") for (int k = 0; k < 2; ++k) dst[n][k] = *(const PG8_LAS bf16x8*)(lds + PG8_SB(b, h) + boff + n * 2048 + k * 1024); } while (0)
; #define PG8_MMA(ai, bj, At, Bt) do { __builtin_amdgcn_s_setprio(1); _Pragma("unroll") for (int m = 0; m < 4; ++m) _Pragma("unroll") for (int n = 0; n < 2; ++n) _Pragma("unroll") for (int k = 0; k < 2; ++k) \
;         acc[ai][bj][m][n] = __builtin_amdgcn_mfma_f32_16x16x32_bf16(Bt[n][k], At[m][k], acc[ai][bj][m][n], 0, 0, 0); __builtin_amdgcn_s_setprio(0); } while (0)
; #define PG8_WAIT_V(n) asm volatile("s_waitcnt vmcnt(" #n ")" ::: "memory")
; #define PG8_WAIT_L(n) asm volatile("s_waitcnt lgkmcnt(" #n ")" ::: "memory")
; #define PG8_BAR __builtin_amdgcn_s_barrier()
; template <class Epi, class Sched, bool ALIGN_EPI = false, bool SP2 = false>
; __device__ __forceinline__ void gemm_phase(PG8_LAS unsigned char* lds, const Gemm g, const Sched& S, const Epi& E) {
;     ...
;             const char* a1 = cA + (size_t)(t + 1) * kstep;
;             const char* a2 = last ? nA : cA + (size_t)(t + 2) * kstep; const char* b2 = last ? nB : cB + (size_t)(t + 2) * kstep;
;             const char* a3 = a2 + kstep; const char* b3 = b2 + kstep;
;             if (last && has_next) S.a_ready(nxt);
;             if constexpr (SP2) {
;             PG8_LDB(B0, 0, 0); PG8_LDB(B1, 0, 1); PG8_SCHED; PG8_LDA(At, 0, 0); PG8_STAGE(PG8_SA(1, 1), a1 + hstep, voffA);
;             PG8_WAIT_V(8); PG8_WAIT_L(0); PG8_BAR; PG8_MMA(0, 0, At, B0); PG8_MMA(0, 1, At, B1); PG8_BAR; PG8_SCHED;
;             PG8_LDA(At, 0, 1); PG8_STAGE(PG8_SB(0, 0), b2, voffB); PG8_STAGE(PG8_SB(0, 1), b2 + hstep, voffB); PG8_STAGE(PG8_SA(0, 0), a2, voffA);
;             PG8_WAIT_V(8); PG8_WAIT_L(0); PG8_BAR; PG8_MMA(1, 0, At, B0); PG8_MMA(1, 1, At, B1); PG8_BAR; PG8_SCHED;
.LBB0_416:
	ds_read_b128 v[136:139], v156
	ds_read_b128 v[140:143], v156 offset:1024
	ds_read_b128 v[172:175], v156 offset:2048
	ds_read_b128 v[176:179], v156 offset:3072
	ds_read_b128 v[180:183], v157
	ds_read_b128 v[184:187], v157 offset:1024
	ds_read_b128 v[206:209], v157 offset:2048
	ds_read_b128 v[210:213], v157 offset:3072
	s_add_u32 s28, s68, 0xfff80080
	s_addc_u32 s29, s69, -1
	s_cmp_eq_u32 s79, 28
	s_cselect_b32 s49, s34, s29
	s_cselect_b32 s48, s35, s28
	s_cselect_b32 s29, s23, s78
	s_cselect_b32 s28, s63, s77
	v_lshl_add_u64 v[200:201], s[68:69], 0, v[128:129]
	s_add_i32 m0, s15, 0xc000
	ds_read_b128 v[214:217], v158
	ds_read_b128 v[218:221], v158 offset:1024
	ds_read_b128 v[222:225], v158 offset:2048
	ds_read_b128 v[226:229], v158 offset:3072
	ds_read_b128 v[230:233], v158 offset:4096
	ds_read_b128 v[234:237], v158 offset:5120
	ds_read_b128 v[238:241], v158 offset:6144
	ds_read_b128 v[242:245], v158 offset:7168
	global_load_lds_dwordx4 v[200:201], off
	v_lshl_add_u64 v[200:201], s[68:69], 0, v[130:131]
	s_add_i32 m0, s15, 0xe000
	s_nop 0
	global_load_lds_dwordx4 v[200:201], off
	s_waitcnt vmcnt(8)
	s_waitcnt lgkmcnt(0)
	s_barrier
	s_setprio 1
	s_waitcnt lgkmcnt(0)
	v_mfma_f32_16x16x32_bf16 v[124:127], v[136:139], v[214:217], v[124:127]
	v_mfma_f32_16x16x32_bf16 v[124:127], v[140:143], v[218:221], v[124:127]
	v_mfma_f32_16x16x32_bf16 v[120:123], v[176:179], v[218:221], v[120:123]
	v_mfma_f32_16x16x32_bf16 v[120:123], v[172:175], v[214:217], v[120:123]
	v_mfma_f32_16x16x32_bf16 v[116:119], v[180:183], v[214:217], v[116:119]
	v_mfma_f32_16x16x32_bf16 v[116:119], v[184:187], v[218:221], v[116:119]
	v_mfma_f32_16x16x32_bf16 v[112:115], v[210:213], v[218:221], v[112:115]
	v_mfma_f32_16x16x32_bf16 v[112:115], v[206:209], v[214:217], v[112:115]
	v_mfma_f32_16x16x32_bf16 v[92:95], v[206:209], v[222:225], v[92:95]
	v_mfma_f32_16x16x32_bf16 v[92:95], v[210:213], v[226:229], v[92:95]
	v_mfma_f32_16x16x32_bf16 v[100:103], v[184:187], v[226:229], v[100:103]
	v_mfma_f32_16x16x32_bf16 v[100:103], v[180:183], v[222:225], v[100:103]
	v_mfma_f32_16x16x32_bf16 v[104:107], v[172:175], v[222:225], v[104:107]
	v_mfma_f32_16x16x32_bf16 v[104:107], v[176:179], v[226:229], v[104:107]
	v_mfma_f32_16x16x32_bf16 v[108:111], v[140:143], v[226:229], v[108:111]
	v_mfma_f32_16x16x32_bf16 v[108:111], v[136:139], v[222:225], v[108:111]
	s_setprio 0
	s_setprio 1
	v_mfma_f32_16x16x32_bf16 v[96:99], v[136:139], v[230:233], v[96:99]
	v_mfma_f32_16x16x32_bf16 v[96:99], v[140:143], v[234:237], v[96:99]
	v_mfma_f32_16x16x32_bf16 v[88:91], v[176:179], v[234:237], v[88:91]
	v_mfma_f32_16x16x32_bf16 v[88:91], v[172:175], v[230:233], v[88:91]
	v_mfma_f32_16x16x32_bf16 v[84:87], v[180:183], v[230:233], v[84:87]
	v_mfma_f32_16x16x32_bf16 v[84:87], v[184:187], v[234:237], v[84:87]
	v_mfma_f32_16x16x32_bf16 v[76:79], v[210:213], v[234:237], v[76:79]
	v_mfma_f32_16x16x32_bf16 v[76:79], v[206:209], v[230:233], v[76:79]
	v_mfma_f32_16x16x32_bf16 v[64:67], v[206:209], v[238:241], v[64:67]
	v_mfma_f32_16x16x32_bf16 v[64:67], v[210:213], v[242:245], v[64:67]
	v_mfma_f32_16x16x32_bf16 v[68:71], v[184:187], v[242:245], v[68:71]
	v_mfma_f32_16x16x32_bf16 v[68:71], v[180:183], v[238:241], v[68:71]
	v_mfma_f32_16x16x32_bf16 v[72:75], v[172:175], v[238:241], v[72:75]
	v_mfma_f32_16x16x32_bf16 v[72:75], v[176:179], v[242:245], v[72:75]
	s_setprio 3
	s_barrier
	v_mfma_f32_16x16x32_bf16 v[80:83], v[140:143], v[242:245], v[80:83]
	v_mfma_f32_16x16x32_bf16 v[80:83], v[136:139], v[238:241], v[80:83]
	s_setprio 0
	s_add_i32 s44, s72, s39
	v_lshl_add_u64 v[200:201], s[28:29], 0, v[166:167]
	s_mov_b32 m0, s44
	ds_read_b128 v[214:217], v158 offset:16384
	ds_read_b128 v[218:221], v158 offset:17408
	ds_read_b128 v[222:225], v158 offset:18432
	ds_read_b128 v[226:229], v158 offset:19456
	ds_read_b128 v[230:233], v158 offset:20480
	ds_read_b128 v[234:237], v158 offset:21504
	ds_read_b128 v[238:241], v158 offset:22528
	ds_read_b128 v[242:245], v158 offset:23552
	global_load_lds_dwordx4 v[200:201], off
	s_add_i32 m0, s44, 0x2000
	s_add_u32 s80, s28, 0x80000
	v_lshl_add_u64 v[246:247], s[28:29], 0, v[170:171]
	s_addc_u32 s81, s29, 0
	s_add_i32 s44, s73, s39
	global_load_lds_dwordx4 v[246:247], off
	v_lshl_add_u64 v[248:249], s[80:81], 0, v[166:167]
	s_mov_b32 m0, s44
	v_lshl_add_u64 v[250:251], s[48:49], 0, v[168:169]
	global_load_lds_dwordx4 v[248:249], off
	v_lshl_add_u64 v[248:249], s[80:81], 0, v[170:171]
	s_add_i32 m0, s44, 0x2000
	s_nop 0
	global_load_lds_dwordx4 v[248:249], off
	v_lshl_add_u64 v[248:249], s[48:49], 0, v[164:165]
	s_mov_b32 m0, s15
	s_nop 0
	global_load_lds_dwordx4 v[248:249], off
	s_mov_b32 m0, s41
	s_nop 0
	global_load_lds_dwordx4 v[250:251], off
	s_waitcnt vmcnt(8)
	s_waitcnt lgkmcnt(0)
	s_barrier
; #define PG8_STAGE(bufoff, gbase, voff) do { _Pragma("unroll") for (int _i = 0; _i < 2; ++_i) \
;         __builtin_amdgcn_global_load_lds((const unsigned*)((const char*)(gbase) + (voff)[_i]), (PG8_LAS unsigned*)(lds + (bufoff) + ldsw + _i * 8192), 16, 0, 0); } while (0)
; #define PG8_LDA(dst, b, h) do { _Pragma("unroll") for (int m = 0; m < 4; ++m) _Pragma("unroll") for (int k = 0; k < 2; ++k) dst[m][k] = *(const PG8_LAS bf16x8*)(lds + PG8_SA(b, h) + aoff + m * 2048 + k * 1024); } while (0)
; #define PG8_LDB(dst, b, h) do { _Pragma("unroll") for (int n = 0; n < 2; ++n) _Pragma("unroll") for (int k = 0; k < 2; ++k) dst[n][k] = *(const PG8_LAS bf16x8*)(lds + PG8_SB(b, h) + boff + n * 2048 + k * 1024); } while (0)
; #define PG8_MMA(ai, bj, At, Bt) do { __builtin_amdgcn_s_setprio(1); _Pragma("unroll") for (int m = 0; m < 4; ++m) _Pragma("unroll") for (int n = 0; n < 2; ++n) _Pragma("unroll") for (int k = 0; k < 2; ++k) \
;         acc[ai][bj][m][n] = __builtin_amdgcn_mfma_f32_16x16x32_bf16(Bt[n][k], At[m][k], acc[ai][bj][m][n], 0, 0, 0); __builtin_amdgcn_s_setprio(0); } while (0)
; #define PG8_WAIT_V(n) asm volatile("s_waitcnt vmcnt(" #n ")" ::: "memory")
; #define PG8_WAIT_L(n) asm volatile("s_waitcnt lgkmcnt(" #n ")" ::: "memory")
; #define PG8_BAR __builtin_amdgcn_s_barrier()
; #define PG8_SCHED __builtin_amdgcn_sched_barrier(0)
; template <class Epi, class Sched, bool ALIGN_EPI = false, bool SP2 = false>
; __device__ __forceinline__ void gemm_phase(PG8_LAS unsigned char* lds, const Gemm g, const Sched& S, const Epi& E) {
;     ...
;             PG8_WAIT_V(8); PG8_WAIT_L(0); PG8_BAR; PG8_MMA(1, 0, At, B0); PG8_MMA(1, 1, At, B1); PG8_BAR; PG8_SCHED;
;             PG8_LDB(B0, 1, 0); PG8_LDB(B1, 1, 1); PG8_SCHED; PG8_LDA(At, 1, 0); PG8_STAGE(PG8_SA(0, 1), a2 + hstep, voffA);
;             PG8_WAIT_V(8); PG8_WAIT_L(0); PG8_BAR; PG8_MMA(0, 0, At, B0); PG8_MMA(0, 1, At, B1); PG8_BAR; PG8_SCHED;
	s_setprio 1
	s_waitcnt lgkmcnt(0)
	v_mfma_f32_16x16x32_bf16 v[60:63], v[136:139], v[214:217], v[60:63]
	v_mfma_f32_16x16x32_bf16 v[60:63], v[140:143], v[218:221], v[60:63]
	v_mfma_f32_16x16x32_bf16 v[56:59], v[176:179], v[218:221], v[56:59]
	v_mfma_f32_16x16x32_bf16 v[56:59], v[172:175], v[214:217], v[56:59]
	v_mfma_f32_16x16x32_bf16 v[52:55], v[180:183], v[214:217], v[52:55]
	v_mfma_f32_16x16x32_bf16 v[52:55], v[184:187], v[218:221], v[52:55]
	v_mfma_f32_16x16x32_bf16 v[44:47], v[210:213], v[218:221], v[44:47]
	v_mfma_f32_16x16x32_bf16 v[44:47], v[206:209], v[214:217], v[44:47]
	v_mfma_f32_16x16x32_bf16 v[28:31], v[206:209], v[222:225], v[28:31]
	v_mfma_f32_16x16x32_bf16 v[28:31], v[210:213], v[226:229], v[28:31]
	v_mfma_f32_16x16x32_bf16 v[36:39], v[184:187], v[226:229], v[36:39]
	v_mfma_f32_16x16x32_bf16 v[36:39], v[180:183], v[222:225], v[36:39]
	v_mfma_f32_16x16x32_bf16 v[40:43], v[172:175], v[222:225], v[40:43]
	v_mfma_f32_16x16x32_bf16 v[40:43], v[176:179], v[226:229], v[40:43]
	v_mfma_f32_16x16x32_bf16 v[48:51], v[140:143], v[226:229], v[48:51]
	v_mfma_f32_16x16x32_bf16 v[48:51], v[136:139], v[222:225], v[48:51]
	s_setprio 0
	s_setprio 1
	v_mfma_f32_16x16x32_bf16 v[32:35], v[136:139], v[230:233], v[32:35]
	v_mfma_f32_16x16x32_bf16 v[32:35], v[140:143], v[234:237], v[32:35]
	v_mfma_f32_16x16x32_bf16 v[24:27], v[176:179], v[234:237], v[24:27]
	v_mfma_f32_16x16x32_bf16 v[24:27], v[172:175], v[230:233], v[24:27]
	v_mfma_f32_16x16x32_bf16 v[20:23], v[180:183], v[230:233], v[20:23]
	v_mfma_f32_16x16x32_bf16 v[20:23], v[184:187], v[234:237], v[20:23]
	v_mfma_f32_16x16x32_bf16 v[16:19], v[210:213], v[234:237], v[16:19]
	v_mfma_f32_16x16x32_bf16 v[16:19], v[206:209], v[230:233], v[16:19]
	v_mfma_f32_16x16x32_bf16 v[0:3], v[206:209], v[238:241], v[0:3]
	v_mfma_f32_16x16x32_bf16 v[0:3], v[210:213], v[242:245], v[0:3]
	v_mfma_f32_16x16x32_bf16 v[4:7], v[184:187], v[242:245], v[4:7]
	v_mfma_f32_16x16x32_bf16 v[4:7], v[180:183], v[238:241], v[4:7]
	v_mfma_f32_16x16x32_bf16 v[8:11], v[172:175], v[238:241], v[8:11]
	v_mfma_f32_16x16x32_bf16 v[8:11], v[176:179], v[242:245], v[8:11]
	s_setprio 3
	s_barrier
	v_mfma_f32_16x16x32_bf16 v[12:15], v[140:143], v[242:245], v[12:15]
	v_mfma_f32_16x16x32_bf16 v[12:15], v[136:139], v[238:241], v[12:15]
	s_setprio 0
	s_add_i32 s44, 0, 0x18000
	v_add_u32_e32 v144, s44, v146
	s_add_i32 s45, 0, 0x1c000
	ds_read_b128 v[136:139], v144
	ds_read_b128 v[140:143], v144 offset:1024
	ds_read_b128 v[172:175], v144 offset:2048
	ds_read_b128 v[176:179], v144 offset:3072
	v_add_u32_e32 v144, s45, v146
	ds_read_b128 v[180:183], v144
	ds_read_b128 v[184:187], v144 offset:1024
	ds_read_b128 v[206:209], v144 offset:2048
	ds_read_b128 v[210:213], v144 offset:3072
	s_add_u32 s48, s48, 0x80000
	s_addc_u32 s49, s49, 0
	s_mov_b32 m0, s56
	v_lshl_add_u64 v[252:253], s[48:49], 0, v[164:165]
	ds_read_b128 v[214:217], v158 offset:32768
	ds_read_b128 v[218:221], v158 offset:33792
	ds_read_b128 v[222:225], v158 offset:34816
	ds_read_b128 v[226:229], v158 offset:35840
	ds_read_b128 v[230:233], v158 offset:36864
	ds_read_b128 v[234:237], v158 offset:37888
	ds_read_b128 v[238:241], v158 offset:38912
	ds_read_b128 v[242:245], v158 offset:39936
	global_load_lds_dwordx4 v[252:253], off
	v_lshl_add_u64 v[252:253], s[48:49], 0, v[168:169]
	s_mov_b32 m0, s57
	s_nop 0
	global_load_lds_dwordx4 v[252:253], off
	s_waitcnt vmcnt(8)
	s_waitcnt lgkmcnt(0)
	s_barrier
	s_setprio 1
	s_waitcnt lgkmcnt(0)
	v_mfma_f32_16x16x32_bf16 v[124:127], v[136:139], v[214:217], v[124:127]
	v_mfma_f32_16x16x32_bf16 v[124:127], v[140:143], v[218:221], v[124:127]
	v_mfma_f32_16x16x32_bf16 v[120:123], v[176:179], v[218:221], v[120:123]
	v_mfma_f32_16x16x32_bf16 v[120:123], v[172:175], v[214:217], v[120:123]
	v_mfma_f32_16x16x32_bf16 v[116:119], v[180:183], v[214:217], v[116:119]
	v_mfma_f32_16x16x32_bf16 v[116:119], v[184:187], v[218:221], v[116:119]
	v_mfma_f32_16x16x32_bf16 v[112:115], v[210:213], v[218:221], v[112:115]
	v_mfma_f32_16x16x32_bf16 v[112:115], v[206:209], v[214:217], v[112:115]
	v_mfma_f32_16x16x32_bf16 v[92:95], v[206:209], v[222:225], v[92:95]
	v_mfma_f32_16x16x32_bf16 v[92:95], v[210:213], v[226:229], v[92:95]
	v_mfma_f32_16x16x32_bf16 v[100:103], v[184:187], v[226:229], v[100:103]
	v_mfma_f32_16x16x32_bf16 v[100:103], v[180:183], v[222:225], v[100:103]
	v_mfma_f32_16x16x32_bf16 v[104:107], v[172:175], v[222:225], v[104:107]
	v_mfma_f32_16x16x32_bf16 v[104:107], v[176:179], v[226:229], v[104:107]
	v_mfma_f32_16x16x32_bf16 v[108:111], v[140:143], v[226:229], v[108:111]
	v_mfma_f32_16x16x32_bf16 v[108:111], v[136:139], v[222:225], v[108:111]
	s_setprio 0
	s_setprio 1
	v_mfma_f32_16x16x32_bf16 v[96:99], v[136:139], v[230:233], v[96:99]
	v_mfma_f32_16x16x32_bf16 v[96:99], v[140:143], v[234:237], v[96:99]
	v_mfma_f32_16x16x32_bf16 v[88:91], v[176:179], v[234:237], v[88:91]
	v_mfma_f32_16x16x32_bf16 v[88:91], v[172:175], v[230:233], v[88:91]
	v_mfma_f32_16x16x32_bf16 v[84:87], v[180:183], v[230:233], v[84:87]
	v_mfma_f32_16x16x32_bf16 v[84:87], v[184:187], v[234:237], v[84:87]
	v_mfma_f32_16x16x32_bf16 v[76:79], v[210:213], v[234:237], v[76:79]
	v_mfma_f32_16x16x32_bf16 v[76:79], v[206:209], v[230:233], v[76:79]
	v_mfma_f32_16x16x32_bf16 v[64:67], v[206:209], v[238:241], v[64:67]
	v_mfma_f32_16x16x32_bf16 v[64:67], v[210:213], v[242:245], v[64:67]
	v_mfma_f32_16x16x32_bf16 v[68:71], v[184:187], v[242:245], v[68:71]
	v_mfma_f32_16x16x32_bf16 v[68:71], v[180:183], v[238:241], v[68:71]
	v_mfma_f32_16x16x32_bf16 v[72:75], v[172:175], v[238:241], v[72:75]
	v_mfma_f32_16x16x32_bf16 v[72:75], v[176:179], v[242:245], v[72:75]
	s_setprio 3
	s_barrier
; #define PG8_STAGE(bufoff, gbase, voff) do { _Pragma("unroll") for (int _i = 0; _i < 2; ++_i) \
;         __builtin_amdgcn_global_load_lds((const unsigned*)((const char*)(gbase) + (voff)[_i]), (PG8_LAS unsigned*)(lds + (bufoff) + ldsw + _i * 8192), 16, 0, 0); } while (0)
; #define PG8_LDA(dst, b, h) do { _Pragma("unroll") for (int m = 0; m < 4; ++m) _Pragma("unroll") for (int k = 0; k < 2; ++k) dst[m][k] = *(const PG8_LAS bf16x8*)(lds + PG8_SA(b, h) + aoff + m * 2048 + k * 1024); } while (0)
; #define PG8_MMA(ai, bj, At, Bt) do { __builtin_amdgcn_s_setprio(1); _Pragma("unroll") for (int m = 0; m < 4; ++m) _Pragma("unroll") for (int n = 0; n < 2; ++n) _Pragma("unroll") for (int k = 0; k < 2; ++k) \
;         acc[ai][bj][m][n] = __builtin_amdgcn_mfma_f32_16x16x32_bf16(Bt[n][k], At[m][k], acc[ai][bj][m][n], 0, 0, 0); __builtin_amdgcn_s_setprio(0); } while (0)
; #define PG8_WAIT_V(n) asm volatile("s_waitcnt vmcnt(" #n ")" ::: "memory")
; #define PG8_WAIT_L(n) asm volatile("s_waitcnt lgkmcnt(" #n ")" ::: "memory")
; #define PG8_BAR __builtin_amdgcn_s_barrier()
; #define PG8_SCHED __builtin_amdgcn_sched_barrier(0)
; template <class Epi, class Sched, bool ALIGN_EPI = false, bool SP2 = false>
; __device__ __forceinline__ void gemm_phase(PG8_LAS unsigned char* lds, const Gemm g, const Sched& S, const Epi& E) {
;     ...
;         for (int t = 0; t < nt; t += 2) {
;     ...
;             PG8_LDA(At, 1, 1); PG8_STAGE(PG8_SB(1, 0), b3, voffB); PG8_STAGE(PG8_SB(1, 1), b3 + hstep, voffB); PG8_STAGE(PG8_SA(1, 0), a3, voffA);
;             PG8_WAIT_V(8); PG8_WAIT_L(0); PG8_BAR; PG8_MMA(1, 0, At, B0); PG8_MMA(1, 1, At, B1); PG8_BAR; PG8_SCHED;
	v_mfma_f32_16x16x32_bf16 v[80:83], v[140:143], v[242:245], v[80:83]
	v_mfma_f32_16x16x32_bf16 v[80:83], v[136:139], v[238:241], v[80:83]
	s_setprio 0
	s_add_i32 s44, s44, s39
	v_lshl_add_u64 v[200:201], v[200:201], 0, s[18:19]
	s_mov_b32 m0, s44
	ds_read_b128 v[214:217], v158 offset:49152
	ds_read_b128 v[218:221], v158 offset:50176
	ds_read_b128 v[222:225], v158 offset:51200
	ds_read_b128 v[226:229], v158 offset:52224
	ds_read_b128 v[230:233], v158 offset:53248
	ds_read_b128 v[234:237], v158 offset:54272
	ds_read_b128 v[238:241], v158 offset:55296
	ds_read_b128 v[242:245], v158 offset:56320
	global_load_lds_dwordx4 v[200:201], off
	s_add_i32 m0, s44, 0x2000
	s_add_u32 s28, s28, 0x80080
	v_lshl_add_u64 v[200:201], v[246:247], 0, s[18:19]
	s_addc_u32 s29, s29, 0
	s_add_i32 s44, s45, s39
	global_load_lds_dwordx4 v[200:201], off
	v_lshl_add_u64 v[200:201], s[28:29], 0, v[166:167]
	s_mov_b32 m0, s44
	s_nop 0
	global_load_lds_dwordx4 v[200:201], off
	v_lshl_add_u64 v[200:201], s[28:29], 0, v[170:171]
	s_add_i32 m0, s44, 0x2000
	s_nop 0
	global_load_lds_dwordx4 v[200:201], off
	v_lshl_add_u64 v[200:201], v[248:249], 0, s[18:19]
	s_mov_b32 m0, s70
	s_nop 0
	global_load_lds_dwordx4 v[200:201], off
	v_lshl_add_u64 v[200:201], v[250:251], 0, s[18:19]
	s_mov_b32 m0, s71
	s_nop 0
	global_load_lds_dwordx4 v[200:201], off
	s_add_i32 s79, s79, 2
	s_add_u32 s68, s68, 0x100
	s_addc_u32 s69, s69, 0
	s_add_u32 s77, s77, 0x100
	s_addc_u32 s78, s78, 0
	s_waitcnt vmcnt(8)
	s_waitcnt lgkmcnt(0)
	s_barrier
	s_setprio 1
	s_waitcnt lgkmcnt(0)
	v_mfma_f32_16x16x32_bf16 v[60:63], v[136:139], v[214:217], v[60:63]
	v_mfma_f32_16x16x32_bf16 v[60:63], v[140:143], v[218:221], v[60:63]
	v_mfma_f32_16x16x32_bf16 v[56:59], v[176:179], v[218:221], v[56:59]
	v_mfma_f32_16x16x32_bf16 v[56:59], v[172:175], v[214:217], v[56:59]
	v_mfma_f32_16x16x32_bf16 v[52:55], v[180:183], v[214:217], v[52:55]
	v_mfma_f32_16x16x32_bf16 v[52:55], v[184:187], v[218:221], v[52:55]
	v_mfma_f32_16x16x32_bf16 v[44:47], v[210:213], v[218:221], v[44:47]
	v_mfma_f32_16x16x32_bf16 v[44:47], v[206:209], v[214:217], v[44:47]
	v_mfma_f32_16x16x32_bf16 v[28:31], v[206:209], v[222:225], v[28:31]
	v_mfma_f32_16x16x32_bf16 v[28:31], v[210:213], v[226:229], v[28:31]
	v_mfma_f32_16x16x32_bf16 v[36:39], v[184:187], v[226:229], v[36:39]
	v_mfma_f32_16x16x32_bf16 v[36:39], v[180:183], v[222:225], v[36:39]
	v_mfma_f32_16x16x32_bf16 v[40:43], v[172:175], v[222:225], v[40:43]
	v_mfma_f32_16x16x32_bf16 v[40:43], v[176:179], v[226:229], v[40:43]
	v_mfma_f32_16x16x32_bf16 v[48:51], v[140:143], v[226:229], v[48:51]
	v_mfma_f32_16x16x32_bf16 v[48:51], v[136:139], v[222:225], v[48:51]
	s_setprio 0
	s_setprio 1
	v_mfma_f32_16x16x32_bf16 v[32:35], v[136:139], v[230:233], v[32:35]
	v_mfma_f32_16x16x32_bf16 v[32:35], v[140:143], v[234:237], v[32:35]
	v_mfma_f32_16x16x32_bf16 v[24:27], v[176:179], v[234:237], v[24:27]
	v_mfma_f32_16x16x32_bf16 v[24:27], v[172:175], v[230:233], v[24:27]
	v_mfma_f32_16x16x32_bf16 v[20:23], v[180:183], v[230:233], v[20:23]
	v_mfma_f32_16x16x32_bf16 v[20:23], v[184:187], v[234:237], v[20:23]
	v_mfma_f32_16x16x32_bf16 v[16:19], v[210:213], v[234:237], v[16:19]
	v_mfma_f32_16x16x32_bf16 v[16:19], v[206:209], v[230:233], v[16:19]
	v_mfma_f32_16x16x32_bf16 v[0:3], v[206:209], v[238:241], v[0:3]
	v_mfma_f32_16x16x32_bf16 v[0:3], v[210:213], v[242:245], v[0:3]
	v_mfma_f32_16x16x32_bf16 v[4:7], v[184:187], v[242:245], v[4:7]
	v_mfma_f32_16x16x32_bf16 v[4:7], v[180:183], v[238:241], v[4:7]
	v_mfma_f32_16x16x32_bf16 v[8:11], v[172:175], v[238:241], v[8:11]
	v_mfma_f32_16x16x32_bf16 v[8:11], v[176:179], v[242:245], v[8:11]
	s_setprio 3
	s_barrier
	v_mfma_f32_16x16x32_bf16 v[12:15], v[140:143], v[242:245], v[12:15]
	v_mfma_f32_16x16x32_bf16 v[12:15], v[136:139], v[238:241], v[12:15]
	s_setprio 0
	s_cmp_gt_u32 s79, 29
	s_cbranch_scc0 .LBB0_416
	s_and_b64 vcc, exec, s[20:21]
	s_cbranch_vccz .LBB0_419
	s_barrier

; #define PG8_STAGE(bufoff, gbase, voff) do { _Pragma("unroll") for (int _i = 0; _i < 2; ++_i) \
;         __builtin_amdgcn_global_load_lds((const unsigned*)((const char*)(gbase) + (voff)[_i]), (PG8_LAS unsigned*)(lds + (bufoff) + ldsw + _i * 8192), 16, 0, 0); } while (0)
; #define PG8_LDA(dst, b, h) do { _Pragma("unroll") for (int m = 0; m < 4; ++m) _Pragma("unroll") for (int k = 0; k < 2; ++k) dst[m][k] = *(const PG8_LAS bf16x8*)(lds + PG8_SA(b, h) + aoff + m * 2048 + k * 1024); } while (0)
; #define PG8_LDB(dst, b, h) do { _Pragma("unroll") for (int n = 0; n < 2; ++n) _Pragma("unroll") for (int k = 0; k < 2; ++k) dst[n][k] = *(const PG8_LAS bf16x8*)(lds + PG8_SB(b, h) + boff + n * 2048 + k * 1024); } while (0)
; #define PG8_MMA(ai, bj, At, Bt) do { __builtin_amdgcn_s_setprio(1); _Pragma("unroll") for (int m = 0; m < 4; ++m) _Pragma("unroll") for (int n = 0; n < 2; ++n) _Pragma("unroll") for (int k = 0; k < 2; ++k) \
;         acc[ai][bj][m][n] = __builtin_amdgcn_mfma_f32_16x16x32_bf16(Bt[n][k], At[m][k], acc[ai][bj][m][n], 0, 0, 0); __builtin_amdgcn_s_setprio(0); } while (0)
; #define PG8_WAIT_V(n) asm volatile("s_waitcnt vmcnt(" #n ")" ::: "memory")
; #define PG8_WAIT_L(n) asm volatile("s_waitcnt lgkmcnt(" #n ")" ::: "memory")
; #define PG8_BAR __builtin_amdgcn_s_barrier()
; template <class Epi, class Sched, bool ALIGN_EPI = false, bool SP2 = false>
; __device__ __forceinline__ void gemm_phase(PG8_LAS unsigned char* lds, const Gemm g, const Sched& S, const Epi& E) {
;     ...
;             const char* a1 = cA + (size_t)(t + 1) * kstep;
;             const char* a2 = last ? nA : cA + (size_t)(t + 2) * kstep; const char* b2 = last ? nB : cB + (size_t)(t + 2) * kstep;
;             const char* a3 = a2 + kstep; const char* b3 = b2 + kstep;
;             if (last && has_next) S.a_ready(nxt);
;             if constexpr (SP2) {
;             PG8_LDB(B0, 0, 0); PG8_LDB(B1, 0, 1); PG8_SCHED; PG8_LDA(At, 0, 0); PG8_STAGE(PG8_SA(1, 1), a1 + hstep, voffA);
;             PG8_WAIT_V(8); PG8_WAIT_L(0); PG8_BAR; PG8_MMA(0, 0, At, B0); PG8_MMA(0, 1, At, B1); PG8_BAR; PG8_SCHED;
;             PG8_LDA(At, 0, 1); PG8_STAGE(PG8_SB(0, 0), b2, voffB); PG8_STAGE(PG8_SB(0, 1), b2 + hstep, voffB); PG8_STAGE(PG8_SA(0, 0), a2, voffA);
;             PG8_WAIT_V(8); PG8_WAIT_L(0); PG8_BAR; PG8_MMA(1, 0, At, B0); PG8_MMA(1, 1, At, B1); PG8_BAR; PG8_SCHED;
.LBB0_482:
	ds_read_b128 v[76:79], v171
	ds_read_b128 v[84:87], v171 offset:1024
	ds_read_b128 v[92:95], v171 offset:2048
	ds_read_b128 v[96:99], v171 offset:3072
	ds_read_b128 v[144:147], v186
	ds_read_b128 v[148:151], v186 offset:1024
	ds_read_b128 v[152:155], v186 offset:2048
	ds_read_b128 v[156:159], v186 offset:3072
	s_add_u32 s28, s64, 0xffea0080
	s_addc_u32 s29, s65, -1
	s_cmpk_eq_i32 s77, 0x54
	s_cselect_b32 s49, s39, s29
	s_cselect_b32 s48, s38, s28
	s_cselect_b32 s29, s63, s35
	s_cselect_b32 s28, s62, s34
	v_lshl_add_u64 v[200:201], s[64:65], 0, v[172:173]
	s_add_i32 m0, s56, 0xc000
	ds_read_b128 v[178:181], v187
	ds_read_b128 v[182:185], v187 offset:1024
	ds_read_b128 v[206:209], v187 offset:2048
	ds_read_b128 v[210:213], v187 offset:3072
	ds_read_b128 v[214:217], v187 offset:4096
	ds_read_b128 v[218:221], v187 offset:5120
	ds_read_b128 v[222:225], v187 offset:6144
	ds_read_b128 v[226:229], v187 offset:7168
	global_load_lds_dwordx4 v[200:201], off
	v_lshl_add_u64 v[200:201], s[64:65], 0, v[174:175]
	s_add_i32 m0, s56, 0xe000
	s_nop 0
	global_load_lds_dwordx4 v[200:201], off
	s_waitcnt vmcnt(8)
	s_waitcnt lgkmcnt(0)
	s_barrier
	s_setprio 1
	s_waitcnt lgkmcnt(0)
	v_mfma_f32_16x16x32_bf16 v[140:143], v[76:79], v[178:181], v[140:143]
	v_mfma_f32_16x16x32_bf16 v[140:143], v[84:87], v[182:185], v[140:143]
	v_mfma_f32_16x16x32_bf16 v[136:139], v[96:99], v[182:185], v[136:139]
	v_mfma_f32_16x16x32_bf16 v[136:139], v[92:95], v[178:181], v[136:139]
	v_mfma_f32_16x16x32_bf16 v[132:135], v[144:147], v[178:181], v[132:135]
	v_mfma_f32_16x16x32_bf16 v[132:135], v[148:151], v[182:185], v[132:135]
	v_mfma_f32_16x16x32_bf16 v[128:131], v[156:159], v[182:185], v[128:131]
	v_mfma_f32_16x16x32_bf16 v[128:131], v[152:155], v[178:181], v[128:131]
	v_mfma_f32_16x16x32_bf16 v[112:115], v[152:155], v[206:209], v[112:115]
	v_mfma_f32_16x16x32_bf16 v[112:115], v[156:159], v[210:213], v[112:115]
	v_mfma_f32_16x16x32_bf16 v[116:119], v[148:151], v[210:213], v[116:119]
	v_mfma_f32_16x16x32_bf16 v[116:119], v[144:147], v[206:209], v[116:119]
	v_mfma_f32_16x16x32_bf16 v[120:123], v[92:95], v[206:209], v[120:123]
	v_mfma_f32_16x16x32_bf16 v[120:123], v[96:99], v[210:213], v[120:123]
	v_mfma_f32_16x16x32_bf16 v[124:127], v[84:87], v[210:213], v[124:127]
	v_mfma_f32_16x16x32_bf16 v[124:127], v[76:79], v[206:209], v[124:127]
	s_setprio 0
	s_setprio 1
	v_mfma_f32_16x16x32_bf16 v[108:111], v[76:79], v[214:217], v[108:111]
	v_mfma_f32_16x16x32_bf16 v[108:111], v[84:87], v[218:221], v[108:111]
	v_mfma_f32_16x16x32_bf16 v[104:107], v[96:99], v[218:221], v[104:107]
	v_mfma_f32_16x16x32_bf16 v[104:107], v[92:95], v[214:217], v[104:107]
	v_mfma_f32_16x16x32_bf16 v[100:103], v[144:147], v[214:217], v[100:103]
	v_mfma_f32_16x16x32_bf16 v[100:103], v[148:151], v[218:221], v[100:103]
	v_mfma_f32_16x16x32_bf16 v[88:91], v[156:159], v[218:221], v[88:91]
	v_mfma_f32_16x16x32_bf16 v[88:91], v[152:155], v[214:217], v[88:91]
	v_mfma_f32_16x16x32_bf16 v[64:67], v[152:155], v[222:225], v[64:67]
	v_mfma_f32_16x16x32_bf16 v[64:67], v[156:159], v[226:229], v[64:67]
	v_mfma_f32_16x16x32_bf16 v[68:71], v[148:151], v[226:229], v[68:71]
	v_mfma_f32_16x16x32_bf16 v[68:71], v[144:147], v[222:225], v[68:71]
	v_mfma_f32_16x16x32_bf16 v[72:75], v[92:95], v[222:225], v[72:75]
	v_mfma_f32_16x16x32_bf16 v[72:75], v[96:99], v[226:229], v[72:75]
	s_setprio 3
	s_barrier
	v_mfma_f32_16x16x32_bf16 v[80:83], v[84:87], v[226:229], v[80:83]
	v_mfma_f32_16x16x32_bf16 v[80:83], v[76:79], v[222:225], v[80:83]
	s_setprio 0
	s_add_i32 s44, s70, s41
	v_lshl_add_u64 v[200:201], s[28:29], 0, v[160:161]
	s_mov_b32 m0, s44
	ds_read_b128 v[178:181], v187 offset:16384
	ds_read_b128 v[182:185], v187 offset:17408
	ds_read_b128 v[206:209], v187 offset:18432
	ds_read_b128 v[210:213], v187 offset:19456
	ds_read_b128 v[214:217], v187 offset:20480
	ds_read_b128 v[218:221], v187 offset:21504
	ds_read_b128 v[222:225], v187 offset:22528
	ds_read_b128 v[226:229], v187 offset:23552
	global_load_lds_dwordx4 v[200:201], off
	s_add_i32 m0, s44, 0x2000
	s_add_u32 s78, s28, 0x160000
	v_lshl_add_u64 v[230:231], s[28:29], 0, v[162:163]
	s_addc_u32 s79, s29, 0
	s_add_i32 s44, s71, s41
	global_load_lds_dwordx4 v[230:231], off
	v_lshl_add_u64 v[232:233], s[78:79], 0, v[160:161]
	s_mov_b32 m0, s44
	v_lshl_add_u64 v[234:235], s[48:49], 0, v[162:163]
	global_load_lds_dwordx4 v[232:233], off
	v_lshl_add_u64 v[232:233], s[78:79], 0, v[162:163]
	s_add_i32 m0, s44, 0x2000
	s_nop 0
	global_load_lds_dwordx4 v[232:233], off
	v_lshl_add_u64 v[232:233], s[48:49], 0, v[160:161]
	s_mov_b32 m0, s56
	s_nop 0
	global_load_lds_dwordx4 v[232:233], off
	s_mov_b32 m0, s57
	s_nop 0
	global_load_lds_dwordx4 v[234:235], off
	s_waitcnt vmcnt(8)
	s_waitcnt lgkmcnt(0)
	s_barrier
; #define PG8_STAGE(bufoff, gbase, voff) do { _Pragma("unroll") for (int _i = 0; _i < 2; ++_i) \
;         __builtin_amdgcn_global_load_lds((const unsigned*)((const char*)(gbase) + (voff)[_i]), (PG8_LAS unsigned*)(lds + (bufoff) + ldsw + _i * 8192), 16, 0, 0); } while (0)
; #define PG8_LDA(dst, b, h) do { _Pragma("unroll") for (int m = 0; m < 4; ++m) _Pragma("unroll") for (int k = 0; k < 2; ++k) dst[m][k] = *(const PG8_LAS bf16x8*)(lds + PG8_SA(b, h) + aoff + m * 2048 + k * 1024); } while (0)
; #define PG8_LDB(dst, b, h) do { _Pragma("unroll") for (int n = 0; n < 2; ++n) _Pragma("unroll") for (int k = 0; k < 2; ++k) dst[n][k] = *(const PG8_LAS bf16x8*)(lds + PG8_SB(b, h) + boff + n * 2048 + k * 1024); } while (0)
; #define PG8_MMA(ai, bj, At, Bt) do { __builtin_amdgcn_s_setprio(1); _Pragma("unroll") for (int m = 0; m < 4; ++m) _Pragma("unroll") for (int n = 0; n < 2; ++n) _Pragma("unroll") for (int k = 0; k < 2; ++k) \
;         acc[ai][bj][m][n] = __builtin_amdgcn_mfma_f32_16x16x32_bf16(Bt[n][k], At[m][k], acc[ai][bj][m][n], 0, 0, 0); __builtin_amdgcn_s_setprio(0); } while (0)
; #define PG8_WAIT_V(n) asm volatile("s_waitcnt vmcnt(" #n ")" ::: "memory")
; #define PG8_WAIT_L(n) asm volatile("s_waitcnt lgkmcnt(" #n ")" ::: "memory")
; #define PG8_BAR __builtin_amdgcn_s_barrier()
; #define PG8_SCHED __builtin_amdgcn_sched_barrier(0)
; template <class Epi, class Sched, bool ALIGN_EPI = false, bool SP2 = false>
; __device__ __forceinline__ void gemm_phase(PG8_LAS unsigned char* lds, const Gemm g, const Sched& S, const Epi& E) {
;     ...
;             PG8_WAIT_V(8); PG8_WAIT_L(0); PG8_BAR; PG8_MMA(1, 0, At, B0); PG8_MMA(1, 1, At, B1); PG8_BAR; PG8_SCHED;
;             PG8_LDB(B0, 1, 0); PG8_LDB(B1, 1, 1); PG8_SCHED; PG8_LDA(At, 1, 0); PG8_STAGE(PG8_SA(0, 1), a2 + hstep, voffA);
;             PG8_WAIT_V(8); PG8_WAIT_L(0); PG8_BAR; PG8_MMA(0, 0, At, B0); PG8_MMA(0, 1, At, B1); PG8_BAR; PG8_SCHED;
	s_setprio 1
	s_waitcnt lgkmcnt(0)
	v_mfma_f32_16x16x32_bf16 v[60:63], v[76:79], v[178:181], v[60:63]
	v_mfma_f32_16x16x32_bf16 v[60:63], v[84:87], v[182:185], v[60:63]
	v_mfma_f32_16x16x32_bf16 v[56:59], v[96:99], v[182:185], v[56:59]
	v_mfma_f32_16x16x32_bf16 v[56:59], v[92:95], v[178:181], v[56:59]
	v_mfma_f32_16x16x32_bf16 v[52:55], v[144:147], v[178:181], v[52:55]
	v_mfma_f32_16x16x32_bf16 v[52:55], v[148:151], v[182:185], v[52:55]
	v_mfma_f32_16x16x32_bf16 v[48:51], v[156:159], v[182:185], v[48:51]
	v_mfma_f32_16x16x32_bf16 v[48:51], v[152:155], v[178:181], v[48:51]
	v_mfma_f32_16x16x32_bf16 v[32:35], v[152:155], v[206:209], v[32:35]
	v_mfma_f32_16x16x32_bf16 v[32:35], v[156:159], v[210:213], v[32:35]
	v_mfma_f32_16x16x32_bf16 v[36:39], v[148:151], v[210:213], v[36:39]
	v_mfma_f32_16x16x32_bf16 v[36:39], v[144:147], v[206:209], v[36:39]
	v_mfma_f32_16x16x32_bf16 v[40:43], v[92:95], v[206:209], v[40:43]
	v_mfma_f32_16x16x32_bf16 v[40:43], v[96:99], v[210:213], v[40:43]
	v_mfma_f32_16x16x32_bf16 v[44:47], v[84:87], v[210:213], v[44:47]
	v_mfma_f32_16x16x32_bf16 v[44:47], v[76:79], v[206:209], v[44:47]
	s_setprio 0
	s_setprio 1
	v_mfma_f32_16x16x32_bf16 v[28:31], v[76:79], v[214:217], v[28:31]
	v_mfma_f32_16x16x32_bf16 v[28:31], v[84:87], v[218:221], v[28:31]
	v_mfma_f32_16x16x32_bf16 v[24:27], v[96:99], v[218:221], v[24:27]
	v_mfma_f32_16x16x32_bf16 v[24:27], v[92:95], v[214:217], v[24:27]
	v_mfma_f32_16x16x32_bf16 v[20:23], v[144:147], v[214:217], v[20:23]
	v_mfma_f32_16x16x32_bf16 v[20:23], v[148:151], v[218:221], v[20:23]
	v_mfma_f32_16x16x32_bf16 v[16:19], v[156:159], v[218:221], v[16:19]
	v_mfma_f32_16x16x32_bf16 v[16:19], v[152:155], v[214:217], v[16:19]
	v_mfma_f32_16x16x32_bf16 v[0:3], v[152:155], v[222:225], v[0:3]
	v_mfma_f32_16x16x32_bf16 v[0:3], v[156:159], v[226:229], v[0:3]
	v_mfma_f32_16x16x32_bf16 v[4:7], v[148:151], v[226:229], v[4:7]
	v_mfma_f32_16x16x32_bf16 v[4:7], v[144:147], v[222:225], v[4:7]
	v_mfma_f32_16x16x32_bf16 v[8:11], v[92:95], v[222:225], v[8:11]
	v_mfma_f32_16x16x32_bf16 v[8:11], v[96:99], v[226:229], v[8:11]
	s_setprio 3
	s_barrier
	v_mfma_f32_16x16x32_bf16 v[12:15], v[84:87], v[226:229], v[12:15]
	v_mfma_f32_16x16x32_bf16 v[12:15], v[76:79], v[222:225], v[12:15]
	s_setprio 0
	s_add_i32 s44, 0, 0x18000
	s_add_i32 s45, 0, 0x1c000
	v_add_u32_e32 v96, s44, v167
	v_add_u32_e32 v156, s45, v167
	ds_read_b128 v[76:79], v96
	ds_read_b128 v[84:87], v96 offset:1024
	ds_read_b128 v[92:95], v96 offset:2048
	ds_read_b128 v[96:99], v96 offset:3072
	ds_read_b128 v[144:147], v156
	ds_read_b128 v[148:151], v156 offset:1024
	ds_read_b128 v[152:155], v156 offset:2048
	ds_read_b128 v[156:159], v156 offset:3072
	s_add_u32 s48, s48, 0x160000
	s_addc_u32 s49, s49, 0
	s_mov_b32 m0, s61
	v_lshl_add_u64 v[236:237], s[48:49], 0, v[160:161]
	ds_read_b128 v[178:181], v187 offset:32768
	ds_read_b128 v[182:185], v187 offset:33792
	ds_read_b128 v[206:209], v187 offset:34816
	ds_read_b128 v[210:213], v187 offset:35840
	ds_read_b128 v[214:217], v187 offset:36864
	ds_read_b128 v[218:221], v187 offset:37888
	ds_read_b128 v[222:225], v187 offset:38912
	ds_read_b128 v[226:229], v187 offset:39936
	global_load_lds_dwordx4 v[236:237], off
	v_lshl_add_u64 v[236:237], s[48:49], 0, v[162:163]
	s_mov_b32 m0, s66
	s_nop 0
	global_load_lds_dwordx4 v[236:237], off
	s_waitcnt vmcnt(8)
	s_waitcnt lgkmcnt(0)
	s_barrier
	s_setprio 1
	s_waitcnt lgkmcnt(0)
	v_mfma_f32_16x16x32_bf16 v[140:143], v[76:79], v[178:181], v[140:143]
	v_mfma_f32_16x16x32_bf16 v[140:143], v[84:87], v[182:185], v[140:143]
	v_mfma_f32_16x16x32_bf16 v[136:139], v[96:99], v[182:185], v[136:139]
	v_mfma_f32_16x16x32_bf16 v[136:139], v[92:95], v[178:181], v[136:139]
	v_mfma_f32_16x16x32_bf16 v[132:135], v[144:147], v[178:181], v[132:135]
	v_mfma_f32_16x16x32_bf16 v[132:135], v[148:151], v[182:185], v[132:135]
	v_mfma_f32_16x16x32_bf16 v[128:131], v[156:159], v[182:185], v[128:131]
	v_mfma_f32_16x16x32_bf16 v[128:131], v[152:155], v[178:181], v[128:131]
	v_mfma_f32_16x16x32_bf16 v[112:115], v[152:155], v[206:209], v[112:115]
	v_mfma_f32_16x16x32_bf16 v[112:115], v[156:159], v[210:213], v[112:115]
	v_mfma_f32_16x16x32_bf16 v[116:119], v[148:151], v[210:213], v[116:119]
	v_mfma_f32_16x16x32_bf16 v[116:119], v[144:147], v[206:209], v[116:119]
	v_mfma_f32_16x16x32_bf16 v[120:123], v[92:95], v[206:209], v[120:123]
	v_mfma_f32_16x16x32_bf16 v[120:123], v[96:99], v[210:213], v[120:123]
	v_mfma_f32_16x16x32_bf16 v[124:127], v[84:87], v[210:213], v[124:127]
	v_mfma_f32_16x16x32_bf16 v[124:127], v[76:79], v[206:209], v[124:127]
	s_setprio 0
	s_setprio 1
	v_mfma_f32_16x16x32_bf16 v[108:111], v[76:79], v[214:217], v[108:111]
	v_mfma_f32_16x16x32_bf16 v[108:111], v[84:87], v[218:221], v[108:111]
	v_mfma_f32_16x16x32_bf16 v[104:107], v[96:99], v[218:221], v[104:107]
	v_mfma_f32_16x16x32_bf16 v[104:107], v[92:95], v[214:217], v[104:107]
	v_mfma_f32_16x16x32_bf16 v[100:103], v[144:147], v[214:217], v[100:103]
	v_mfma_f32_16x16x32_bf16 v[100:103], v[148:151], v[218:221], v[100:103]
	v_mfma_f32_16x16x32_bf16 v[88:91], v[156:159], v[218:221], v[88:91]
	v_mfma_f32_16x16x32_bf16 v[88:91], v[152:155], v[214:217], v[88:91]
	v_mfma_f32_16x16x32_bf16 v[64:67], v[152:155], v[222:225], v[64:67]
	v_mfma_f32_16x16x32_bf16 v[64:67], v[156:159], v[226:229], v[64:67]
	v_mfma_f32_16x16x32_bf16 v[68:71], v[148:151], v[226:229], v[68:71]
	v_mfma_f32_16x16x32_bf16 v[68:71], v[144:147], v[222:225], v[68:71]
	v_mfma_f32_16x16x32_bf16 v[72:75], v[92:95], v[222:225], v[72:75]
	v_mfma_f32_16x16x32_bf16 v[72:75], v[96:99], v[226:229], v[72:75]
	s_setprio 3
	s_barrier
; #define PG8_STAGE(bufoff, gbase, voff) do { _Pragma("unroll") for (int _i = 0; _i < 2; ++_i) \
;         __builtin_amdgcn_global_load_lds((const unsigned*)((const char*)(gbase) + (voff)[_i]), (PG8_LAS unsigned*)(lds + (bufoff) + ldsw + _i * 8192), 16, 0, 0); } while (0)
; #define PG8_LDA(dst, b, h) do { _Pragma("unroll") for (int m = 0; m < 4; ++m) _Pragma("unroll") for (int k = 0; k < 2; ++k) dst[m][k] = *(const PG8_LAS bf16x8*)(lds + PG8_SA(b, h) + aoff + m * 2048 + k * 1024); } while (0)
; #define PG8_MMA(ai, bj, At, Bt) do { __builtin_amdgcn_s_setprio(1); _Pragma("unroll") for (int m = 0; m < 4; ++m) _Pragma("unroll") for (int n = 0; n < 2; ++n) _Pragma("unroll") for (int k = 0; k < 2; ++k) \
;         acc[ai][bj][m][n] = __builtin_amdgcn_mfma_f32_16x16x32_bf16(Bt[n][k], At[m][k], acc[ai][bj][m][n], 0, 0, 0); __builtin_amdgcn_s_setprio(0); } while (0)
; #define PG8_WAIT_V(n) asm volatile("s_waitcnt vmcnt(" #n ")" ::: "memory")
; #define PG8_WAIT_L(n) asm volatile("s_waitcnt lgkmcnt(" #n ")" ::: "memory")
; #define PG8_BAR __builtin_amdgcn_s_barrier()
; #define PG8_SCHED __builtin_amdgcn_sched_barrier(0)
; template <class Epi, class Sched, bool ALIGN_EPI = false, bool SP2 = false>
; __device__ __forceinline__ void gemm_phase(PG8_LAS unsigned char* lds, const Gemm g, const Sched& S, const Epi& E) {
;     ...
;         for (int t = 0; t < nt; t += 2) {
;     ...
;             PG8_LDA(At, 1, 1); PG8_STAGE(PG8_SB(1, 0), b3, voffB); PG8_STAGE(PG8_SB(1, 1), b3 + hstep, voffB); PG8_STAGE(PG8_SA(1, 0), a3, voffA);
;             PG8_WAIT_V(8); PG8_WAIT_L(0); PG8_BAR; PG8_MMA(1, 0, At, B0); PG8_MMA(1, 1, At, B1); PG8_BAR; PG8_SCHED;
;     ...
;         if constexpr (ALIGN_EPI) { if (wr == 0) PG8_BAR; }
	v_mfma_f32_16x16x32_bf16 v[80:83], v[84:87], v[226:229], v[80:83]
	v_mfma_f32_16x16x32_bf16 v[80:83], v[76:79], v[222:225], v[80:83]
	s_setprio 0
	s_add_i32 s44, s44, s41
	v_lshl_add_u64 v[200:201], v[200:201], 0, s[20:21]
	s_mov_b32 m0, s44
	ds_read_b128 v[178:181], v187 offset:49152
	ds_read_b128 v[182:185], v187 offset:50176
	ds_read_b128 v[206:209], v187 offset:51200
	ds_read_b128 v[210:213], v187 offset:52224
	ds_read_b128 v[214:217], v187 offset:53248
	ds_read_b128 v[218:221], v187 offset:54272
	ds_read_b128 v[222:225], v187 offset:55296
	ds_read_b128 v[226:229], v187 offset:56320
	global_load_lds_dwordx4 v[200:201], off
	s_add_i32 m0, s44, 0x2000
	s_add_u32 s28, s28, 0x160080
	v_lshl_add_u64 v[200:201], v[230:231], 0, s[20:21]
	s_addc_u32 s29, s29, 0
	s_add_i32 s44, s45, s41
	global_load_lds_dwordx4 v[200:201], off
	v_lshl_add_u64 v[200:201], s[28:29], 0, v[160:161]
	s_mov_b32 m0, s44
	s_nop 0
	global_load_lds_dwordx4 v[200:201], off
	v_lshl_add_u64 v[200:201], s[28:29], 0, v[162:163]
	s_add_i32 m0, s44, 0x2000
	s_nop 0
	global_load_lds_dwordx4 v[200:201], off
	v_lshl_add_u64 v[200:201], v[232:233], 0, s[20:21]
	s_mov_b32 m0, s67
	s_nop 0
	global_load_lds_dwordx4 v[200:201], off
	v_lshl_add_u64 v[200:201], v[234:235], 0, s[20:21]
	s_mov_b32 m0, s68
	s_nop 0
	global_load_lds_dwordx4 v[200:201], off
	s_add_i32 s77, s77, 2
	s_add_u32 s64, s64, 0x100
	s_addc_u32 s65, s65, 0
	s_add_u32 s34, s34, 0x100
	s_addc_u32 s35, s35, 0
	s_waitcnt vmcnt(8)
	s_waitcnt lgkmcnt(0)
	s_barrier
	s_setprio 1
	s_waitcnt lgkmcnt(0)
	v_mfma_f32_16x16x32_bf16 v[60:63], v[76:79], v[178:181], v[60:63]
	v_mfma_f32_16x16x32_bf16 v[60:63], v[84:87], v[182:185], v[60:63]
	v_mfma_f32_16x16x32_bf16 v[56:59], v[96:99], v[182:185], v[56:59]
	v_mfma_f32_16x16x32_bf16 v[56:59], v[92:95], v[178:181], v[56:59]
	v_mfma_f32_16x16x32_bf16 v[52:55], v[144:147], v[178:181], v[52:55]
	v_mfma_f32_16x16x32_bf16 v[52:55], v[148:151], v[182:185], v[52:55]
	v_mfma_f32_16x16x32_bf16 v[48:51], v[156:159], v[182:185], v[48:51]
	v_mfma_f32_16x16x32_bf16 v[48:51], v[152:155], v[178:181], v[48:51]
	v_mfma_f32_16x16x32_bf16 v[32:35], v[152:155], v[206:209], v[32:35]
	v_mfma_f32_16x16x32_bf16 v[32:35], v[156:159], v[210:213], v[32:35]
	v_mfma_f32_16x16x32_bf16 v[36:39], v[148:151], v[210:213], v[36:39]
	v_mfma_f32_16x16x32_bf16 v[36:39], v[144:147], v[206:209], v[36:39]
	v_mfma_f32_16x16x32_bf16 v[40:43], v[92:95], v[206:209], v[40:43]
	v_mfma_f32_16x16x32_bf16 v[40:43], v[96:99], v[210:213], v[40:43]
	v_mfma_f32_16x16x32_bf16 v[44:47], v[84:87], v[210:213], v[44:47]
	v_mfma_f32_16x16x32_bf16 v[44:47], v[76:79], v[206:209], v[44:47]
	s_setprio 0
	s_setprio 1
	v_mfma_f32_16x16x32_bf16 v[28:31], v[76:79], v[214:217], v[28:31]
	v_mfma_f32_16x16x32_bf16 v[28:31], v[84:87], v[218:221], v[28:31]
	v_mfma_f32_16x16x32_bf16 v[24:27], v[96:99], v[218:221], v[24:27]
	v_mfma_f32_16x16x32_bf16 v[24:27], v[92:95], v[214:217], v[24:27]
	v_mfma_f32_16x16x32_bf16 v[20:23], v[144:147], v[214:217], v[20:23]
	v_mfma_f32_16x16x32_bf16 v[20:23], v[148:151], v[218:221], v[20:23]
	v_mfma_f32_16x16x32_bf16 v[16:19], v[156:159], v[218:221], v[16:19]
	v_mfma_f32_16x16x32_bf16 v[16:19], v[152:155], v[214:217], v[16:19]
	v_mfma_f32_16x16x32_bf16 v[0:3], v[152:155], v[222:225], v[0:3]
	v_mfma_f32_16x16x32_bf16 v[0:3], v[156:159], v[226:229], v[0:3]
	v_mfma_f32_16x16x32_bf16 v[4:7], v[148:151], v[226:229], v[4:7]
	v_mfma_f32_16x16x32_bf16 v[4:7], v[144:147], v[222:225], v[4:7]
	v_mfma_f32_16x16x32_bf16 v[8:11], v[92:95], v[222:225], v[8:11]
	v_mfma_f32_16x16x32_bf16 v[8:11], v[96:99], v[226:229], v[8:11]
	s_setprio 3
	s_barrier
	v_mfma_f32_16x16x32_bf16 v[12:15], v[84:87], v[226:229], v[12:15]
	v_mfma_f32_16x16x32_bf16 v[12:15], v[76:79], v[222:225], v[12:15]
	s_setprio 0
	s_cmpk_gt_u32 s77, 0x55
	s_cbranch_scc0 .LBB0_482
	s_and_b64 vcc, exec, s[22:23]
	s_cbranch_vccz .LBB0_485
	s_barrier

; #define PG8_STAGE(bufoff, gbase, voff) do { _Pragma("unroll") for (int _i = 0; _i < 2; ++_i) \
;         __builtin_amdgcn_global_load_lds((const unsigned*)((const char*)(gbase) + (voff)[_i]), (PG8_LAS unsigned*)(lds + (bufoff) + ldsw + _i * 8192), 16, 0, 0); } while (0)
; #define PG8_LDA(dst, b, h) do { _Pragma("unroll") for (int m = 0; m < 4; ++m) _Pragma("unroll") for (int k = 0; k < 2; ++k) dst[m][k] = *(const PG8_LAS bf16x8*)(lds + PG8_SA(b, h) + aoff + m * 2048 + k * 1024); } while (0)
; #define PG8_LDB(dst, b, h) do { _Pragma("unroll") for (int n = 0; n < 2; ++n) _Pragma("unroll") for (int k = 0; k < 2; ++k) dst[n][k] = *(const PG8_LAS bf16x8*)(lds + PG8_SB(b, h) + boff + n * 2048 + k * 1024); } while (0)
; #define PG8_MMA(ai, bj, At, Bt) do { __builtin_amdgcn_s_setprio(1); _Pragma("unroll") for (int m = 0; m < 4; ++m) _Pragma("unroll") for (int n = 0; n < 2; ++n) _Pragma("unroll") for (int k = 0; k < 2; ++k) \
;         acc[ai][bj][m][n] = __builtin_amdgcn_mfma_f32_16x16x32_bf16(Bt[n][k], At[m][k], acc[ai][bj][m][n], 0, 0, 0); __builtin_amdgcn_s_setprio(0); } while (0)
; #define PG8_WAIT_V(n) asm volatile("s_waitcnt vmcnt(" #n ")" ::: "memory")
; #define PG8_WAIT_L(n) asm volatile("s_waitcnt lgkmcnt(" #n ")" ::: "memory")
; #define PG8_BAR __builtin_amdgcn_s_barrier()
; template <class Epi, class Sched, bool ALIGN_EPI = false, bool SP2 = false>
; __device__ __forceinline__ void gemm_phase(PG8_LAS unsigned char* lds, const Gemm g, const Sched& S, const Epi& E) {
;     ...
;             const char* a1 = cA + (size_t)(t + 1) * kstep;
;             const char* a2 = last ? nA : cA + (size_t)(t + 2) * kstep; const char* b2 = last ? nB : cB + (size_t)(t + 2) * kstep;
;             const char* a3 = a2 + kstep; const char* b3 = b2 + kstep;
;             if (last && has_next) S.a_ready(nxt);
;             if constexpr (SP2) {
;             PG8_LDB(B0, 0, 0); PG8_LDB(B1, 0, 1); PG8_SCHED; PG8_LDA(At, 0, 0); PG8_STAGE(PG8_SA(1, 1), a1 + hstep, voffA);
;             PG8_WAIT_V(8); PG8_WAIT_L(0); PG8_BAR; PG8_MMA(0, 0, At, B0); PG8_MMA(0, 1, At, B1); PG8_BAR; PG8_SCHED;
;             PG8_LDA(At, 0, 1); PG8_STAGE(PG8_SB(0, 0), b2, voffB); PG8_STAGE(PG8_SB(0, 1), b2 + hstep, voffB); PG8_STAGE(PG8_SA(0, 0), a2, voffA);
;             PG8_WAIT_V(8); PG8_WAIT_L(0); PG8_BAR; PG8_MMA(1, 0, At, B0); PG8_MMA(1, 1, At, B1); PG8_BAR; PG8_SCHED;
.LBB0_536:
	ds_read_b128 v[136:139], v156
	ds_read_b128 v[140:143], v156 offset:1024
	ds_read_b128 v[172:175], v156 offset:2048
	ds_read_b128 v[176:179], v156 offset:3072
	ds_read_b128 v[180:183], v157
	ds_read_b128 v[184:187], v157 offset:1024
	ds_read_b128 v[206:209], v157 offset:2048
	ds_read_b128 v[210:213], v157 offset:3072
	s_add_u32 s28, s66, 0xfff80080
	s_addc_u32 s29, s67, -1
	s_cmp_eq_u32 s79, 28
	s_cselect_b32 s49, s34, s29
	s_cselect_b32 s48, s35, s28
	s_cselect_b32 s29, s23, s78
	s_cselect_b32 s28, s39, s77
	v_lshl_add_u64 v[200:201], s[66:67], 0, v[128:129]
	s_add_i32 m0, s11, 0xc000
	ds_read_b128 v[214:217], v158
	ds_read_b128 v[218:221], v158 offset:1024
	ds_read_b128 v[222:225], v158 offset:2048
	ds_read_b128 v[226:229], v158 offset:3072
	ds_read_b128 v[230:233], v158 offset:4096
	ds_read_b128 v[234:237], v158 offset:5120
	ds_read_b128 v[238:241], v158 offset:6144
	ds_read_b128 v[242:245], v158 offset:7168
	global_load_lds_dwordx4 v[200:201], off
	v_lshl_add_u64 v[200:201], s[66:67], 0, v[130:131]
	s_add_i32 m0, s11, 0xe000
	s_nop 0
	global_load_lds_dwordx4 v[200:201], off
	s_waitcnt vmcnt(8)
	s_waitcnt lgkmcnt(0)
	s_barrier
	s_setprio 1
	s_waitcnt lgkmcnt(0)
	v_mfma_f32_16x16x32_bf16 v[124:127], v[136:139], v[214:217], v[124:127]
	v_mfma_f32_16x16x32_bf16 v[124:127], v[140:143], v[218:221], v[124:127]
	v_mfma_f32_16x16x32_bf16 v[120:123], v[176:179], v[218:221], v[120:123]
	v_mfma_f32_16x16x32_bf16 v[120:123], v[172:175], v[214:217], v[120:123]
	v_mfma_f32_16x16x32_bf16 v[116:119], v[180:183], v[214:217], v[116:119]
	v_mfma_f32_16x16x32_bf16 v[116:119], v[184:187], v[218:221], v[116:119]
	v_mfma_f32_16x16x32_bf16 v[112:115], v[210:213], v[218:221], v[112:115]
	v_mfma_f32_16x16x32_bf16 v[112:115], v[206:209], v[214:217], v[112:115]
	v_mfma_f32_16x16x32_bf16 v[92:95], v[206:209], v[222:225], v[92:95]
	v_mfma_f32_16x16x32_bf16 v[92:95], v[210:213], v[226:229], v[92:95]
	v_mfma_f32_16x16x32_bf16 v[100:103], v[184:187], v[226:229], v[100:103]
	v_mfma_f32_16x16x32_bf16 v[100:103], v[180:183], v[222:225], v[100:103]
	v_mfma_f32_16x16x32_bf16 v[104:107], v[172:175], v[222:225], v[104:107]
	v_mfma_f32_16x16x32_bf16 v[104:107], v[176:179], v[226:229], v[104:107]
	v_mfma_f32_16x16x32_bf16 v[108:111], v[140:143], v[226:229], v[108:111]
	v_mfma_f32_16x16x32_bf16 v[108:111], v[136:139], v[222:225], v[108:111]
	s_setprio 0
	s_setprio 1
	v_mfma_f32_16x16x32_bf16 v[96:99], v[136:139], v[230:233], v[96:99]
	v_mfma_f32_16x16x32_bf16 v[96:99], v[140:143], v[234:237], v[96:99]
	v_mfma_f32_16x16x32_bf16 v[88:91], v[176:179], v[234:237], v[88:91]
	v_mfma_f32_16x16x32_bf16 v[88:91], v[172:175], v[230:233], v[88:91]
	v_mfma_f32_16x16x32_bf16 v[84:87], v[180:183], v[230:233], v[84:87]
	v_mfma_f32_16x16x32_bf16 v[84:87], v[184:187], v[234:237], v[84:87]
	v_mfma_f32_16x16x32_bf16 v[76:79], v[210:213], v[234:237], v[76:79]
	v_mfma_f32_16x16x32_bf16 v[76:79], v[206:209], v[230:233], v[76:79]
	v_mfma_f32_16x16x32_bf16 v[64:67], v[206:209], v[238:241], v[64:67]
	v_mfma_f32_16x16x32_bf16 v[64:67], v[210:213], v[242:245], v[64:67]
	v_mfma_f32_16x16x32_bf16 v[68:71], v[184:187], v[242:245], v[68:71]
	v_mfma_f32_16x16x32_bf16 v[68:71], v[180:183], v[238:241], v[68:71]
	v_mfma_f32_16x16x32_bf16 v[72:75], v[172:175], v[238:241], v[72:75]
	v_mfma_f32_16x16x32_bf16 v[72:75], v[176:179], v[242:245], v[72:75]
	s_setprio 3
	s_barrier
	v_mfma_f32_16x16x32_bf16 v[80:83], v[140:143], v[242:245], v[80:83]
	v_mfma_f32_16x16x32_bf16 v[80:83], v[136:139], v[238:241], v[80:83]
	s_setprio 0
	s_add_i32 s44, s72, s41
	v_lshl_add_u64 v[200:201], s[28:29], 0, v[166:167]
	s_mov_b32 m0, s44
	ds_read_b128 v[214:217], v158 offset:16384
	ds_read_b128 v[218:221], v158 offset:17408
	ds_read_b128 v[222:225], v158 offset:18432
	ds_read_b128 v[226:229], v158 offset:19456
	ds_read_b128 v[230:233], v158 offset:20480
	ds_read_b128 v[234:237], v158 offset:21504
	ds_read_b128 v[238:241], v158 offset:22528
	ds_read_b128 v[242:245], v158 offset:23552
	global_load_lds_dwordx4 v[200:201], off
	s_add_i32 m0, s44, 0x2000
	s_add_u32 s80, s28, 0x80000
	v_lshl_add_u64 v[246:247], s[28:29], 0, v[170:171]
	s_addc_u32 s81, s29, 0
	s_add_i32 s44, s73, s41
	global_load_lds_dwordx4 v[246:247], off
	v_lshl_add_u64 v[248:249], s[80:81], 0, v[166:167]
	s_mov_b32 m0, s44
	v_lshl_add_u64 v[250:251], s[48:49], 0, v[168:169]
	global_load_lds_dwordx4 v[248:249], off
	v_lshl_add_u64 v[248:249], s[80:81], 0, v[170:171]
	s_add_i32 m0, s44, 0x2000
	s_nop 0
	global_load_lds_dwordx4 v[248:249], off
	v_lshl_add_u64 v[248:249], s[48:49], 0, v[164:165]
	s_mov_b32 m0, s11
	s_nop 0
	global_load_lds_dwordx4 v[248:249], off
	s_mov_b32 m0, s57
	s_nop 0
	global_load_lds_dwordx4 v[250:251], off
	s_waitcnt vmcnt(8)
	s_waitcnt lgkmcnt(0)
	s_barrier
; #define PG8_STAGE(bufoff, gbase, voff) do { _Pragma("unroll") for (int _i = 0; _i < 2; ++_i) \
;         __builtin_amdgcn_global_load_lds((const unsigned*)((const char*)(gbase) + (voff)[_i]), (PG8_LAS unsigned*)(lds + (bufoff) + ldsw + _i * 8192), 16, 0, 0); } while (0)
; #define PG8_LDA(dst, b, h) do { _Pragma("unroll") for (int m = 0; m < 4; ++m) _Pragma("unroll") for (int k = 0; k < 2; ++k) dst[m][k] = *(const PG8_LAS bf16x8*)(lds + PG8_SA(b, h) + aoff + m * 2048 + k * 1024); } while (0)
; #define PG8_LDB(dst, b, h) do { _Pragma("unroll") for (int n = 0; n < 2; ++n) _Pragma("unroll") for (int k = 0; k < 2; ++k) dst[n][k] = *(const PG8_LAS bf16x8*)(lds + PG8_SB(b, h) + boff + n * 2048 + k * 1024); } while (0)
; #define PG8_MMA(ai, bj, At, Bt) do { __builtin_amdgcn_s_setprio(1); _Pragma("unroll") for (int m = 0; m < 4; ++m) _Pragma("unroll") for (int n = 0; n < 2; ++n) _Pragma("unroll") for (int k = 0; k < 2; ++k) \
;         acc[ai][bj][m][n] = __builtin_amdgcn_mfma_f32_16x16x32_bf16(Bt[n][k], At[m][k], acc[ai][bj][m][n], 0, 0, 0); __builtin_amdgcn_s_setprio(0); } while (0)
; #define PG8_WAIT_V(n) asm volatile("s_waitcnt vmcnt(" #n ")" ::: "memory")
; #define PG8_WAIT_L(n) asm volatile("s_waitcnt lgkmcnt(" #n ")" ::: "memory")
; #define PG8_BAR __builtin_amdgcn_s_barrier()
; #define PG8_SCHED __builtin_amdgcn_sched_barrier(0)
; template <class Epi, class Sched, bool ALIGN_EPI = false, bool SP2 = false>
; __device__ __forceinline__ void gemm_phase(PG8_LAS unsigned char* lds, const Gemm g, const Sched& S, const Epi& E) {
;     ...
;             PG8_WAIT_V(8); PG8_WAIT_L(0); PG8_BAR; PG8_MMA(1, 0, At, B0); PG8_MMA(1, 1, At, B1); PG8_BAR; PG8_SCHED;
;             PG8_LDB(B0, 1, 0); PG8_LDB(B1, 1, 1); PG8_SCHED; PG8_LDA(At, 1, 0); PG8_STAGE(PG8_SA(0, 1), a2 + hstep, voffA);
;             PG8_WAIT_V(8); PG8_WAIT_L(0); PG8_BAR; PG8_MMA(0, 0, At, B0); PG8_MMA(0, 1, At, B1); PG8_BAR; PG8_SCHED;
	s_setprio 1
	s_waitcnt lgkmcnt(0)
	v_mfma_f32_16x16x32_bf16 v[60:63], v[136:139], v[214:217], v[60:63]
	v_mfma_f32_16x16x32_bf16 v[60:63], v[140:143], v[218:221], v[60:63]
	v_mfma_f32_16x16x32_bf16 v[56:59], v[176:179], v[218:221], v[56:59]
	v_mfma_f32_16x16x32_bf16 v[56:59], v[172:175], v[214:217], v[56:59]
	v_mfma_f32_16x16x32_bf16 v[52:55], v[180:183], v[214:217], v[52:55]
	v_mfma_f32_16x16x32_bf16 v[52:55], v[184:187], v[218:221], v[52:55]
	v_mfma_f32_16x16x32_bf16 v[44:47], v[210:213], v[218:221], v[44:47]
	v_mfma_f32_16x16x32_bf16 v[44:47], v[206:209], v[214:217], v[44:47]
	v_mfma_f32_16x16x32_bf16 v[28:31], v[206:209], v[222:225], v[28:31]
	v_mfma_f32_16x16x32_bf16 v[28:31], v[210:213], v[226:229], v[28:31]
	v_mfma_f32_16x16x32_bf16 v[36:39], v[184:187], v[226:229], v[36:39]
	v_mfma_f32_16x16x32_bf16 v[36:39], v[180:183], v[222:225], v[36:39]
	v_mfma_f32_16x16x32_bf16 v[40:43], v[172:175], v[222:225], v[40:43]
	v_mfma_f32_16x16x32_bf16 v[40:43], v[176:179], v[226:229], v[40:43]
	v_mfma_f32_16x16x32_bf16 v[48:51], v[140:143], v[226:229], v[48:51]
	v_mfma_f32_16x16x32_bf16 v[48:51], v[136:139], v[222:225], v[48:51]
	s_setprio 0
	s_setprio 1
	v_mfma_f32_16x16x32_bf16 v[32:35], v[136:139], v[230:233], v[32:35]
	v_mfma_f32_16x16x32_bf16 v[32:35], v[140:143], v[234:237], v[32:35]
	v_mfma_f32_16x16x32_bf16 v[24:27], v[176:179], v[234:237], v[24:27]
	v_mfma_f32_16x16x32_bf16 v[24:27], v[172:175], v[230:233], v[24:27]
	v_mfma_f32_16x16x32_bf16 v[20:23], v[180:183], v[230:233], v[20:23]
	v_mfma_f32_16x16x32_bf16 v[20:23], v[184:187], v[234:237], v[20:23]
	v_mfma_f32_16x16x32_bf16 v[16:19], v[210:213], v[234:237], v[16:19]
	v_mfma_f32_16x16x32_bf16 v[16:19], v[206:209], v[230:233], v[16:19]
	v_mfma_f32_16x16x32_bf16 v[0:3], v[206:209], v[238:241], v[0:3]
	v_mfma_f32_16x16x32_bf16 v[0:3], v[210:213], v[242:245], v[0:3]
	v_mfma_f32_16x16x32_bf16 v[4:7], v[184:187], v[242:245], v[4:7]
	v_mfma_f32_16x16x32_bf16 v[4:7], v[180:183], v[238:241], v[4:7]
	v_mfma_f32_16x16x32_bf16 v[8:11], v[172:175], v[238:241], v[8:11]
	v_mfma_f32_16x16x32_bf16 v[8:11], v[176:179], v[242:245], v[8:11]
	s_setprio 3
	s_barrier
	v_mfma_f32_16x16x32_bf16 v[12:15], v[140:143], v[242:245], v[12:15]
	v_mfma_f32_16x16x32_bf16 v[12:15], v[136:139], v[238:241], v[12:15]
	s_setprio 0
	s_add_i32 s44, 0, 0x18000
	v_add_u32_e32 v144, s44, v146
	s_add_i32 s45, 0, 0x1c000
	ds_read_b128 v[136:139], v144
	ds_read_b128 v[140:143], v144 offset:1024
	ds_read_b128 v[172:175], v144 offset:2048
	ds_read_b128 v[176:179], v144 offset:3072
	v_add_u32_e32 v144, s45, v146
	ds_read_b128 v[180:183], v144
	ds_read_b128 v[184:187], v144 offset:1024
	ds_read_b128 v[206:209], v144 offset:2048
	ds_read_b128 v[210:213], v144 offset:3072
	s_add_u32 s48, s48, 0x80000
	s_addc_u32 s49, s49, 0
	s_mov_b32 m0, s61
	v_lshl_add_u64 v[252:253], s[48:49], 0, v[164:165]
	ds_read_b128 v[214:217], v158 offset:32768
	ds_read_b128 v[218:221], v158 offset:33792
	ds_read_b128 v[222:225], v158 offset:34816
	ds_read_b128 v[226:229], v158 offset:35840
	ds_read_b128 v[230:233], v158 offset:36864
	ds_read_b128 v[234:237], v158 offset:37888
	ds_read_b128 v[238:241], v158 offset:38912
	ds_read_b128 v[242:245], v158 offset:39936
	global_load_lds_dwordx4 v[252:253], off
	v_lshl_add_u64 v[252:253], s[48:49], 0, v[168:169]
	s_mov_b32 m0, s68
	s_nop 0
	global_load_lds_dwordx4 v[252:253], off
	s_waitcnt vmcnt(8)
	s_waitcnt lgkmcnt(0)
	s_barrier
	s_setprio 1
	s_waitcnt lgkmcnt(0)
	v_mfma_f32_16x16x32_bf16 v[124:127], v[136:139], v[214:217], v[124:127]
	v_mfma_f32_16x16x32_bf16 v[124:127], v[140:143], v[218:221], v[124:127]
	v_mfma_f32_16x16x32_bf16 v[120:123], v[176:179], v[218:221], v[120:123]
	v_mfma_f32_16x16x32_bf16 v[120:123], v[172:175], v[214:217], v[120:123]
	v_mfma_f32_16x16x32_bf16 v[116:119], v[180:183], v[214:217], v[116:119]
	v_mfma_f32_16x16x32_bf16 v[116:119], v[184:187], v[218:221], v[116:119]
	v_mfma_f32_16x16x32_bf16 v[112:115], v[210:213], v[218:221], v[112:115]
	v_mfma_f32_16x16x32_bf16 v[112:115], v[206:209], v[214:217], v[112:115]
	v_mfma_f32_16x16x32_bf16 v[92:95], v[206:209], v[222:225], v[92:95]
	v_mfma_f32_16x16x32_bf16 v[92:95], v[210:213], v[226:229], v[92:95]
	v_mfma_f32_16x16x32_bf16 v[100:103], v[184:187], v[226:229], v[100:103]
	v_mfma_f32_16x16x32_bf16 v[100:103], v[180:183], v[222:225], v[100:103]
	v_mfma_f32_16x16x32_bf16 v[104:107], v[172:175], v[222:225], v[104:107]
	v_mfma_f32_16x16x32_bf16 v[104:107], v[176:179], v[226:229], v[104:107]
	v_mfma_f32_16x16x32_bf16 v[108:111], v[140:143], v[226:229], v[108:111]
	v_mfma_f32_16x16x32_bf16 v[108:111], v[136:139], v[222:225], v[108:111]
	s_setprio 0
	s_setprio 1
	v_mfma_f32_16x16x32_bf16 v[96:99], v[136:139], v[230:233], v[96:99]
	v_mfma_f32_16x16x32_bf16 v[96:99], v[140:143], v[234:237], v[96:99]
	v_mfma_f32_16x16x32_bf16 v[88:91], v[176:179], v[234:237], v[88:91]
	v_mfma_f32_16x16x32_bf16 v[88:91], v[172:175], v[230:233], v[88:91]
	v_mfma_f32_16x16x32_bf16 v[84:87], v[180:183], v[230:233], v[84:87]
	v_mfma_f32_16x16x32_bf16 v[84:87], v[184:187], v[234:237], v[84:87]
	v_mfma_f32_16x16x32_bf16 v[76:79], v[210:213], v[234:237], v[76:79]
	v_mfma_f32_16x16x32_bf16 v[76:79], v[206:209], v[230:233], v[76:79]
	v_mfma_f32_16x16x32_bf16 v[64:67], v[206:209], v[238:241], v[64:67]
	v_mfma_f32_16x16x32_bf16 v[64:67], v[210:213], v[242:245], v[64:67]
	v_mfma_f32_16x16x32_bf16 v[68:71], v[184:187], v[242:245], v[68:71]
	v_mfma_f32_16x16x32_bf16 v[68:71], v[180:183], v[238:241], v[68:71]
	v_mfma_f32_16x16x32_bf16 v[72:75], v[172:175], v[238:241], v[72:75]
	v_mfma_f32_16x16x32_bf16 v[72:75], v[176:179], v[242:245], v[72:75]
	s_setprio 3
	s_barrier
; #define PG8_STAGE(bufoff, gbase, voff) do { _Pragma("unroll") for (int _i = 0; _i < 2; ++_i) \
;         __builtin_amdgcn_global_load_lds((const unsigned*)((const char*)(gbase) + (voff)[_i]), (PG8_LAS unsigned*)(lds + (bufoff) + ldsw + _i * 8192), 16, 0, 0); } while (0)
; #define PG8_LDA(dst, b, h) do { _Pragma("unroll") for (int m = 0; m < 4; ++m) _Pragma("unroll") for (int k = 0; k < 2; ++k) dst[m][k] = *(const PG8_LAS bf16x8*)(lds + PG8_SA(b, h) + aoff + m * 2048 + k * 1024); } while (0)
; #define PG8_MMA(ai, bj, At, Bt) do { __builtin_amdgcn_s_setprio(1); _Pragma("unroll") for (int m = 0; m < 4; ++m) _Pragma("unroll") for (int n = 0; n < 2; ++n) _Pragma("unroll") for (int k = 0; k < 2; ++k) \
;         acc[ai][bj][m][n] = __builtin_amdgcn_mfma_f32_16x16x32_bf16(Bt[n][k], At[m][k], acc[ai][bj][m][n], 0, 0, 0); __builtin_amdgcn_s_setprio(0); } while (0)
; #define PG8_WAIT_V(n) asm volatile("s_waitcnt vmcnt(" #n ")" ::: "memory")
; #define PG8_WAIT_L(n) asm volatile("s_waitcnt lgkmcnt(" #n ")" ::: "memory")
; #define PG8_BAR __builtin_amdgcn_s_barrier()
; #define PG8_SCHED __builtin_amdgcn_sched_barrier(0)
; template <class Epi, class Sched, bool ALIGN_EPI = false, bool SP2 = false>
; __device__ __forceinline__ void gemm_phase(PG8_LAS unsigned char* lds, const Gemm g, const Sched& S, const Epi& E) {
;     ...
;         for (int t = 0; t < nt; t += 2) {
;     ...
;             PG8_LDA(At, 1, 1); PG8_STAGE(PG8_SB(1, 0), b3, voffB); PG8_STAGE(PG8_SB(1, 1), b3 + hstep, voffB); PG8_STAGE(PG8_SA(1, 0), a3, voffA);
;             PG8_WAIT_V(8); PG8_WAIT_L(0); PG8_BAR; PG8_MMA(1, 0, At, B0); PG8_MMA(1, 1, At, B1); PG8_BAR; PG8_SCHED;
;     ...
;         if constexpr (ALIGN_EPI) { if (wr == 0) PG8_BAR; }
	v_mfma_f32_16x16x32_bf16 v[80:83], v[140:143], v[242:245], v[80:83]
	v_mfma_f32_16x16x32_bf16 v[80:83], v[136:139], v[238:241], v[80:83]
	s_setprio 0
	s_add_i32 s44, s44, s41
	v_lshl_add_u64 v[200:201], v[200:201], 0, s[18:19]
	s_mov_b32 m0, s44
	ds_read_b128 v[214:217], v158 offset:49152
	ds_read_b128 v[218:221], v158 offset:50176
	ds_read_b128 v[222:225], v158 offset:51200
	ds_read_b128 v[226:229], v158 offset:52224
	ds_read_b128 v[230:233], v158 offset:53248
	ds_read_b128 v[234:237], v158 offset:54272
	ds_read_b128 v[238:241], v158 offset:55296
	ds_read_b128 v[242:245], v158 offset:56320
	global_load_lds_dwordx4 v[200:201], off
	s_add_i32 m0, s44, 0x2000
	s_add_u32 s28, s28, 0x80080
	v_lshl_add_u64 v[200:201], v[246:247], 0, s[18:19]
	s_addc_u32 s29, s29, 0
	s_add_i32 s44, s45, s41
	global_load_lds_dwordx4 v[200:201], off
	v_lshl_add_u64 v[200:201], s[28:29], 0, v[166:167]
	s_mov_b32 m0, s44
	s_nop 0
	global_load_lds_dwordx4 v[200:201], off
	v_lshl_add_u64 v[200:201], s[28:29], 0, v[170:171]
	s_add_i32 m0, s44, 0x2000
	s_nop 0
	global_load_lds_dwordx4 v[200:201], off
	v_lshl_add_u64 v[200:201], v[248:249], 0, s[18:19]
	s_mov_b32 m0, s70
	s_nop 0
	global_load_lds_dwordx4 v[200:201], off
	v_lshl_add_u64 v[200:201], v[250:251], 0, s[18:19]
	s_mov_b32 m0, s71
	s_nop 0
	global_load_lds_dwordx4 v[200:201], off
	s_add_i32 s79, s79, 2
	s_add_u32 s66, s66, 0x100
	s_addc_u32 s67, s67, 0
	s_add_u32 s77, s77, 0x100
	s_addc_u32 s78, s78, 0
	s_waitcnt vmcnt(8)
	s_waitcnt lgkmcnt(0)
	s_barrier
	s_setprio 1
	s_waitcnt lgkmcnt(0)
	v_mfma_f32_16x16x32_bf16 v[60:63], v[136:139], v[214:217], v[60:63]
	v_mfma_f32_16x16x32_bf16 v[60:63], v[140:143], v[218:221], v[60:63]
	v_mfma_f32_16x16x32_bf16 v[56:59], v[176:179], v[218:221], v[56:59]
	v_mfma_f32_16x16x32_bf16 v[56:59], v[172:175], v[214:217], v[56:59]
	v_mfma_f32_16x16x32_bf16 v[52:55], v[180:183], v[214:217], v[52:55]
	v_mfma_f32_16x16x32_bf16 v[52:55], v[184:187], v[218:221], v[52:55]
	v_mfma_f32_16x16x32_bf16 v[44:47], v[210:213], v[218:221], v[44:47]
	v_mfma_f32_16x16x32_bf16 v[44:47], v[206:209], v[214:217], v[44:47]
	v_mfma_f32_16x16x32_bf16 v[28:31], v[206:209], v[222:225], v[28:31]
	v_mfma_f32_16x16x32_bf16 v[28:31], v[210:213], v[226:229], v[28:31]
	v_mfma_f32_16x16x32_bf16 v[36:39], v[184:187], v[226:229], v[36:39]
	v_mfma_f32_16x16x32_bf16 v[36:39], v[180:183], v[222:225], v[36:39]
	v_mfma_f32_16x16x32_bf16 v[40:43], v[172:175], v[222:225], v[40:43]
	v_mfma_f32_16x16x32_bf16 v[40:43], v[176:179], v[226:229], v[40:43]
	v_mfma_f32_16x16x32_bf16 v[48:51], v[140:143], v[226:229], v[48:51]
	v_mfma_f32_16x16x32_bf16 v[48:51], v[136:139], v[222:225], v[48:51]
	s_setprio 0
	s_setprio 1
	v_mfma_f32_16x16x32_bf16 v[32:35], v[136:139], v[230:233], v[32:35]
	v_mfma_f32_16x16x32_bf16 v[32:35], v[140:143], v[234:237], v[32:35]
	v_mfma_f32_16x16x32_bf16 v[24:27], v[176:179], v[234:237], v[24:27]
	v_mfma_f32_16x16x32_bf16 v[24:27], v[172:175], v[230:233], v[24:27]
	v_mfma_f32_16x16x32_bf16 v[20:23], v[180:183], v[230:233], v[20:23]
	v_mfma_f32_16x16x32_bf16 v[20:23], v[184:187], v[234:237], v[20:23]
	v_mfma_f32_16x16x32_bf16 v[16:19], v[210:213], v[234:237], v[16:19]
	v_mfma_f32_16x16x32_bf16 v[16:19], v[206:209], v[230:233], v[16:19]
	v_mfma_f32_16x16x32_bf16 v[0:3], v[206:209], v[238:241], v[0:3]
	v_mfma_f32_16x16x32_bf16 v[0:3], v[210:213], v[242:245], v[0:3]
	v_mfma_f32_16x16x32_bf16 v[4:7], v[184:187], v[242:245], v[4:7]
	v_mfma_f32_16x16x32_bf16 v[4:7], v[180:183], v[238:241], v[4:7]
	v_mfma_f32_16x16x32_bf16 v[8:11], v[172:175], v[238:241], v[8:11]
	v_mfma_f32_16x16x32_bf16 v[8:11], v[176:179], v[242:245], v[8:11]
	s_setprio 3
	s_barrier
	v_mfma_f32_16x16x32_bf16 v[12:15], v[140:143], v[242:245], v[12:15]
	v_mfma_f32_16x16x32_bf16 v[12:15], v[136:139], v[238:241], v[12:15]
	s_setprio 0
	s_cmp_gt_u32 s79, 29
	s_cbranch_scc0 .LBB0_536
	s_and_b64 vcc, exec, s[20:21]
	s_cbranch_vccz .LBB0_539
	s_barrier

; #define PG8_STAGE(bufoff, gbase, voff) do { _Pragma("unroll") for (int _i = 0; _i < 2; ++_i) \
;         __builtin_amdgcn_global_load_lds((const unsigned*)((const char*)(gbase) + (voff)[_i]), (PG8_LAS unsigned*)(lds + (bufoff) + ldsw + _i * 8192), 16, 0, 0); } while (0)
; #define PG8_LDA(dst, b, h) do { _Pragma("unroll") for (int m = 0; m < 4; ++m) _Pragma("unroll") for (int k = 0; k < 2; ++k) dst[m][k] = *(const PG8_LAS bf16x8*)(lds + PG8_SA(b, h) + aoff + m * 2048 + k * 1024); } while (0)
; #define PG8_LDB(dst, b, h) do { _Pragma("unroll") for (int n = 0; n < 2; ++n) _Pragma("unroll") for (int k = 0; k < 2; ++k) dst[n][k] = *(const PG8_LAS bf16x8*)(lds + PG8_SB(b, h) + boff + n * 2048 + k * 1024); } while (0)
; #define PG8_MMA(ai, bj, At, Bt) do { __builtin_amdgcn_s_setprio(1); _Pragma("unroll") for (int m = 0; m < 4; ++m) _Pragma("unroll") for (int n = 0; n < 2; ++n) _Pragma("unroll") for (int k = 0; k < 2; ++k) \
;         acc[ai][bj][m][n] = __builtin_amdgcn_mfma_f32_16x16x32_bf16(Bt[n][k], At[m][k], acc[ai][bj][m][n], 0, 0, 0); __builtin_amdgcn_s_setprio(0); } while (0)
; #define PG8_WAIT_V(n) asm volatile("s_waitcnt vmcnt(" #n ")" ::: "memory")
; #define PG8_WAIT_L(n) asm volatile("s_waitcnt lgkmcnt(" #n ")" ::: "memory")
; #define PG8_BAR __builtin_amdgcn_s_barrier()
; template <class Epi, class Sched, bool ALIGN_EPI = false, bool SP2 = false>
; __device__ __forceinline__ void gemm_phase(PG8_LAS unsigned char* lds, const Gemm g, const Sched& S, const Epi& E) {
;     ...
;             const char* a1 = cA + (size_t)(t + 1) * kstep;
;             const char* a2 = last ? nA : cA + (size_t)(t + 2) * kstep; const char* b2 = last ? nB : cB + (size_t)(t + 2) * kstep;
;             const char* a3 = a2 + kstep; const char* b3 = b2 + kstep;
;             if (last && has_next) S.a_ready(nxt);
;             if constexpr (SP2) {
;             PG8_LDB(B0, 0, 0); PG8_LDB(B1, 0, 1); PG8_SCHED; PG8_LDA(At, 0, 0); PG8_STAGE(PG8_SA(1, 1), a1 + hstep, voffA);
;             PG8_WAIT_V(8); PG8_WAIT_L(0); PG8_BAR; PG8_MMA(0, 0, At, B0); PG8_MMA(0, 1, At, B1); PG8_BAR; PG8_SCHED;
;             PG8_LDA(At, 0, 1); PG8_STAGE(PG8_SB(0, 0), b2, voffB); PG8_STAGE(PG8_SB(0, 1), b2 + hstep, voffB); PG8_STAGE(PG8_SA(0, 0), a2, voffA);
;             PG8_WAIT_V(8); PG8_WAIT_L(0); PG8_BAR; PG8_MMA(1, 0, At, B0); PG8_MMA(1, 1, At, B1); PG8_BAR; PG8_SCHED;
.LBB0_602:
	ds_read_b128 v[76:79], v171
	ds_read_b128 v[84:87], v171 offset:1024
	ds_read_b128 v[92:95], v171 offset:2048
	ds_read_b128 v[96:99], v171 offset:3072
	ds_read_b128 v[144:147], v186
	ds_read_b128 v[148:151], v186 offset:1024
	ds_read_b128 v[152:155], v186 offset:2048
	ds_read_b128 v[156:159], v186 offset:3072
	s_add_u32 s28, s62, 0xffea0080
	s_addc_u32 s29, s63, -1
	s_cmpk_eq_i32 s77, 0x54
	s_cselect_b32 s49, s39, s29
	s_cselect_b32 s48, s38, s28
	s_cselect_b32 s29, s41, s35
	s_cselect_b32 s28, s40, s34
	v_lshl_add_u64 v[200:201], s[62:63], 0, v[172:173]
	s_add_i32 m0, s61, 0xc000
	ds_read_b128 v[178:181], v187
	ds_read_b128 v[182:185], v187 offset:1024
	ds_read_b128 v[206:209], v187 offset:2048
	ds_read_b128 v[210:213], v187 offset:3072
	ds_read_b128 v[214:217], v187 offset:4096
	ds_read_b128 v[218:221], v187 offset:5120
	ds_read_b128 v[222:225], v187 offset:6144
	ds_read_b128 v[226:229], v187 offset:7168
	global_load_lds_dwordx4 v[200:201], off
	v_lshl_add_u64 v[200:201], s[62:63], 0, v[174:175]
	s_add_i32 m0, s61, 0xe000
	s_nop 0
	global_load_lds_dwordx4 v[200:201], off
	s_waitcnt vmcnt(8)
	s_waitcnt lgkmcnt(0)
	s_barrier
	s_setprio 1
	s_waitcnt lgkmcnt(0)
	v_mfma_f32_16x16x32_bf16 v[140:143], v[76:79], v[178:181], v[140:143]
	v_mfma_f32_16x16x32_bf16 v[140:143], v[84:87], v[182:185], v[140:143]
	v_mfma_f32_16x16x32_bf16 v[136:139], v[96:99], v[182:185], v[136:139]
	v_mfma_f32_16x16x32_bf16 v[136:139], v[92:95], v[178:181], v[136:139]
	v_mfma_f32_16x16x32_bf16 v[132:135], v[144:147], v[178:181], v[132:135]
	v_mfma_f32_16x16x32_bf16 v[132:135], v[148:151], v[182:185], v[132:135]
	v_mfma_f32_16x16x32_bf16 v[128:131], v[156:159], v[182:185], v[128:131]
	v_mfma_f32_16x16x32_bf16 v[128:131], v[152:155], v[178:181], v[128:131]
	v_mfma_f32_16x16x32_bf16 v[112:115], v[152:155], v[206:209], v[112:115]
	v_mfma_f32_16x16x32_bf16 v[112:115], v[156:159], v[210:213], v[112:115]
	v_mfma_f32_16x16x32_bf16 v[116:119], v[148:151], v[210:213], v[116:119]
	v_mfma_f32_16x16x32_bf16 v[116:119], v[144:147], v[206:209], v[116:119]
	v_mfma_f32_16x16x32_bf16 v[120:123], v[92:95], v[206:209], v[120:123]
	v_mfma_f32_16x16x32_bf16 v[120:123], v[96:99], v[210:213], v[120:123]
	v_mfma_f32_16x16x32_bf16 v[124:127], v[84:87], v[210:213], v[124:127]
	v_mfma_f32_16x16x32_bf16 v[124:127], v[76:79], v[206:209], v[124:127]
	s_setprio 0
	s_setprio 1
	v_mfma_f32_16x16x32_bf16 v[108:111], v[76:79], v[214:217], v[108:111]
	v_mfma_f32_16x16x32_bf16 v[108:111], v[84:87], v[218:221], v[108:111]
	v_mfma_f32_16x16x32_bf16 v[104:107], v[96:99], v[218:221], v[104:107]
	v_mfma_f32_16x16x32_bf16 v[104:107], v[92:95], v[214:217], v[104:107]
	v_mfma_f32_16x16x32_bf16 v[100:103], v[144:147], v[214:217], v[100:103]
	v_mfma_f32_16x16x32_bf16 v[100:103], v[148:151], v[218:221], v[100:103]
	v_mfma_f32_16x16x32_bf16 v[88:91], v[156:159], v[218:221], v[88:91]
	v_mfma_f32_16x16x32_bf16 v[88:91], v[152:155], v[214:217], v[88:91]
	v_mfma_f32_16x16x32_bf16 v[64:67], v[152:155], v[222:225], v[64:67]
	v_mfma_f32_16x16x32_bf16 v[64:67], v[156:159], v[226:229], v[64:67]
	v_mfma_f32_16x16x32_bf16 v[68:71], v[148:151], v[226:229], v[68:71]
	v_mfma_f32_16x16x32_bf16 v[68:71], v[144:147], v[222:225], v[68:71]
	v_mfma_f32_16x16x32_bf16 v[72:75], v[92:95], v[222:225], v[72:75]
	v_mfma_f32_16x16x32_bf16 v[72:75], v[96:99], v[226:229], v[72:75]
	s_setprio 3
	s_barrier
	v_mfma_f32_16x16x32_bf16 v[80:83], v[84:87], v[226:229], v[80:83]
	v_mfma_f32_16x16x32_bf16 v[80:83], v[76:79], v[222:225], v[80:83]
	s_setprio 0
	s_add_i32 s44, s70, s57
	v_lshl_add_u64 v[200:201], s[28:29], 0, v[160:161]
	s_mov_b32 m0, s44
	ds_read_b128 v[178:181], v187 offset:16384
	ds_read_b128 v[182:185], v187 offset:17408
	ds_read_b128 v[206:209], v187 offset:18432
	ds_read_b128 v[210:213], v187 offset:19456
	ds_read_b128 v[214:217], v187 offset:20480
	ds_read_b128 v[218:221], v187 offset:21504
	ds_read_b128 v[222:225], v187 offset:22528
	ds_read_b128 v[226:229], v187 offset:23552
	global_load_lds_dwordx4 v[200:201], off
	s_add_i32 m0, s44, 0x2000
	s_add_u32 s78, s28, 0x160000
	v_lshl_add_u64 v[230:231], s[28:29], 0, v[162:163]
	s_addc_u32 s79, s29, 0
	s_add_i32 s44, s71, s57
	global_load_lds_dwordx4 v[230:231], off
	v_lshl_add_u64 v[232:233], s[78:79], 0, v[160:161]
	s_mov_b32 m0, s44
	v_lshl_add_u64 v[234:235], s[48:49], 0, v[162:163]
	global_load_lds_dwordx4 v[232:233], off
	v_lshl_add_u64 v[232:233], s[78:79], 0, v[162:163]
	s_add_i32 m0, s44, 0x2000
	s_nop 0
	global_load_lds_dwordx4 v[232:233], off
	v_lshl_add_u64 v[232:233], s[48:49], 0, v[160:161]
	s_mov_b32 m0, s61
	s_nop 0
	global_load_lds_dwordx4 v[232:233], off
	s_mov_b32 m0, s64
	s_nop 0
	global_load_lds_dwordx4 v[234:235], off
	s_waitcnt vmcnt(8)
	s_waitcnt lgkmcnt(0)
	s_barrier
; #define PG8_STAGE(bufoff, gbase, voff) do { _Pragma("unroll") for (int _i = 0; _i < 2; ++_i) \
;         __builtin_amdgcn_global_load_lds((const unsigned*)((const char*)(gbase) + (voff)[_i]), (PG8_LAS unsigned*)(lds + (bufoff) + ldsw + _i * 8192), 16, 0, 0); } while (0)
; #define PG8_LDA(dst, b, h) do { _Pragma("unroll") for (int m = 0; m < 4; ++m) _Pragma("unroll") for (int k = 0; k < 2; ++k) dst[m][k] = *(const PG8_LAS bf16x8*)(lds + PG8_SA(b, h) + aoff + m * 2048 + k * 1024); } while (0)
; #define PG8_LDB(dst, b, h) do { _Pragma("unroll") for (int n = 0; n < 2; ++n) _Pragma("unroll") for (int k = 0; k < 2; ++k) dst[n][k] = *(const PG8_LAS bf16x8*)(lds + PG8_SB(b, h) + boff + n * 2048 + k * 1024); } while (0)
; #define PG8_MMA(ai, bj, At, Bt) do { __builtin_amdgcn_s_setprio(1); _Pragma("unroll") for (int m = 0; m < 4; ++m) _Pragma("unroll") for (int n = 0; n < 2; ++n) _Pragma("unroll") for (int k = 0; k < 2; ++k) \
;         acc[ai][bj][m][n] = __builtin_amdgcn_mfma_f32_16x16x32_bf16(Bt[n][k], At[m][k], acc[ai][bj][m][n], 0, 0, 0); __builtin_amdgcn_s_setprio(0); } while (0)
; #define PG8_WAIT_V(n) asm volatile("s_waitcnt vmcnt(" #n ")" ::: "memory")
; #define PG8_WAIT_L(n) asm volatile("s_waitcnt lgkmcnt(" #n ")" ::: "memory")
; #define PG8_BAR __builtin_amdgcn_s_barrier()
; #define PG8_SCHED __builtin_amdgcn_sched_barrier(0)
; template <class Epi, class Sched, bool ALIGN_EPI = false, bool SP2 = false>
; __device__ __forceinline__ void gemm_phase(PG8_LAS unsigned char* lds, const Gemm g, const Sched& S, const Epi& E) {
;     ...
;             PG8_WAIT_V(8); PG8_WAIT_L(0); PG8_BAR; PG8_MMA(1, 0, At, B0); PG8_MMA(1, 1, At, B1); PG8_BAR; PG8_SCHED;
;             PG8_LDB(B0, 1, 0); PG8_LDB(B1, 1, 1); PG8_SCHED; PG8_LDA(At, 1, 0); PG8_STAGE(PG8_SA(0, 1), a2 + hstep, voffA);
;             PG8_WAIT_V(8); PG8_WAIT_L(0); PG8_BAR; PG8_MMA(0, 0, At, B0); PG8_MMA(0, 1, At, B1); PG8_BAR; PG8_SCHED;
	s_setprio 1
	s_waitcnt lgkmcnt(0)
	v_mfma_f32_16x16x32_bf16 v[60:63], v[76:79], v[178:181], v[60:63]
	v_mfma_f32_16x16x32_bf16 v[60:63], v[84:87], v[182:185], v[60:63]
	v_mfma_f32_16x16x32_bf16 v[56:59], v[96:99], v[182:185], v[56:59]
	v_mfma_f32_16x16x32_bf16 v[56:59], v[92:95], v[178:181], v[56:59]
	v_mfma_f32_16x16x32_bf16 v[52:55], v[144:147], v[178:181], v[52:55]
	v_mfma_f32_16x16x32_bf16 v[52:55], v[148:151], v[182:185], v[52:55]
	v_mfma_f32_16x16x32_bf16 v[48:51], v[156:159], v[182:185], v[48:51]
	v_mfma_f32_16x16x32_bf16 v[48:51], v[152:155], v[178:181], v[48:51]
	v_mfma_f32_16x16x32_bf16 v[32:35], v[152:155], v[206:209], v[32:35]
	v_mfma_f32_16x16x32_bf16 v[32:35], v[156:159], v[210:213], v[32:35]
	v_mfma_f32_16x16x32_bf16 v[36:39], v[148:151], v[210:213], v[36:39]
	v_mfma_f32_16x16x32_bf16 v[36:39], v[144:147], v[206:209], v[36:39]
	v_mfma_f32_16x16x32_bf16 v[40:43], v[92:95], v[206:209], v[40:43]
	v_mfma_f32_16x16x32_bf16 v[40:43], v[96:99], v[210:213], v[40:43]
	v_mfma_f32_16x16x32_bf16 v[44:47], v[84:87], v[210:213], v[44:47]
	v_mfma_f32_16x16x32_bf16 v[44:47], v[76:79], v[206:209], v[44:47]
	s_setprio 0
	s_setprio 1
	v_mfma_f32_16x16x32_bf16 v[28:31], v[76:79], v[214:217], v[28:31]
	v_mfma_f32_16x16x32_bf16 v[28:31], v[84:87], v[218:221], v[28:31]
	v_mfma_f32_16x16x32_bf16 v[24:27], v[96:99], v[218:221], v[24:27]
	v_mfma_f32_16x16x32_bf16 v[24:27], v[92:95], v[214:217], v[24:27]
	v_mfma_f32_16x16x32_bf16 v[20:23], v[144:147], v[214:217], v[20:23]
	v_mfma_f32_16x16x32_bf16 v[20:23], v[148:151], v[218:221], v[20:23]
	v_mfma_f32_16x16x32_bf16 v[16:19], v[156:159], v[218:221], v[16:19]
	v_mfma_f32_16x16x32_bf16 v[16:19], v[152:155], v[214:217], v[16:19]
	v_mfma_f32_16x16x32_bf16 v[0:3], v[152:155], v[222:225], v[0:3]
	v_mfma_f32_16x16x32_bf16 v[0:3], v[156:159], v[226:229], v[0:3]
	v_mfma_f32_16x16x32_bf16 v[4:7], v[148:151], v[226:229], v[4:7]
	v_mfma_f32_16x16x32_bf16 v[4:7], v[144:147], v[222:225], v[4:7]
	v_mfma_f32_16x16x32_bf16 v[8:11], v[92:95], v[222:225], v[8:11]
	v_mfma_f32_16x16x32_bf16 v[8:11], v[96:99], v[226:229], v[8:11]
	s_setprio 3
	s_barrier
	v_mfma_f32_16x16x32_bf16 v[12:15], v[84:87], v[226:229], v[12:15]
	v_mfma_f32_16x16x32_bf16 v[12:15], v[76:79], v[222:225], v[12:15]
	s_setprio 0
	s_add_i32 s44, 0, 0x18000
	s_add_i32 s45, 0, 0x1c000
	v_add_u32_e32 v96, s44, v167
	v_add_u32_e32 v156, s45, v167
	ds_read_b128 v[76:79], v96
	ds_read_b128 v[84:87], v96 offset:1024
	ds_read_b128 v[92:95], v96 offset:2048
	ds_read_b128 v[96:99], v96 offset:3072
	ds_read_b128 v[144:147], v156
	ds_read_b128 v[148:151], v156 offset:1024
	ds_read_b128 v[152:155], v156 offset:2048
	ds_read_b128 v[156:159], v156 offset:3072
	s_add_u32 s48, s48, 0x160000
	s_addc_u32 s49, s49, 0
	s_mov_b32 m0, s65
	v_lshl_add_u64 v[236:237], s[48:49], 0, v[160:161]
	ds_read_b128 v[178:181], v187 offset:32768
	ds_read_b128 v[182:185], v187 offset:33792
	ds_read_b128 v[206:209], v187 offset:34816
	ds_read_b128 v[210:213], v187 offset:35840
	ds_read_b128 v[214:217], v187 offset:36864
	ds_read_b128 v[218:221], v187 offset:37888
	ds_read_b128 v[222:225], v187 offset:38912
	ds_read_b128 v[226:229], v187 offset:39936
	global_load_lds_dwordx4 v[236:237], off
	v_lshl_add_u64 v[236:237], s[48:49], 0, v[162:163]
	s_mov_b32 m0, s66
	s_nop 0
	global_load_lds_dwordx4 v[236:237], off
	s_waitcnt vmcnt(8)
	s_waitcnt lgkmcnt(0)
	s_barrier
	s_setprio 1
	s_waitcnt lgkmcnt(0)
	v_mfma_f32_16x16x32_bf16 v[140:143], v[76:79], v[178:181], v[140:143]
	v_mfma_f32_16x16x32_bf16 v[140:143], v[84:87], v[182:185], v[140:143]
	v_mfma_f32_16x16x32_bf16 v[136:139], v[96:99], v[182:185], v[136:139]
	v_mfma_f32_16x16x32_bf16 v[136:139], v[92:95], v[178:181], v[136:139]
	v_mfma_f32_16x16x32_bf16 v[132:135], v[144:147], v[178:181], v[132:135]
	v_mfma_f32_16x16x32_bf16 v[132:135], v[148:151], v[182:185], v[132:135]
	v_mfma_f32_16x16x32_bf16 v[128:131], v[156:159], v[182:185], v[128:131]
	v_mfma_f32_16x16x32_bf16 v[128:131], v[152:155], v[178:181], v[128:131]
	v_mfma_f32_16x16x32_bf16 v[112:115], v[152:155], v[206:209], v[112:115]
	v_mfma_f32_16x16x32_bf16 v[112:115], v[156:159], v[210:213], v[112:115]
	v_mfma_f32_16x16x32_bf16 v[116:119], v[148:151], v[210:213], v[116:119]
	v_mfma_f32_16x16x32_bf16 v[116:119], v[144:147], v[206:209], v[116:119]
	v_mfma_f32_16x16x32_bf16 v[120:123], v[92:95], v[206:209], v[120:123]
	v_mfma_f32_16x16x32_bf16 v[120:123], v[96:99], v[210:213], v[120:123]
	v_mfma_f32_16x16x32_bf16 v[124:127], v[84:87], v[210:213], v[124:127]
	v_mfma_f32_16x16x32_bf16 v[124:127], v[76:79], v[206:209], v[124:127]
	s_setprio 0
	s_setprio 1
	v_mfma_f32_16x16x32_bf16 v[108:111], v[76:79], v[214:217], v[108:111]
	v_mfma_f32_16x16x32_bf16 v[108:111], v[84:87], v[218:221], v[108:111]
	v_mfma_f32_16x16x32_bf16 v[104:107], v[96:99], v[218:221], v[104:107]
	v_mfma_f32_16x16x32_bf16 v[104:107], v[92:95], v[214:217], v[104:107]
	v_mfma_f32_16x16x32_bf16 v[100:103], v[144:147], v[214:217], v[100:103]
	v_mfma_f32_16x16x32_bf16 v[100:103], v[148:151], v[218:221], v[100:103]
	v_mfma_f32_16x16x32_bf16 v[88:91], v[156:159], v[218:221], v[88:91]
	v_mfma_f32_16x16x32_bf16 v[88:91], v[152:155], v[214:217], v[88:91]
	v_mfma_f32_16x16x32_bf16 v[64:67], v[152:155], v[222:225], v[64:67]
	v_mfma_f32_16x16x32_bf16 v[64:67], v[156:159], v[226:229], v[64:67]
	v_mfma_f32_16x16x32_bf16 v[68:71], v[148:151], v[226:229], v[68:71]
	v_mfma_f32_16x16x32_bf16 v[68:71], v[144:147], v[222:225], v[68:71]
	v_mfma_f32_16x16x32_bf16 v[72:75], v[92:95], v[222:225], v[72:75]
	v_mfma_f32_16x16x32_bf16 v[72:75], v[96:99], v[226:229], v[72:75]
	s_setprio 3
	s_barrier
; #define PG8_STAGE(bufoff, gbase, voff) do { _Pragma("unroll") for (int _i = 0; _i < 2; ++_i) \
;         __builtin_amdgcn_global_load_lds((const unsigned*)((const char*)(gbase) + (voff)[_i]), (PG8_LAS unsigned*)(lds + (bufoff) + ldsw + _i * 8192), 16, 0, 0); } while (0)
; #define PG8_LDA(dst, b, h) do { _Pragma("unroll") for (int m = 0; m < 4; ++m) _Pragma("unroll") for (int k = 0; k < 2; ++k) dst[m][k] = *(const PG8_LAS bf16x8*)(lds + PG8_SA(b, h) + aoff + m * 2048 + k * 1024); } while (0)
; #define PG8_MMA(ai, bj, At, Bt) do { __builtin_amdgcn_s_setprio(1); _Pragma("unroll") for (int m = 0; m < 4; ++m) _Pragma("unroll") for (int n = 0; n < 2; ++n) _Pragma("unroll") for (int k = 0; k < 2; ++k) \
;         acc[ai][bj][m][n] = __builtin_amdgcn_mfma_f32_16x16x32_bf16(Bt[n][k], At[m][k], acc[ai][bj][m][n], 0, 0, 0); __builtin_amdgcn_s_setprio(0); } while (0)
; #define PG8_WAIT_V(n) asm volatile("s_waitcnt vmcnt(" #n ")" ::: "memory")
; #define PG8_WAIT_L(n) asm volatile("s_waitcnt lgkmcnt(" #n ")" ::: "memory")
; #define PG8_BAR __builtin_amdgcn_s_barrier()
; #define PG8_SCHED __builtin_amdgcn_sched_barrier(0)
; template <class Epi, class Sched, bool ALIGN_EPI = false, bool SP2 = false>
; __device__ __forceinline__ void gemm_phase(PG8_LAS unsigned char* lds, const Gemm g, const Sched& S, const Epi& E) {
;     ...
;         for (int t = 0; t < nt; t += 2) {
;     ...
;             PG8_LDA(At, 1, 1); PG8_STAGE(PG8_SB(1, 0), b3, voffB); PG8_STAGE(PG8_SB(1, 1), b3 + hstep, voffB); PG8_STAGE(PG8_SA(1, 0), a3, voffA);
;             PG8_WAIT_V(8); PG8_WAIT_L(0); PG8_BAR; PG8_MMA(1, 0, At, B0); PG8_MMA(1, 1, At, B1); PG8_BAR; PG8_SCHED;
;     ...
;         if constexpr (ALIGN_EPI) { if (wr == 0) PG8_BAR; }
	v_mfma_f32_16x16x32_bf16 v[80:83], v[84:87], v[226:229], v[80:83]
	v_mfma_f32_16x16x32_bf16 v[80:83], v[76:79], v[222:225], v[80:83]
	s_setprio 0
	s_add_i32 s44, s44, s57
	v_lshl_add_u64 v[200:201], v[200:201], 0, s[20:21]
	s_mov_b32 m0, s44
	ds_read_b128 v[178:181], v187 offset:49152
	ds_read_b128 v[182:185], v187 offset:50176
	ds_read_b128 v[206:209], v187 offset:51200
	ds_read_b128 v[210:213], v187 offset:52224
	ds_read_b128 v[214:217], v187 offset:53248
	ds_read_b128 v[218:221], v187 offset:54272
	ds_read_b128 v[222:225], v187 offset:55296
	ds_read_b128 v[226:229], v187 offset:56320
	global_load_lds_dwordx4 v[200:201], off
	s_add_i32 m0, s44, 0x2000
	s_add_u32 s28, s28, 0x160080
	v_lshl_add_u64 v[200:201], v[230:231], 0, s[20:21]
	s_addc_u32 s29, s29, 0
	s_add_i32 s44, s45, s57
	global_load_lds_dwordx4 v[200:201], off
	v_lshl_add_u64 v[200:201], s[28:29], 0, v[160:161]
	s_mov_b32 m0, s44
	s_nop 0
	global_load_lds_dwordx4 v[200:201], off
	v_lshl_add_u64 v[200:201], s[28:29], 0, v[162:163]
	s_add_i32 m0, s44, 0x2000
	s_nop 0
	global_load_lds_dwordx4 v[200:201], off
	v_lshl_add_u64 v[200:201], v[232:233], 0, s[20:21]
	s_mov_b32 m0, s67
	s_nop 0
	global_load_lds_dwordx4 v[200:201], off
	v_lshl_add_u64 v[200:201], v[234:235], 0, s[20:21]
	s_mov_b32 m0, s68
	s_nop 0
	global_load_lds_dwordx4 v[200:201], off
	s_add_i32 s77, s77, 2
	s_add_u32 s62, s62, 0x100
	s_addc_u32 s63, s63, 0
	s_add_u32 s34, s34, 0x100
	s_addc_u32 s35, s35, 0
	s_waitcnt vmcnt(8)
	s_waitcnt lgkmcnt(0)
	s_barrier
	s_setprio 1
	s_waitcnt lgkmcnt(0)
	v_mfma_f32_16x16x32_bf16 v[60:63], v[76:79], v[178:181], v[60:63]
	v_mfma_f32_16x16x32_bf16 v[60:63], v[84:87], v[182:185], v[60:63]
	v_mfma_f32_16x16x32_bf16 v[56:59], v[96:99], v[182:185], v[56:59]
	v_mfma_f32_16x16x32_bf16 v[56:59], v[92:95], v[178:181], v[56:59]
	v_mfma_f32_16x16x32_bf16 v[52:55], v[144:147], v[178:181], v[52:55]
	v_mfma_f32_16x16x32_bf16 v[52:55], v[148:151], v[182:185], v[52:55]
	v_mfma_f32_16x16x32_bf16 v[48:51], v[156:159], v[182:185], v[48:51]
	v_mfma_f32_16x16x32_bf16 v[48:51], v[152:155], v[178:181], v[48:51]
	v_mfma_f32_16x16x32_bf16 v[32:35], v[152:155], v[206:209], v[32:35]
	v_mfma_f32_16x16x32_bf16 v[32:35], v[156:159], v[210:213], v[32:35]
	v_mfma_f32_16x16x32_bf16 v[36:39], v[148:151], v[210:213], v[36:39]
	v_mfma_f32_16x16x32_bf16 v[36:39], v[144:147], v[206:209], v[36:39]
	v_mfma_f32_16x16x32_bf16 v[40:43], v[92:95], v[206:209], v[40:43]
	v_mfma_f32_16x16x32_bf16 v[40:43], v[96:99], v[210:213], v[40:43]
	v_mfma_f32_16x16x32_bf16 v[44:47], v[84:87], v[210:213], v[44:47]
	v_mfma_f32_16x16x32_bf16 v[44:47], v[76:79], v[206:209], v[44:47]
	s_setprio 0
	s_setprio 1
	v_mfma_f32_16x16x32_bf16 v[28:31], v[76:79], v[214:217], v[28:31]
	v_mfma_f32_16x16x32_bf16 v[28:31], v[84:87], v[218:221], v[28:31]
	v_mfma_f32_16x16x32_bf16 v[24:27], v[96:99], v[218:221], v[24:27]
	v_mfma_f32_16x16x32_bf16 v[24:27], v[92:95], v[214:217], v[24:27]
	v_mfma_f32_16x16x32_bf16 v[20:23], v[144:147], v[214:217], v[20:23]
	v_mfma_f32_16x16x32_bf16 v[20:23], v[148:151], v[218:221], v[20:23]
	v_mfma_f32_16x16x32_bf16 v[16:19], v[156:159], v[218:221], v[16:19]
	v_mfma_f32_16x16x32_bf16 v[16:19], v[152:155], v[214:217], v[16:19]
	v_mfma_f32_16x16x32_bf16 v[0:3], v[152:155], v[222:225], v[0:3]
	v_mfma_f32_16x16x32_bf16 v[0:3], v[156:159], v[226:229], v[0:3]
	v_mfma_f32_16x16x32_bf16 v[4:7], v[148:151], v[226:229], v[4:7]
	v_mfma_f32_16x16x32_bf16 v[4:7], v[144:147], v[222:225], v[4:7]
	v_mfma_f32_16x16x32_bf16 v[8:11], v[92:95], v[222:225], v[8:11]
	v_mfma_f32_16x16x32_bf16 v[8:11], v[96:99], v[226:229], v[8:11]
	s_setprio 3
	s_barrier
	v_mfma_f32_16x16x32_bf16 v[12:15], v[84:87], v[226:229], v[12:15]
	v_mfma_f32_16x16x32_bf16 v[12:15], v[76:79], v[222:225], v[12:15]
	s_setprio 0
	s_cmpk_gt_u32 s77, 0x55
	s_cbranch_scc0 .LBB0_602
	s_and_b64 vcc, exec, s[22:23]
	s_cbranch_vccz .LBB0_605
	s_barrier

; #define PG8_STAGE(bufoff, gbase, voff) do { _Pragma("unroll") for (int _i = 0; _i < 2; ++_i) \
;         __builtin_amdgcn_global_load_lds((const unsigned*)((const char*)(gbase) + (voff)[_i]), (PG8_LAS unsigned*)(lds + (bufoff) + ldsw + _i * 8192), 16, 0, 0); } while (0)
; #define PG8_LDA(dst, b, h) do { _Pragma("unroll") for (int m = 0; m < 4; ++m) _Pragma("unroll") for (int k = 0; k < 2; ++k) dst[m][k] = *(const PG8_LAS bf16x8*)(lds + PG8_SA(b, h) + aoff + m * 2048 + k * 1024); } while (0)
; #define PG8_LDB(dst, b, h) do { _Pragma("unroll") for (int n = 0; n < 2; ++n) _Pragma("unroll") for (int k = 0; k < 2; ++k) dst[n][k] = *(const PG8_LAS bf16x8*)(lds + PG8_SB(b, h) + boff + n * 2048 + k * 1024); } while (0)
; #define PG8_MMA(ai, bj, At, Bt) do { __builtin_amdgcn_s_setprio(1); _Pragma("unroll") for (int m = 0; m < 4; ++m) _Pragma("unroll") for (int n = 0; n < 2; ++n) _Pragma("unroll") for (int k = 0; k < 2; ++k) \
;         acc[ai][bj][m][n] = __builtin_amdgcn_mfma_f32_16x16x32_bf16(Bt[n][k], At[m][k], acc[ai][bj][m][n], 0, 0, 0); __builtin_amdgcn_s_setprio(0); } while (0)
; #define PG8_WAIT_V(n) asm volatile("s_waitcnt vmcnt(" #n ")" ::: "memory")
; #define PG8_WAIT_L(n) asm volatile("s_waitcnt lgkmcnt(" #n ")" ::: "memory")
; #define PG8_BAR __builtin_amdgcn_s_barrier()
; template <class Epi, class Sched, bool ALIGN_EPI = false, bool SP2 = false>
; __device__ __forceinline__ void gemm_phase(PG8_LAS unsigned char* lds, const Gemm g, const Sched& S, const Epi& E) {
;     ...
;             const char* a1 = cA + (size_t)(t + 1) * kstep;
;             const char* a2 = last ? nA : cA + (size_t)(t + 2) * kstep; const char* b2 = last ? nB : cB + (size_t)(t + 2) * kstep;
;             const char* a3 = a2 + kstep; const char* b3 = b2 + kstep;
;             if (last && has_next) S.a_ready(nxt);
;             if constexpr (SP2) {
;             PG8_LDB(B0, 0, 0); PG8_LDB(B1, 0, 1); PG8_SCHED; PG8_LDA(At, 0, 0); PG8_STAGE(PG8_SA(1, 1), a1 + hstep, voffA);
;             PG8_WAIT_V(8); PG8_WAIT_L(0); PG8_BAR; PG8_MMA(0, 0, At, B0); PG8_MMA(0, 1, At, B1); PG8_BAR; PG8_SCHED;
;             PG8_LDA(At, 0, 1); PG8_STAGE(PG8_SB(0, 0), b2, voffB); PG8_STAGE(PG8_SB(0, 1), b2 + hstep, voffB); PG8_STAGE(PG8_SA(0, 0), a2, voffA);
;             PG8_WAIT_V(8); PG8_WAIT_L(0); PG8_BAR; PG8_MMA(1, 0, At, B0); PG8_MMA(1, 1, At, B1); PG8_BAR; PG8_SCHED;
.LBB0_719:
	ds_read_b128 v[88:91], v208
	ds_read_b128 v[96:99], v208 offset:1024
	ds_read_b128 v[136:139], v208 offset:2048
	ds_read_b128 v[140:143], v208 offset:3072
	ds_read_b128 v[144:147], v209
	ds_read_b128 v[148:151], v209 offset:1024
	ds_read_b128 v[152:155], v209 offset:2048
	ds_read_b128 v[156:159], v209 offset:3072
	s_add_u32 s44, s62, 0xfff80080
	s_addc_u32 s45, s63, -1
	s_cmp_eq_u32 s76, 28
	s_cselect_b32 s59, s29, s45
	s_cselect_b32 s58, s34, s44
	s_cselect_b32 s57, s23, s75
	s_cselect_b32 s56, s35, s74
	v_lshl_add_u64 v[200:201], s[62:63], 0, v[172:173]
	s_add_i32 m0, s49, 0xc000
	ds_read_b128 v[178:181], v210
	ds_read_b128 v[182:185], v210 offset:1024
	ds_read_b128 v[186:189], v210 offset:2048
	ds_read_b128 v[212:215], v210 offset:3072
	ds_read_b128 v[216:219], v210 offset:4096
	ds_read_b128 v[220:223], v210 offset:5120
	ds_read_b128 v[224:227], v210 offset:6144
	ds_read_b128 v[228:231], v210 offset:7168
	global_load_lds_dwordx4 v[200:201], off
	v_lshl_add_u64 v[200:201], s[62:63], 0, v[174:175]
	s_add_i32 m0, s49, 0xe000
	s_nop 0
	global_load_lds_dwordx4 v[200:201], off
	s_waitcnt vmcnt(8)
	s_waitcnt lgkmcnt(0)
	s_barrier
	s_setprio 1
	s_waitcnt lgkmcnt(0)
	v_mfma_f32_16x16x32_bf16 v[128:131], v[88:91], v[178:181], v[128:131]
	v_mfma_f32_16x16x32_bf16 v[128:131], v[96:99], v[182:185], v[128:131]
	v_mfma_f32_16x16x32_bf16 v[120:123], v[140:143], v[182:185], v[120:123]
	v_mfma_f32_16x16x32_bf16 v[120:123], v[136:139], v[178:181], v[120:123]
	v_mfma_f32_16x16x32_bf16 v[132:135], v[144:147], v[178:181], v[132:135]
	v_mfma_f32_16x16x32_bf16 v[132:135], v[148:151], v[182:185], v[132:135]
	v_mfma_f32_16x16x32_bf16 v[124:127], v[156:159], v[182:185], v[124:127]
	v_mfma_f32_16x16x32_bf16 v[124:127], v[152:155], v[178:181], v[124:127]
	v_mfma_f32_16x16x32_bf16 v[104:107], v[152:155], v[186:189], v[104:107]
	v_mfma_f32_16x16x32_bf16 v[104:107], v[156:159], v[212:215], v[104:107]
	v_mfma_f32_16x16x32_bf16 v[112:115], v[148:151], v[212:215], v[112:115]
	v_mfma_f32_16x16x32_bf16 v[112:115], v[144:147], v[186:189], v[112:115]
	v_mfma_f32_16x16x32_bf16 v[108:111], v[136:139], v[186:189], v[108:111]
	v_mfma_f32_16x16x32_bf16 v[108:111], v[140:143], v[212:215], v[108:111]
	v_mfma_f32_16x16x32_bf16 v[116:119], v[96:99], v[212:215], v[116:119]
	v_mfma_f32_16x16x32_bf16 v[116:119], v[88:91], v[186:189], v[116:119]
	s_setprio 0
	s_setprio 1
	v_mfma_f32_16x16x32_bf16 v[100:103], v[88:91], v[216:219], v[100:103]
	v_mfma_f32_16x16x32_bf16 v[100:103], v[96:99], v[220:223], v[100:103]
	v_mfma_f32_16x16x32_bf16 v[84:87], v[140:143], v[220:223], v[84:87]
	v_mfma_f32_16x16x32_bf16 v[84:87], v[136:139], v[216:219], v[84:87]
	v_mfma_f32_16x16x32_bf16 v[92:95], v[144:147], v[216:219], v[92:95]
	v_mfma_f32_16x16x32_bf16 v[92:95], v[148:151], v[220:223], v[92:95]
	v_mfma_f32_16x16x32_bf16 v[80:83], v[156:159], v[220:223], v[80:83]
	v_mfma_f32_16x16x32_bf16 v[80:83], v[152:155], v[216:219], v[80:83]
	v_mfma_f32_16x16x32_bf16 v[64:67], v[152:155], v[224:227], v[64:67]
	v_mfma_f32_16x16x32_bf16 v[64:67], v[156:159], v[228:231], v[64:67]
	v_mfma_f32_16x16x32_bf16 v[72:75], v[148:151], v[228:231], v[72:75]
	v_mfma_f32_16x16x32_bf16 v[72:75], v[144:147], v[224:227], v[72:75]
	v_mfma_f32_16x16x32_bf16 v[68:71], v[136:139], v[224:227], v[68:71]
	v_mfma_f32_16x16x32_bf16 v[68:71], v[140:143], v[228:231], v[68:71]
	s_setprio 3
	s_barrier
	v_mfma_f32_16x16x32_bf16 v[76:79], v[96:99], v[228:231], v[76:79]
	v_mfma_f32_16x16x32_bf16 v[76:79], v[88:91], v[224:227], v[76:79]
	s_setprio 0
	s_add_i32 s44, s71, s65
	v_lshl_add_u64 v[200:201], s[56:57], 0, v[164:165]
	s_mov_b32 m0, s44
	ds_read_b128 v[178:181], v210 offset:16384
	ds_read_b128 v[182:185], v210 offset:17408
	ds_read_b128 v[186:189], v210 offset:18432
	ds_read_b128 v[212:215], v210 offset:19456
	ds_read_b128 v[216:219], v210 offset:20480
	ds_read_b128 v[220:223], v210 offset:21504
	ds_read_b128 v[224:227], v210 offset:22528
	ds_read_b128 v[228:231], v210 offset:23552
	global_load_lds_dwordx4 v[200:201], off
	s_add_i32 m0, s44, 0x2000
	s_add_u32 s78, s56, 0x80000
	v_lshl_add_u64 v[232:233], s[56:57], 0, v[168:169]
	s_addc_u32 s79, s57, 0
	s_add_i32 s44, s72, s65
	global_load_lds_dwordx4 v[232:233], off
	v_lshl_add_u64 v[234:235], s[78:79], 0, v[164:165]
	s_mov_b32 m0, s44
	v_lshl_add_u64 v[236:237], s[58:59], 0, v[168:169]
	global_load_lds_dwordx4 v[234:235], off
	v_lshl_add_u64 v[234:235], s[78:79], 0, v[168:169]
	s_add_i32 m0, s44, 0x2000
	s_nop 0
	global_load_lds_dwordx4 v[234:235], off
	v_lshl_add_u64 v[234:235], s[58:59], 0, v[164:165]
	s_mov_b32 m0, s49
	s_nop 0
	global_load_lds_dwordx4 v[234:235], off
	s_mov_b32 m0, s61
	s_nop 0
	global_load_lds_dwordx4 v[236:237], off
	s_waitcnt vmcnt(8)
	s_waitcnt lgkmcnt(0)
	s_barrier
; #define PG8_STAGE(bufoff, gbase, voff) do { _Pragma("unroll") for (int _i = 0; _i < 2; ++_i) \
;         __builtin_amdgcn_global_load_lds((const unsigned*)((const char*)(gbase) + (voff)[_i]), (PG8_LAS unsigned*)(lds + (bufoff) + ldsw + _i * 8192), 16, 0, 0); } while (0)
; #define PG8_LDA(dst, b, h) do { _Pragma("unroll") for (int m = 0; m < 4; ++m) _Pragma("unroll") for (int k = 0; k < 2; ++k) dst[m][k] = *(const PG8_LAS bf16x8*)(lds + PG8_SA(b, h) + aoff + m * 2048 + k * 1024); } while (0)
; #define PG8_LDB(dst, b, h) do { _Pragma("unroll") for (int n = 0; n < 2; ++n) _Pragma("unroll") for (int k = 0; k < 2; ++k) dst[n][k] = *(const PG8_LAS bf16x8*)(lds + PG8_SB(b, h) + boff + n * 2048 + k * 1024); } while (0)
; #define PG8_MMA(ai, bj, At, Bt) do { __builtin_amdgcn_s_setprio(1); _Pragma("unroll") for (int m = 0; m < 4; ++m) _Pragma("unroll") for (int n = 0; n < 2; ++n) _Pragma("unroll") for (int k = 0; k < 2; ++k) \
;         acc[ai][bj][m][n] = __builtin_amdgcn_mfma_f32_16x16x32_bf16(Bt[n][k], At[m][k], acc[ai][bj][m][n], 0, 0, 0); __builtin_amdgcn_s_setprio(0); } while (0)
; #define PG8_WAIT_V(n) asm volatile("s_waitcnt vmcnt(" #n ")" ::: "memory")
; #define PG8_WAIT_L(n) asm volatile("s_waitcnt lgkmcnt(" #n ")" ::: "memory")
; #define PG8_BAR __builtin_amdgcn_s_barrier()
; #define PG8_SCHED __builtin_amdgcn_sched_barrier(0)
; template <class Epi, class Sched, bool ALIGN_EPI = false, bool SP2 = false>
; __device__ __forceinline__ void gemm_phase(PG8_LAS unsigned char* lds, const Gemm g, const Sched& S, const Epi& E) {
;     ...
;             PG8_WAIT_V(8); PG8_WAIT_L(0); PG8_BAR; PG8_MMA(1, 0, At, B0); PG8_MMA(1, 1, At, B1); PG8_BAR; PG8_SCHED;
;             PG8_LDB(B0, 1, 0); PG8_LDB(B1, 1, 1); PG8_SCHED; PG8_LDA(At, 1, 0); PG8_STAGE(PG8_SA(0, 1), a2 + hstep, voffA);
;             PG8_WAIT_V(8); PG8_WAIT_L(0); PG8_BAR; PG8_MMA(0, 0, At, B0); PG8_MMA(0, 1, At, B1); PG8_BAR; PG8_SCHED;
	s_setprio 1
	s_waitcnt lgkmcnt(0)
	v_mfma_f32_16x16x32_bf16 v[56:59], v[88:91], v[178:181], v[56:59]
	v_mfma_f32_16x16x32_bf16 v[56:59], v[96:99], v[182:185], v[56:59]
	v_mfma_f32_16x16x32_bf16 v[48:51], v[140:143], v[182:185], v[48:51]
	v_mfma_f32_16x16x32_bf16 v[48:51], v[136:139], v[178:181], v[48:51]
	v_mfma_f32_16x16x32_bf16 v[60:63], v[144:147], v[178:181], v[60:63]
	v_mfma_f32_16x16x32_bf16 v[60:63], v[148:151], v[182:185], v[60:63]
	v_mfma_f32_16x16x32_bf16 v[52:55], v[156:159], v[182:185], v[52:55]
	v_mfma_f32_16x16x32_bf16 v[52:55], v[152:155], v[178:181], v[52:55]
	v_mfma_f32_16x16x32_bf16 v[32:35], v[152:155], v[186:189], v[32:35]
	v_mfma_f32_16x16x32_bf16 v[32:35], v[156:159], v[212:215], v[32:35]
	v_mfma_f32_16x16x32_bf16 v[40:43], v[148:151], v[212:215], v[40:43]
	v_mfma_f32_16x16x32_bf16 v[40:43], v[144:147], v[186:189], v[40:43]
	v_mfma_f32_16x16x32_bf16 v[36:39], v[136:139], v[186:189], v[36:39]
	v_mfma_f32_16x16x32_bf16 v[36:39], v[140:143], v[212:215], v[36:39]
	v_mfma_f32_16x16x32_bf16 v[44:47], v[96:99], v[212:215], v[44:47]
	v_mfma_f32_16x16x32_bf16 v[44:47], v[88:91], v[186:189], v[44:47]
	s_setprio 0
	s_setprio 1
	v_mfma_f32_16x16x32_bf16 v[28:31], v[88:91], v[216:219], v[28:31]
	v_mfma_f32_16x16x32_bf16 v[28:31], v[96:99], v[220:223], v[28:31]
	v_mfma_f32_16x16x32_bf16 v[20:23], v[140:143], v[220:223], v[20:23]
	v_mfma_f32_16x16x32_bf16 v[20:23], v[136:139], v[216:219], v[20:23]
	v_mfma_f32_16x16x32_bf16 v[24:27], v[144:147], v[216:219], v[24:27]
	v_mfma_f32_16x16x32_bf16 v[24:27], v[148:151], v[220:223], v[24:27]
	v_mfma_f32_16x16x32_bf16 v[16:19], v[156:159], v[220:223], v[16:19]
	v_mfma_f32_16x16x32_bf16 v[16:19], v[152:155], v[216:219], v[16:19]
	v_mfma_f32_16x16x32_bf16 v[0:3], v[152:155], v[224:227], v[0:3]
	v_mfma_f32_16x16x32_bf16 v[0:3], v[156:159], v[228:231], v[0:3]
	v_mfma_f32_16x16x32_bf16 v[8:11], v[148:151], v[228:231], v[8:11]
	v_mfma_f32_16x16x32_bf16 v[8:11], v[144:147], v[224:227], v[8:11]
	v_mfma_f32_16x16x32_bf16 v[4:7], v[136:139], v[224:227], v[4:7]
	v_mfma_f32_16x16x32_bf16 v[4:7], v[140:143], v[228:231], v[4:7]
	s_setprio 3
	s_barrier
	v_mfma_f32_16x16x32_bf16 v[12:15], v[96:99], v[228:231], v[12:15]
	v_mfma_f32_16x16x32_bf16 v[12:15], v[88:91], v[224:227], v[12:15]
	s_setprio 0
	s_add_i32 s44, 0, 0x18000
	s_add_i32 s45, 0, 0x1c000
	v_add_u32_e32 v140, s44, v163
	v_add_u32_e32 v156, s45, v163
	ds_read_b128 v[88:91], v140
	ds_read_b128 v[96:99], v140 offset:1024
	ds_read_b128 v[136:139], v140 offset:2048
	ds_read_b128 v[140:143], v140 offset:3072
	ds_read_b128 v[144:147], v156
	ds_read_b128 v[148:151], v156 offset:1024
	ds_read_b128 v[152:155], v156 offset:2048
	ds_read_b128 v[156:159], v156 offset:3072
	s_add_u32 s58, s58, 0x80000
	s_addc_u32 s59, s59, 0
	s_mov_b32 m0, s66
	v_lshl_add_u64 v[238:239], s[58:59], 0, v[164:165]
	ds_read_b128 v[178:181], v210 offset:32768
	ds_read_b128 v[182:185], v210 offset:33792
	ds_read_b128 v[186:189], v210 offset:34816
	ds_read_b128 v[212:215], v210 offset:35840
	ds_read_b128 v[216:219], v210 offset:36864
	ds_read_b128 v[220:223], v210 offset:37888
	ds_read_b128 v[224:227], v210 offset:38912
	ds_read_b128 v[228:231], v210 offset:39936
	global_load_lds_dwordx4 v[238:239], off
	v_lshl_add_u64 v[238:239], s[58:59], 0, v[168:169]
	s_mov_b32 m0, s67
	s_nop 0
	global_load_lds_dwordx4 v[238:239], off
	s_waitcnt vmcnt(8)
	s_waitcnt lgkmcnt(0)
	s_barrier
	s_setprio 1
	s_waitcnt lgkmcnt(0)
	v_mfma_f32_16x16x32_bf16 v[128:131], v[88:91], v[178:181], v[128:131]
	v_mfma_f32_16x16x32_bf16 v[128:131], v[96:99], v[182:185], v[128:131]
	v_mfma_f32_16x16x32_bf16 v[120:123], v[140:143], v[182:185], v[120:123]
	v_mfma_f32_16x16x32_bf16 v[120:123], v[136:139], v[178:181], v[120:123]
	v_mfma_f32_16x16x32_bf16 v[132:135], v[144:147], v[178:181], v[132:135]
	v_mfma_f32_16x16x32_bf16 v[132:135], v[148:151], v[182:185], v[132:135]
	v_mfma_f32_16x16x32_bf16 v[124:127], v[156:159], v[182:185], v[124:127]
	v_mfma_f32_16x16x32_bf16 v[124:127], v[152:155], v[178:181], v[124:127]
	v_mfma_f32_16x16x32_bf16 v[104:107], v[152:155], v[186:189], v[104:107]
	v_mfma_f32_16x16x32_bf16 v[104:107], v[156:159], v[212:215], v[104:107]
	v_mfma_f32_16x16x32_bf16 v[112:115], v[148:151], v[212:215], v[112:115]
	v_mfma_f32_16x16x32_bf16 v[112:115], v[144:147], v[186:189], v[112:115]
	v_mfma_f32_16x16x32_bf16 v[108:111], v[136:139], v[186:189], v[108:111]
	v_mfma_f32_16x16x32_bf16 v[108:111], v[140:143], v[212:215], v[108:111]
	v_mfma_f32_16x16x32_bf16 v[116:119], v[96:99], v[212:215], v[116:119]
	v_mfma_f32_16x16x32_bf16 v[116:119], v[88:91], v[186:189], v[116:119]
	s_setprio 0
	s_setprio 1
	v_mfma_f32_16x16x32_bf16 v[100:103], v[88:91], v[216:219], v[100:103]
	v_mfma_f32_16x16x32_bf16 v[100:103], v[96:99], v[220:223], v[100:103]
	v_mfma_f32_16x16x32_bf16 v[84:87], v[140:143], v[220:223], v[84:87]
	v_mfma_f32_16x16x32_bf16 v[84:87], v[136:139], v[216:219], v[84:87]
	v_mfma_f32_16x16x32_bf16 v[92:95], v[144:147], v[216:219], v[92:95]
	v_mfma_f32_16x16x32_bf16 v[92:95], v[148:151], v[220:223], v[92:95]
	v_mfma_f32_16x16x32_bf16 v[80:83], v[156:159], v[220:223], v[80:83]
	v_mfma_f32_16x16x32_bf16 v[80:83], v[152:155], v[216:219], v[80:83]
	v_mfma_f32_16x16x32_bf16 v[64:67], v[152:155], v[224:227], v[64:67]
	v_mfma_f32_16x16x32_bf16 v[64:67], v[156:159], v[228:231], v[64:67]
	v_mfma_f32_16x16x32_bf16 v[72:75], v[148:151], v[228:231], v[72:75]
	v_mfma_f32_16x16x32_bf16 v[72:75], v[144:147], v[224:227], v[72:75]
	v_mfma_f32_16x16x32_bf16 v[68:71], v[136:139], v[224:227], v[68:71]
	v_mfma_f32_16x16x32_bf16 v[68:71], v[140:143], v[228:231], v[68:71]
	s_setprio 3
	s_barrier
; #define PG8_STAGE(bufoff, gbase, voff) do { _Pragma("unroll") for (int _i = 0; _i < 2; ++_i) \
;         __builtin_amdgcn_global_load_lds((const unsigned*)((const char*)(gbase) + (voff)[_i]), (PG8_LAS unsigned*)(lds + (bufoff) + ldsw + _i * 8192), 16, 0, 0); } while (0)
; #define PG8_LDA(dst, b, h) do { _Pragma("unroll") for (int m = 0; m < 4; ++m) _Pragma("unroll") for (int k = 0; k < 2; ++k) dst[m][k] = *(const PG8_LAS bf16x8*)(lds + PG8_SA(b, h) + aoff + m * 2048 + k * 1024); } while (0)
; #define PG8_MMA(ai, bj, At, Bt) do { __builtin_amdgcn_s_setprio(1); _Pragma("unroll") for (int m = 0; m < 4; ++m) _Pragma("unroll") for (int n = 0; n < 2; ++n) _Pragma("unroll") for (int k = 0; k < 2; ++k) \
;         acc[ai][bj][m][n] = __builtin_amdgcn_mfma_f32_16x16x32_bf16(Bt[n][k], At[m][k], acc[ai][bj][m][n], 0, 0, 0); __builtin_amdgcn_s_setprio(0); } while (0)
; #define PG8_WAIT_V(n) asm volatile("s_waitcnt vmcnt(" #n ")" ::: "memory")
; #define PG8_WAIT_L(n) asm volatile("s_waitcnt lgkmcnt(" #n ")" ::: "memory")
; #define PG8_BAR __builtin_amdgcn_s_barrier()
; #define PG8_SCHED __builtin_amdgcn_sched_barrier(0)
; template <class Epi, class Sched, bool ALIGN_EPI = false, bool SP2 = false>
; __device__ __forceinline__ void gemm_phase(PG8_LAS unsigned char* lds, const Gemm g, const Sched& S, const Epi& E) {
;     ...
;         for (int t = 0; t < nt; t += 2) {
;     ...
;             PG8_LDA(At, 1, 1); PG8_STAGE(PG8_SB(1, 0), b3, voffB); PG8_STAGE(PG8_SB(1, 1), b3 + hstep, voffB); PG8_STAGE(PG8_SA(1, 0), a3, voffA);
;             PG8_WAIT_V(8); PG8_WAIT_L(0); PG8_BAR; PG8_MMA(1, 0, At, B0); PG8_MMA(1, 1, At, B1); PG8_BAR; PG8_SCHED;
;     ...
;         if constexpr (ALIGN_EPI) { if (wr == 0) PG8_BAR; }
	v_mfma_f32_16x16x32_bf16 v[76:79], v[96:99], v[228:231], v[76:79]
	v_mfma_f32_16x16x32_bf16 v[76:79], v[88:91], v[224:227], v[76:79]
	s_setprio 0
	s_add_i32 s44, s44, s65
	v_lshl_add_u64 v[200:201], v[200:201], 0, s[18:19]
	s_mov_b32 m0, s44
	ds_read_b128 v[178:181], v210 offset:49152
	ds_read_b128 v[182:185], v210 offset:50176
	ds_read_b128 v[186:189], v210 offset:51200
	ds_read_b128 v[212:215], v210 offset:52224
	ds_read_b128 v[216:219], v210 offset:53248
	ds_read_b128 v[220:223], v210 offset:54272
	ds_read_b128 v[224:227], v210 offset:55296
	ds_read_b128 v[228:231], v210 offset:56320
	global_load_lds_dwordx4 v[200:201], off
	s_add_i32 m0, s44, 0x2000
	s_add_u32 s56, s56, 0x80080
	v_lshl_add_u64 v[200:201], v[232:233], 0, s[18:19]
	s_addc_u32 s57, s57, 0
	s_add_i32 s44, s45, s65
	global_load_lds_dwordx4 v[200:201], off
	v_lshl_add_u64 v[200:201], s[56:57], 0, v[164:165]
	s_mov_b32 m0, s44
	s_nop 0
	global_load_lds_dwordx4 v[200:201], off
	v_lshl_add_u64 v[200:201], s[56:57], 0, v[168:169]
	s_add_i32 m0, s44, 0x2000
	s_nop 0
	global_load_lds_dwordx4 v[200:201], off
	v_lshl_add_u64 v[200:201], v[234:235], 0, s[18:19]
	s_mov_b32 m0, s68
	s_nop 0
	global_load_lds_dwordx4 v[200:201], off
	v_lshl_add_u64 v[200:201], v[236:237], 0, s[18:19]
	s_mov_b32 m0, s69
	s_nop 0
	global_load_lds_dwordx4 v[200:201], off
	s_add_i32 s76, s76, 2
	s_add_u32 s62, s62, 0x100
	s_addc_u32 s63, s63, 0
	s_add_u32 s74, s74, 0x100
	s_addc_u32 s75, s75, 0
	s_waitcnt vmcnt(8)
	s_waitcnt lgkmcnt(0)
	s_barrier
	s_setprio 1
	s_waitcnt lgkmcnt(0)
	v_mfma_f32_16x16x32_bf16 v[56:59], v[88:91], v[178:181], v[56:59]
	v_mfma_f32_16x16x32_bf16 v[56:59], v[96:99], v[182:185], v[56:59]
	v_mfma_f32_16x16x32_bf16 v[48:51], v[140:143], v[182:185], v[48:51]
	v_mfma_f32_16x16x32_bf16 v[48:51], v[136:139], v[178:181], v[48:51]
	v_mfma_f32_16x16x32_bf16 v[60:63], v[144:147], v[178:181], v[60:63]
	v_mfma_f32_16x16x32_bf16 v[60:63], v[148:151], v[182:185], v[60:63]
	v_mfma_f32_16x16x32_bf16 v[52:55], v[156:159], v[182:185], v[52:55]
	v_mfma_f32_16x16x32_bf16 v[52:55], v[152:155], v[178:181], v[52:55]
	v_mfma_f32_16x16x32_bf16 v[32:35], v[152:155], v[186:189], v[32:35]
	v_mfma_f32_16x16x32_bf16 v[32:35], v[156:159], v[212:215], v[32:35]
	v_mfma_f32_16x16x32_bf16 v[40:43], v[148:151], v[212:215], v[40:43]
	v_mfma_f32_16x16x32_bf16 v[40:43], v[144:147], v[186:189], v[40:43]
	v_mfma_f32_16x16x32_bf16 v[36:39], v[136:139], v[186:189], v[36:39]
	v_mfma_f32_16x16x32_bf16 v[36:39], v[140:143], v[212:215], v[36:39]
	v_mfma_f32_16x16x32_bf16 v[44:47], v[96:99], v[212:215], v[44:47]
	v_mfma_f32_16x16x32_bf16 v[44:47], v[88:91], v[186:189], v[44:47]
	s_setprio 0
	s_setprio 1
	v_mfma_f32_16x16x32_bf16 v[28:31], v[88:91], v[216:219], v[28:31]
	v_mfma_f32_16x16x32_bf16 v[28:31], v[96:99], v[220:223], v[28:31]
	v_mfma_f32_16x16x32_bf16 v[20:23], v[140:143], v[220:223], v[20:23]
	v_mfma_f32_16x16x32_bf16 v[20:23], v[136:139], v[216:219], v[20:23]
	v_mfma_f32_16x16x32_bf16 v[24:27], v[144:147], v[216:219], v[24:27]
	v_mfma_f32_16x16x32_bf16 v[24:27], v[148:151], v[220:223], v[24:27]
	v_mfma_f32_16x16x32_bf16 v[16:19], v[156:159], v[220:223], v[16:19]
	v_mfma_f32_16x16x32_bf16 v[16:19], v[152:155], v[216:219], v[16:19]
	v_mfma_f32_16x16x32_bf16 v[0:3], v[152:155], v[224:227], v[0:3]
	v_mfma_f32_16x16x32_bf16 v[0:3], v[156:159], v[228:231], v[0:3]
	v_mfma_f32_16x16x32_bf16 v[8:11], v[148:151], v[228:231], v[8:11]
	v_mfma_f32_16x16x32_bf16 v[8:11], v[144:147], v[224:227], v[8:11]
	v_mfma_f32_16x16x32_bf16 v[4:7], v[136:139], v[224:227], v[4:7]
	v_mfma_f32_16x16x32_bf16 v[4:7], v[140:143], v[228:231], v[4:7]
	s_setprio 3
	s_barrier
	v_mfma_f32_16x16x32_bf16 v[12:15], v[96:99], v[228:231], v[12:15]
	v_mfma_f32_16x16x32_bf16 v[12:15], v[88:91], v[224:227], v[12:15]
	s_setprio 0
	s_cmp_gt_u32 s76, 29
	s_cbranch_scc0 .LBB0_719
	s_and_b64 vcc, exec, s[20:21]
	s_cbranch_vccz .LBB0_722
	s_barrier

; #define PG8_STAGE(bufoff, gbase, voff) do { _Pragma("unroll") for (int _i = 0; _i < 2; ++_i) \
;         __builtin_amdgcn_global_load_lds((const unsigned*)((const char*)(gbase) + (voff)[_i]), (PG8_LAS unsigned*)(lds + (bufoff) + ldsw + _i * 8192), 16, 0, 0); } while (0)
; #define PG8_LDA(dst, b, h) do { _Pragma("unroll") for (int m = 0; m < 4; ++m) _Pragma("unroll") for (int k = 0; k < 2; ++k) dst[m][k] = *(const PG8_LAS bf16x8*)(lds + PG8_SA(b, h) + aoff + m * 2048 + k * 1024); } while (0)
; #define PG8_LDB(dst, b, h) do { _Pragma("unroll") for (int n = 0; n < 2; ++n) _Pragma("unroll") for (int k = 0; k < 2; ++k) dst[n][k] = *(const PG8_LAS bf16x8*)(lds + PG8_SB(b, h) + boff + n * 2048 + k * 1024); } while (0)
; #define PG8_MMA(ai, bj, At, Bt) do { __builtin_amdgcn_s_setprio(1); _Pragma("unroll") for (int m = 0; m < 4; ++m) _Pragma("unroll") for (int n = 0; n < 2; ++n) _Pragma("unroll") for (int k = 0; k < 2; ++k) \
;         acc[ai][bj][m][n] = __builtin_amdgcn_mfma_f32_16x16x32_bf16(Bt[n][k], At[m][k], acc[ai][bj][m][n], 0, 0, 0); __builtin_amdgcn_s_setprio(0); } while (0)
; #define PG8_WAIT_V(n) asm volatile("s_waitcnt vmcnt(" #n ")" ::: "memory")
; #define PG8_WAIT_L(n) asm volatile("s_waitcnt lgkmcnt(" #n ")" ::: "memory")
; #define PG8_BAR __builtin_amdgcn_s_barrier()
; template <class Epi, class Sched, bool ALIGN_EPI = false, bool SP2 = false>
; __device__ __forceinline__ void gemm_phase(PG8_LAS unsigned char* lds, const Gemm g, const Sched& S, const Epi& E) {
;     ...
;             const char* a1 = cA + (size_t)(t + 1) * kstep;
;             const char* a2 = last ? nA : cA + (size_t)(t + 2) * kstep; const char* b2 = last ? nB : cB + (size_t)(t + 2) * kstep;
;             const char* a3 = a2 + kstep; const char* b3 = b2 + kstep;
;             if (last && has_next) S.a_ready(nxt);
;             if constexpr (SP2) {
;             PG8_LDB(B0, 0, 0); PG8_LDB(B1, 0, 1); PG8_SCHED; PG8_LDA(At, 0, 0); PG8_STAGE(PG8_SA(1, 1), a1 + hstep, voffA);
;             PG8_WAIT_V(8); PG8_WAIT_L(0); PG8_BAR; PG8_MMA(0, 0, At, B0); PG8_MMA(0, 1, At, B1); PG8_BAR; PG8_SCHED;
;             PG8_LDA(At, 0, 1); PG8_STAGE(PG8_SB(0, 0), b2, voffB); PG8_STAGE(PG8_SB(0, 1), b2 + hstep, voffB); PG8_STAGE(PG8_SA(0, 0), a2, voffA);
;             PG8_WAIT_V(8); PG8_WAIT_L(0); PG8_BAR; PG8_MMA(1, 0, At, B0); PG8_MMA(1, 1, At, B1); PG8_BAR; PG8_SCHED;
.LBB0_774:
	ds_read_b128 v[136:139], v156
	ds_read_b128 v[140:143], v156 offset:1024
	ds_read_b128 v[172:175], v156 offset:2048
	ds_read_b128 v[176:179], v156 offset:3072
	ds_read_b128 v[180:183], v157
	ds_read_b128 v[184:187], v157 offset:1024
	ds_read_b128 v[208:211], v157 offset:2048
	ds_read_b128 v[212:215], v157 offset:3072
	s_add_u32 s42, s40, 0xfff80080
	s_addc_u32 s43, s41, -1
	s_cmp_eq_u32 s71, 28
	s_cselect_b32 s49, s23, s43
	s_cselect_b32 s48, s34, s42
	s_cselect_b32 s43, s21, s70
	s_cselect_b32 s42, s35, s69
	v_lshl_add_u64 v[188:189], s[40:41], 0, v[128:129]
	s_add_i32 m0, s11, 0xc000
	ds_read_b128 v[216:219], v158
	ds_read_b128 v[220:223], v158 offset:1024
	ds_read_b128 v[224:227], v158 offset:2048
	ds_read_b128 v[228:231], v158 offset:3072
	ds_read_b128 v[232:235], v158 offset:4096
	ds_read_b128 v[236:239], v158 offset:5120
	ds_read_b128 v[240:243], v158 offset:6144
	ds_read_b128 v[244:247], v158 offset:7168
	global_load_lds_dwordx4 v[188:189], off
	v_lshl_add_u64 v[188:189], s[40:41], 0, v[130:131]
	s_add_i32 m0, s11, 0xe000
	s_nop 0
	global_load_lds_dwordx4 v[188:189], off
	s_waitcnt vmcnt(8)
	s_waitcnt lgkmcnt(0)
	s_barrier
	s_setprio 1
	s_waitcnt lgkmcnt(0)
	v_mfma_f32_16x16x32_bf16 v[124:127], v[136:139], v[216:219], v[124:127]
	v_mfma_f32_16x16x32_bf16 v[124:127], v[140:143], v[220:223], v[124:127]
	v_mfma_f32_16x16x32_bf16 v[120:123], v[176:179], v[220:223], v[120:123]
	v_mfma_f32_16x16x32_bf16 v[120:123], v[172:175], v[216:219], v[120:123]
	v_mfma_f32_16x16x32_bf16 v[116:119], v[180:183], v[216:219], v[116:119]
	v_mfma_f32_16x16x32_bf16 v[116:119], v[184:187], v[220:223], v[116:119]
	v_mfma_f32_16x16x32_bf16 v[112:115], v[212:215], v[220:223], v[112:115]
	v_mfma_f32_16x16x32_bf16 v[112:115], v[208:211], v[216:219], v[112:115]
	v_mfma_f32_16x16x32_bf16 v[92:95], v[208:211], v[224:227], v[92:95]
	v_mfma_f32_16x16x32_bf16 v[92:95], v[212:215], v[228:231], v[92:95]
	v_mfma_f32_16x16x32_bf16 v[100:103], v[184:187], v[228:231], v[100:103]
	v_mfma_f32_16x16x32_bf16 v[100:103], v[180:183], v[224:227], v[100:103]
	v_mfma_f32_16x16x32_bf16 v[104:107], v[172:175], v[224:227], v[104:107]
	v_mfma_f32_16x16x32_bf16 v[104:107], v[176:179], v[228:231], v[104:107]
	v_mfma_f32_16x16x32_bf16 v[108:111], v[140:143], v[228:231], v[108:111]
	v_mfma_f32_16x16x32_bf16 v[108:111], v[136:139], v[224:227], v[108:111]
	s_setprio 0
	s_setprio 1
	v_mfma_f32_16x16x32_bf16 v[96:99], v[136:139], v[232:235], v[96:99]
	v_mfma_f32_16x16x32_bf16 v[96:99], v[140:143], v[236:239], v[96:99]
	v_mfma_f32_16x16x32_bf16 v[88:91], v[176:179], v[236:239], v[88:91]
	v_mfma_f32_16x16x32_bf16 v[88:91], v[172:175], v[232:235], v[88:91]
	v_mfma_f32_16x16x32_bf16 v[84:87], v[180:183], v[232:235], v[84:87]
	v_mfma_f32_16x16x32_bf16 v[84:87], v[184:187], v[236:239], v[84:87]
	v_mfma_f32_16x16x32_bf16 v[76:79], v[212:215], v[236:239], v[76:79]
	v_mfma_f32_16x16x32_bf16 v[76:79], v[208:211], v[232:235], v[76:79]
	v_mfma_f32_16x16x32_bf16 v[64:67], v[208:211], v[240:243], v[64:67]
	v_mfma_f32_16x16x32_bf16 v[64:67], v[212:215], v[244:247], v[64:67]
	v_mfma_f32_16x16x32_bf16 v[68:71], v[184:187], v[244:247], v[68:71]
	v_mfma_f32_16x16x32_bf16 v[68:71], v[180:183], v[240:243], v[68:71]
	v_mfma_f32_16x16x32_bf16 v[72:75], v[172:175], v[240:243], v[72:75]
	v_mfma_f32_16x16x32_bf16 v[72:75], v[176:179], v[244:247], v[72:75]
	s_setprio 3
	s_barrier
	v_mfma_f32_16x16x32_bf16 v[80:83], v[140:143], v[244:247], v[80:83]
	v_mfma_f32_16x16x32_bf16 v[80:83], v[136:139], v[240:243], v[80:83]
	s_setprio 0
	s_add_i32 s44, s64, s52
	v_lshl_add_u64 v[188:189], s[42:43], 0, v[166:167]
	s_mov_b32 m0, s44
	ds_read_b128 v[216:219], v158 offset:16384
	ds_read_b128 v[220:223], v158 offset:17408
	ds_read_b128 v[224:227], v158 offset:18432
	ds_read_b128 v[228:231], v158 offset:19456
	ds_read_b128 v[232:235], v158 offset:20480
	ds_read_b128 v[236:239], v158 offset:21504
	ds_read_b128 v[240:243], v158 offset:22528
	ds_read_b128 v[244:247], v158 offset:23552
	global_load_lds_dwordx4 v[188:189], off
	s_add_i32 m0, s44, 0x2000
	s_add_u32 s72, s42, 0x80000
	v_lshl_add_u64 v[200:201], s[42:43], 0, v[170:171]
	s_addc_u32 s73, s43, 0
	s_add_i32 s44, s65, s52
	global_load_lds_dwordx4 v[200:201], off
	v_lshl_add_u64 v[248:249], s[72:73], 0, v[166:167]
	s_mov_b32 m0, s44
	v_lshl_add_u64 v[250:251], s[48:49], 0, v[168:169]
	global_load_lds_dwordx4 v[248:249], off
	v_lshl_add_u64 v[248:249], s[72:73], 0, v[170:171]
	s_add_i32 m0, s44, 0x2000
	s_nop 0
	global_load_lds_dwordx4 v[248:249], off
	v_lshl_add_u64 v[248:249], s[48:49], 0, v[164:165]
	s_mov_b32 m0, s11
	s_nop 0
	global_load_lds_dwordx4 v[248:249], off
	s_mov_b32 m0, s58
	s_nop 0
	global_load_lds_dwordx4 v[250:251], off
	s_waitcnt vmcnt(8)
	s_waitcnt lgkmcnt(0)
	s_barrier
; #define PG8_STAGE(bufoff, gbase, voff) do { _Pragma("unroll") for (int _i = 0; _i < 2; ++_i) \
;         __builtin_amdgcn_global_load_lds((const unsigned*)((const char*)(gbase) + (voff)[_i]), (PG8_LAS unsigned*)(lds + (bufoff) + ldsw + _i * 8192), 16, 0, 0); } while (0)
; #define PG8_LDA(dst, b, h) do { _Pragma("unroll") for (int m = 0; m < 4; ++m) _Pragma("unroll") for (int k = 0; k < 2; ++k) dst[m][k] = *(const PG8_LAS bf16x8*)(lds + PG8_SA(b, h) + aoff + m * 2048 + k * 1024); } while (0)
; #define PG8_LDB(dst, b, h) do { _Pragma("unroll") for (int n = 0; n < 2; ++n) _Pragma("unroll") for (int k = 0; k < 2; ++k) dst[n][k] = *(const PG8_LAS bf16x8*)(lds + PG8_SB(b, h) + boff + n * 2048 + k * 1024); } while (0)
; #define PG8_MMA(ai, bj, At, Bt) do { __builtin_amdgcn_s_setprio(1); _Pragma("unroll") for (int m = 0; m < 4; ++m) _Pragma("unroll") for (int n = 0; n < 2; ++n) _Pragma("unroll") for (int k = 0; k < 2; ++k) \
;         acc[ai][bj][m][n] = __builtin_amdgcn_mfma_f32_16x16x32_bf16(Bt[n][k], At[m][k], acc[ai][bj][m][n], 0, 0, 0); __builtin_amdgcn_s_setprio(0); } while (0)
; #define PG8_WAIT_V(n) asm volatile("s_waitcnt vmcnt(" #n ")" ::: "memory")
; #define PG8_WAIT_L(n) asm volatile("s_waitcnt lgkmcnt(" #n ")" ::: "memory")
; #define PG8_BAR __builtin_amdgcn_s_barrier()
; #define PG8_SCHED __builtin_amdgcn_sched_barrier(0)
; template <class Epi, class Sched, bool ALIGN_EPI = false, bool SP2 = false>
; __device__ __forceinline__ void gemm_phase(PG8_LAS unsigned char* lds, const Gemm g, const Sched& S, const Epi& E) {
;     ...
;             PG8_WAIT_V(8); PG8_WAIT_L(0); PG8_BAR; PG8_MMA(1, 0, At, B0); PG8_MMA(1, 1, At, B1); PG8_BAR; PG8_SCHED;
;             PG8_LDB(B0, 1, 0); PG8_LDB(B1, 1, 1); PG8_SCHED; PG8_LDA(At, 1, 0); PG8_STAGE(PG8_SA(0, 1), a2 + hstep, voffA);
;             PG8_WAIT_V(8); PG8_WAIT_L(0); PG8_BAR; PG8_MMA(0, 0, At, B0); PG8_MMA(0, 1, At, B1); PG8_BAR; PG8_SCHED;
	s_setprio 1
	s_waitcnt lgkmcnt(0)
	v_mfma_f32_16x16x32_bf16 v[60:63], v[136:139], v[216:219], v[60:63]
	v_mfma_f32_16x16x32_bf16 v[60:63], v[140:143], v[220:223], v[60:63]
	v_mfma_f32_16x16x32_bf16 v[56:59], v[176:179], v[220:223], v[56:59]
	v_mfma_f32_16x16x32_bf16 v[56:59], v[172:175], v[216:219], v[56:59]
	v_mfma_f32_16x16x32_bf16 v[52:55], v[180:183], v[216:219], v[52:55]
	v_mfma_f32_16x16x32_bf16 v[52:55], v[184:187], v[220:223], v[52:55]
	v_mfma_f32_16x16x32_bf16 v[44:47], v[212:215], v[220:223], v[44:47]
	v_mfma_f32_16x16x32_bf16 v[44:47], v[208:211], v[216:219], v[44:47]
	v_mfma_f32_16x16x32_bf16 v[28:31], v[208:211], v[224:227], v[28:31]
	v_mfma_f32_16x16x32_bf16 v[28:31], v[212:215], v[228:231], v[28:31]
	v_mfma_f32_16x16x32_bf16 v[36:39], v[184:187], v[228:231], v[36:39]
	v_mfma_f32_16x16x32_bf16 v[36:39], v[180:183], v[224:227], v[36:39]
	v_mfma_f32_16x16x32_bf16 v[40:43], v[172:175], v[224:227], v[40:43]
	v_mfma_f32_16x16x32_bf16 v[40:43], v[176:179], v[228:231], v[40:43]
	v_mfma_f32_16x16x32_bf16 v[48:51], v[140:143], v[228:231], v[48:51]
	v_mfma_f32_16x16x32_bf16 v[48:51], v[136:139], v[224:227], v[48:51]
	s_setprio 0
	s_setprio 1
	v_mfma_f32_16x16x32_bf16 v[32:35], v[136:139], v[232:235], v[32:35]
	v_mfma_f32_16x16x32_bf16 v[32:35], v[140:143], v[236:239], v[32:35]
	v_mfma_f32_16x16x32_bf16 v[24:27], v[176:179], v[236:239], v[24:27]
	v_mfma_f32_16x16x32_bf16 v[24:27], v[172:175], v[232:235], v[24:27]
	v_mfma_f32_16x16x32_bf16 v[20:23], v[180:183], v[232:235], v[20:23]
	v_mfma_f32_16x16x32_bf16 v[20:23], v[184:187], v[236:239], v[20:23]
	v_mfma_f32_16x16x32_bf16 v[16:19], v[212:215], v[236:239], v[16:19]
	v_mfma_f32_16x16x32_bf16 v[16:19], v[208:211], v[232:235], v[16:19]
	v_mfma_f32_16x16x32_bf16 v[0:3], v[208:211], v[240:243], v[0:3]
	v_mfma_f32_16x16x32_bf16 v[0:3], v[212:215], v[244:247], v[0:3]
	v_mfma_f32_16x16x32_bf16 v[4:7], v[184:187], v[244:247], v[4:7]
	v_mfma_f32_16x16x32_bf16 v[4:7], v[180:183], v[240:243], v[4:7]
	v_mfma_f32_16x16x32_bf16 v[8:11], v[172:175], v[240:243], v[8:11]
	v_mfma_f32_16x16x32_bf16 v[8:11], v[176:179], v[244:247], v[8:11]
	s_setprio 3
	s_barrier
	v_mfma_f32_16x16x32_bf16 v[12:15], v[140:143], v[244:247], v[12:15]
	v_mfma_f32_16x16x32_bf16 v[12:15], v[136:139], v[240:243], v[12:15]
	s_setprio 0
	s_add_i32 s44, 0, 0x18000
	v_add_u32_e32 v144, s44, v146
	s_add_i32 s45, 0, 0x1c000
	ds_read_b128 v[136:139], v144
	ds_read_b128 v[140:143], v144 offset:1024
	ds_read_b128 v[172:175], v144 offset:2048
	ds_read_b128 v[176:179], v144 offset:3072
	v_add_u32_e32 v144, s45, v146
	ds_read_b128 v[180:183], v144
	ds_read_b128 v[184:187], v144 offset:1024
	ds_read_b128 v[208:211], v144 offset:2048
	ds_read_b128 v[212:215], v144 offset:3072
	s_add_u32 s48, s48, 0x80000
	s_addc_u32 s49, s49, 0
	s_mov_b32 m0, s59
	v_lshl_add_u64 v[252:253], s[48:49], 0, v[164:165]
	ds_read_b128 v[216:219], v158 offset:32768
	ds_read_b128 v[220:223], v158 offset:33792
	ds_read_b128 v[224:227], v158 offset:34816
	ds_read_b128 v[228:231], v158 offset:35840
	ds_read_b128 v[232:235], v158 offset:36864
	ds_read_b128 v[236:239], v158 offset:37888
	ds_read_b128 v[240:243], v158 offset:38912
	ds_read_b128 v[244:247], v158 offset:39936
	global_load_lds_dwordx4 v[252:253], off
	v_lshl_add_u64 v[252:253], s[48:49], 0, v[168:169]
	s_mov_b32 m0, s60
	s_nop 0
	global_load_lds_dwordx4 v[252:253], off
	s_waitcnt vmcnt(8)
	s_waitcnt lgkmcnt(0)
	s_barrier
	s_setprio 1
	s_waitcnt lgkmcnt(0)
	v_mfma_f32_16x16x32_bf16 v[124:127], v[136:139], v[216:219], v[124:127]
	v_mfma_f32_16x16x32_bf16 v[124:127], v[140:143], v[220:223], v[124:127]
	v_mfma_f32_16x16x32_bf16 v[120:123], v[176:179], v[220:223], v[120:123]
	v_mfma_f32_16x16x32_bf16 v[120:123], v[172:175], v[216:219], v[120:123]
	v_mfma_f32_16x16x32_bf16 v[116:119], v[180:183], v[216:219], v[116:119]
	v_mfma_f32_16x16x32_bf16 v[116:119], v[184:187], v[220:223], v[116:119]
	v_mfma_f32_16x16x32_bf16 v[112:115], v[212:215], v[220:223], v[112:115]
	v_mfma_f32_16x16x32_bf16 v[112:115], v[208:211], v[216:219], v[112:115]
	v_mfma_f32_16x16x32_bf16 v[92:95], v[208:211], v[224:227], v[92:95]
	v_mfma_f32_16x16x32_bf16 v[92:95], v[212:215], v[228:231], v[92:95]
	v_mfma_f32_16x16x32_bf16 v[100:103], v[184:187], v[228:231], v[100:103]
	v_mfma_f32_16x16x32_bf16 v[100:103], v[180:183], v[224:227], v[100:103]
	v_mfma_f32_16x16x32_bf16 v[104:107], v[172:175], v[224:227], v[104:107]
	v_mfma_f32_16x16x32_bf16 v[104:107], v[176:179], v[228:231], v[104:107]
	v_mfma_f32_16x16x32_bf16 v[108:111], v[140:143], v[228:231], v[108:111]
	v_mfma_f32_16x16x32_bf16 v[108:111], v[136:139], v[224:227], v[108:111]
	s_setprio 0
	s_setprio 1
	v_mfma_f32_16x16x32_bf16 v[96:99], v[136:139], v[232:235], v[96:99]
	v_mfma_f32_16x16x32_bf16 v[96:99], v[140:143], v[236:239], v[96:99]
	v_mfma_f32_16x16x32_bf16 v[88:91], v[176:179], v[236:239], v[88:91]
	v_mfma_f32_16x16x32_bf16 v[88:91], v[172:175], v[232:235], v[88:91]
	v_mfma_f32_16x16x32_bf16 v[84:87], v[180:183], v[232:235], v[84:87]
	v_mfma_f32_16x16x32_bf16 v[84:87], v[184:187], v[236:239], v[84:87]
	v_mfma_f32_16x16x32_bf16 v[76:79], v[212:215], v[236:239], v[76:79]
	v_mfma_f32_16x16x32_bf16 v[76:79], v[208:211], v[232:235], v[76:79]
	v_mfma_f32_16x16x32_bf16 v[64:67], v[208:211], v[240:243], v[64:67]
	v_mfma_f32_16x16x32_bf16 v[64:67], v[212:215], v[244:247], v[64:67]
	v_mfma_f32_16x16x32_bf16 v[68:71], v[184:187], v[244:247], v[68:71]
	v_mfma_f32_16x16x32_bf16 v[68:71], v[180:183], v[240:243], v[68:71]
	v_mfma_f32_16x16x32_bf16 v[72:75], v[172:175], v[240:243], v[72:75]
	v_mfma_f32_16x16x32_bf16 v[72:75], v[176:179], v[244:247], v[72:75]
	s_setprio 3
	s_barrier
; #define PG8_STAGE(bufoff, gbase, voff) do { _Pragma("unroll") for (int _i = 0; _i < 2; ++_i) \
;         __builtin_amdgcn_global_load_lds((const unsigned*)((const char*)(gbase) + (voff)[_i]), (PG8_LAS unsigned*)(lds + (bufoff) + ldsw + _i * 8192), 16, 0, 0); } while (0)
; #define PG8_LDA(dst, b, h) do { _Pragma("unroll") for (int m = 0; m < 4; ++m) _Pragma("unroll") for (int k = 0; k < 2; ++k) dst[m][k] = *(const PG8_LAS bf16x8*)(lds + PG8_SA(b, h) + aoff + m * 2048 + k * 1024); } while (0)
; #define PG8_MMA(ai, bj, At, Bt) do { __builtin_amdgcn_s_setprio(1); _Pragma("unroll") for (int m = 0; m < 4; ++m) _Pragma("unroll") for (int n = 0; n < 2; ++n) _Pragma("unroll") for (int k = 0; k < 2; ++k) \
;         acc[ai][bj][m][n] = __builtin_amdgcn_mfma_f32_16x16x32_bf16(Bt[n][k], At[m][k], acc[ai][bj][m][n], 0, 0, 0); __builtin_amdgcn_s_setprio(0); } while (0)
; #define PG8_WAIT_V(n) asm volatile("s_waitcnt vmcnt(" #n ")" ::: "memory")
; #define PG8_WAIT_L(n) asm volatile("s_waitcnt lgkmcnt(" #n ")" ::: "memory")
; #define PG8_BAR __builtin_amdgcn_s_barrier()
; #define PG8_SCHED __builtin_amdgcn_sched_barrier(0)
; template <class Epi, class Sched, bool ALIGN_EPI = false, bool SP2 = false>
; __device__ __forceinline__ void gemm_phase(PG8_LAS unsigned char* lds, const Gemm g, const Sched& S, const Epi& E) {
;     ...
;         for (int t = 0; t < nt; t += 2) {
;     ...
;             PG8_LDA(At, 1, 1); PG8_STAGE(PG8_SB(1, 0), b3, voffB); PG8_STAGE(PG8_SB(1, 1), b3 + hstep, voffB); PG8_STAGE(PG8_SA(1, 0), a3, voffA);
;             PG8_WAIT_V(8); PG8_WAIT_L(0); PG8_BAR; PG8_MMA(1, 0, At, B0); PG8_MMA(1, 1, At, B1); PG8_BAR; PG8_SCHED;
;     ...
;         if constexpr (ALIGN_EPI) { if (wr == 0) PG8_BAR; }
	v_mfma_f32_16x16x32_bf16 v[80:83], v[140:143], v[244:247], v[80:83]
	v_mfma_f32_16x16x32_bf16 v[80:83], v[136:139], v[240:243], v[80:83]
	s_setprio 0
	s_add_i32 s44, s44, s52
	v_lshl_add_u64 v[188:189], v[188:189], 0, s[16:17]
	s_mov_b32 m0, s44
	ds_read_b128 v[216:219], v158 offset:49152
	ds_read_b128 v[220:223], v158 offset:50176
	ds_read_b128 v[224:227], v158 offset:51200
	ds_read_b128 v[228:231], v158 offset:52224
	ds_read_b128 v[232:235], v158 offset:53248
	ds_read_b128 v[236:239], v158 offset:54272
	ds_read_b128 v[240:243], v158 offset:55296
	ds_read_b128 v[244:247], v158 offset:56320
	global_load_lds_dwordx4 v[188:189], off
	s_add_i32 m0, s44, 0x2000
	s_add_u32 s42, s42, 0x80080
	v_lshl_add_u64 v[188:189], v[200:201], 0, s[16:17]
	s_addc_u32 s43, s43, 0
	s_add_i32 s44, s45, s52
	global_load_lds_dwordx4 v[188:189], off
	v_lshl_add_u64 v[188:189], s[42:43], 0, v[166:167]
	s_mov_b32 m0, s44
	s_nop 0
	global_load_lds_dwordx4 v[188:189], off
	v_lshl_add_u64 v[188:189], s[42:43], 0, v[170:171]
	s_add_i32 m0, s44, 0x2000
	s_nop 0
	global_load_lds_dwordx4 v[188:189], off
	v_lshl_add_u64 v[188:189], v[248:249], 0, s[16:17]
	s_mov_b32 m0, s62
	s_nop 0
	global_load_lds_dwordx4 v[188:189], off
	v_lshl_add_u64 v[188:189], v[250:251], 0, s[16:17]
	s_mov_b32 m0, s63
	s_nop 0
	global_load_lds_dwordx4 v[188:189], off
	s_add_i32 s71, s71, 2
	s_add_u32 s40, s40, 0x100
	s_addc_u32 s41, s41, 0
	s_add_u32 s69, s69, 0x100
	s_addc_u32 s70, s70, 0
	s_waitcnt vmcnt(8)
	s_waitcnt lgkmcnt(0)
	s_barrier
	s_setprio 1
	s_waitcnt lgkmcnt(0)
	v_mfma_f32_16x16x32_bf16 v[60:63], v[136:139], v[216:219], v[60:63]
	v_mfma_f32_16x16x32_bf16 v[60:63], v[140:143], v[220:223], v[60:63]
	v_mfma_f32_16x16x32_bf16 v[56:59], v[176:179], v[220:223], v[56:59]
	v_mfma_f32_16x16x32_bf16 v[56:59], v[172:175], v[216:219], v[56:59]
	v_mfma_f32_16x16x32_bf16 v[52:55], v[180:183], v[216:219], v[52:55]
	v_mfma_f32_16x16x32_bf16 v[52:55], v[184:187], v[220:223], v[52:55]
	v_mfma_f32_16x16x32_bf16 v[44:47], v[212:215], v[220:223], v[44:47]
	v_mfma_f32_16x16x32_bf16 v[44:47], v[208:211], v[216:219], v[44:47]
	v_mfma_f32_16x16x32_bf16 v[28:31], v[208:211], v[224:227], v[28:31]
	v_mfma_f32_16x16x32_bf16 v[28:31], v[212:215], v[228:231], v[28:31]
	v_mfma_f32_16x16x32_bf16 v[36:39], v[184:187], v[228:231], v[36:39]
	v_mfma_f32_16x16x32_bf16 v[36:39], v[180:183], v[224:227], v[36:39]
	v_mfma_f32_16x16x32_bf16 v[40:43], v[172:175], v[224:227], v[40:43]
	v_mfma_f32_16x16x32_bf16 v[40:43], v[176:179], v[228:231], v[40:43]
	v_mfma_f32_16x16x32_bf16 v[48:51], v[140:143], v[228:231], v[48:51]
	v_mfma_f32_16x16x32_bf16 v[48:51], v[136:139], v[224:227], v[48:51]
	s_setprio 0
	s_setprio 1
	v_mfma_f32_16x16x32_bf16 v[32:35], v[136:139], v[232:235], v[32:35]
	v_mfma_f32_16x16x32_bf16 v[32:35], v[140:143], v[236:239], v[32:35]
	v_mfma_f32_16x16x32_bf16 v[24:27], v[176:179], v[236:239], v[24:27]
	v_mfma_f32_16x16x32_bf16 v[24:27], v[172:175], v[232:235], v[24:27]
	v_mfma_f32_16x16x32_bf16 v[20:23], v[180:183], v[232:235], v[20:23]
	v_mfma_f32_16x16x32_bf16 v[20:23], v[184:187], v[236:239], v[20:23]
	v_mfma_f32_16x16x32_bf16 v[16:19], v[212:215], v[236:239], v[16:19]
	v_mfma_f32_16x16x32_bf16 v[16:19], v[208:211], v[232:235], v[16:19]
	v_mfma_f32_16x16x32_bf16 v[0:3], v[208:211], v[240:243], v[0:3]
	v_mfma_f32_16x16x32_bf16 v[0:3], v[212:215], v[244:247], v[0:3]
	v_mfma_f32_16x16x32_bf16 v[4:7], v[184:187], v[244:247], v[4:7]
	v_mfma_f32_16x16x32_bf16 v[4:7], v[180:183], v[240:243], v[4:7]
	v_mfma_f32_16x16x32_bf16 v[8:11], v[172:175], v[240:243], v[8:11]
	v_mfma_f32_16x16x32_bf16 v[8:11], v[176:179], v[244:247], v[8:11]
	s_setprio 3
	s_barrier
	v_mfma_f32_16x16x32_bf16 v[12:15], v[140:143], v[244:247], v[12:15]
	v_mfma_f32_16x16x32_bf16 v[12:15], v[136:139], v[240:243], v[12:15]
	s_setprio 0
	s_cmp_gt_u32 s71, 29
	s_cbranch_scc0 .LBB0_774
	s_and_b64 vcc, exec, s[18:19]
	s_cbranch_vccz .LBB0_777
	s_barrier

; #define PG8_STAGE(bufoff, gbase, voff) do { _Pragma("unroll") for (int _i = 0; _i < 2; ++_i) \
;         __builtin_amdgcn_global_load_lds((const unsigned*)((const char*)(gbase) + (voff)[_i]), (PG8_LAS unsigned*)(lds + (bufoff) + ldsw + _i * 8192), 16, 0, 0); } while (0)
; #define PG8_LDA(dst, b, h) do { _Pragma("unroll") for (int m = 0; m < 4; ++m) _Pragma("unroll") for (int k = 0; k < 2; ++k) dst[m][k] = *(const PG8_LAS bf16x8*)(lds + PG8_SA(b, h) + aoff + m * 2048 + k * 1024); } while (0)
; #define PG8_LDB(dst, b, h) do { _Pragma("unroll") for (int n = 0; n < 2; ++n) _Pragma("unroll") for (int k = 0; k < 2; ++k) dst[n][k] = *(const PG8_LAS bf16x8*)(lds + PG8_SB(b, h) + boff + n * 2048 + k * 1024); } while (0)
; #define PG8_MMA(ai, bj, At, Bt) do { __builtin_amdgcn_s_setprio(1); _Pragma("unroll") for (int m = 0; m < 4; ++m) _Pragma("unroll") for (int n = 0; n < 2; ++n) _Pragma("unroll") for (int k = 0; k < 2; ++k) \
;         acc[ai][bj][m][n] = __builtin_amdgcn_mfma_f32_16x16x32_bf16(Bt[n][k], At[m][k], acc[ai][bj][m][n], 0, 0, 0); __builtin_amdgcn_s_setprio(0); } while (0)
; #define PG8_WAIT_V(n) asm volatile("s_waitcnt vmcnt(" #n ")" ::: "memory")
; #define PG8_WAIT_L(n) asm volatile("s_waitcnt lgkmcnt(" #n ")" ::: "memory")
; #define PG8_BAR __builtin_amdgcn_s_barrier()
; template <class Epi, class Sched, bool ALIGN_EPI = false, bool SP2 = false>
; __device__ __forceinline__ void gemm_phase(PG8_LAS unsigned char* lds, const Gemm g, const Sched& S, const Epi& E) {
;     ...
;             const char* a1 = cA + (size_t)(t + 1) * kstep;
;             const char* a2 = last ? nA : cA + (size_t)(t + 2) * kstep; const char* b2 = last ? nB : cB + (size_t)(t + 2) * kstep;
;             const char* a3 = a2 + kstep; const char* b3 = b2 + kstep;
;             if (last && has_next) S.a_ready(nxt);
;             if constexpr (SP2) {
;             PG8_LDB(B0, 0, 0); PG8_LDB(B1, 0, 1); PG8_SCHED; PG8_LDA(At, 0, 0); PG8_STAGE(PG8_SA(1, 1), a1 + hstep, voffA);
;             PG8_WAIT_V(8); PG8_WAIT_L(0); PG8_BAR; PG8_MMA(0, 0, At, B0); PG8_MMA(0, 1, At, B1); PG8_BAR; PG8_SCHED;
;             PG8_LDA(At, 0, 1); PG8_STAGE(PG8_SB(0, 0), b2, voffB); PG8_STAGE(PG8_SB(0, 1), b2 + hstep, voffB); PG8_STAGE(PG8_SA(0, 0), a2, voffA);
;             PG8_WAIT_V(8); PG8_WAIT_L(0); PG8_BAR; PG8_MMA(1, 0, At, B0); PG8_MMA(1, 1, At, B1); PG8_BAR; PG8_SCHED;
.LBB0_837:
	ds_read_b128 v[134:137], v143
	ds_read_b128 v[146:149], v143 offset:1024
	ds_read_b128 v[150:153], v143 offset:2048
	ds_read_b128 v[154:157], v143 offset:3072
	ds_read_b128 v[172:175], v144
	ds_read_b128 v[176:179], v144 offset:1024
	ds_read_b128 v[180:183], v144 offset:2048
	ds_read_b128 v[184:187], v144 offset:3072
	s_add_u32 s44, s42, 0xffea0080
	s_addc_u32 s45, s43, -1
	s_cmpk_eq_i32 s75, 0x54
	s_cselect_b32 s53, s39, s45
	s_cselect_b32 s52, s38, s44
	s_cselect_b32 s49, s41, s35
	s_cselect_b32 s48, s40, s34
	v_lshl_add_u64 v[138:139], s[42:43], 0, v[128:129]
	s_add_i32 m0, s61, 0xc000
	ds_read_b128 v[208:211], v145
	ds_read_b128 v[212:215], v145 offset:1024
	ds_read_b128 v[216:219], v145 offset:2048
	ds_read_b128 v[220:223], v145 offset:3072
	ds_read_b128 v[224:227], v145 offset:4096
	ds_read_b128 v[228:231], v145 offset:5120
	ds_read_b128 v[232:235], v145 offset:6144
	ds_read_b128 v[236:239], v145 offset:7168
	global_load_lds_dwordx4 v[138:139], off
	v_lshl_add_u64 v[138:139], s[42:43], 0, v[130:131]
	s_add_i32 m0, s61, 0xe000
	s_nop 0
	global_load_lds_dwordx4 v[138:139], off
	s_waitcnt vmcnt(8)
	s_waitcnt lgkmcnt(0)
	s_barrier
	s_setprio 1
	s_waitcnt lgkmcnt(0)
	v_mfma_f32_16x16x32_bf16 v[124:127], v[134:137], v[208:211], v[124:127]
	v_mfma_f32_16x16x32_bf16 v[124:127], v[146:149], v[212:215], v[124:127]
	v_mfma_f32_16x16x32_bf16 v[120:123], v[154:157], v[212:215], v[120:123]
	v_mfma_f32_16x16x32_bf16 v[120:123], v[150:153], v[208:211], v[120:123]
	v_mfma_f32_16x16x32_bf16 v[108:111], v[172:175], v[208:211], v[108:111]
	v_mfma_f32_16x16x32_bf16 v[108:111], v[176:179], v[212:215], v[108:111]
	v_mfma_f32_16x16x32_bf16 v[104:107], v[184:187], v[212:215], v[104:107]
	v_mfma_f32_16x16x32_bf16 v[104:107], v[180:183], v[208:211], v[104:107]
	v_mfma_f32_16x16x32_bf16 v[96:99], v[180:183], v[216:219], v[96:99]
	v_mfma_f32_16x16x32_bf16 v[96:99], v[184:187], v[220:223], v[96:99]
	v_mfma_f32_16x16x32_bf16 v[100:103], v[176:179], v[220:223], v[100:103]
	v_mfma_f32_16x16x32_bf16 v[100:103], v[172:175], v[216:219], v[100:103]
	v_mfma_f32_16x16x32_bf16 v[112:115], v[150:153], v[216:219], v[112:115]
	v_mfma_f32_16x16x32_bf16 v[112:115], v[154:157], v[220:223], v[112:115]
	v_mfma_f32_16x16x32_bf16 v[116:119], v[146:149], v[220:223], v[116:119]
	v_mfma_f32_16x16x32_bf16 v[116:119], v[134:137], v[216:219], v[116:119]
	s_setprio 0
	s_setprio 1
	v_mfma_f32_16x16x32_bf16 v[92:95], v[134:137], v[224:227], v[92:95]
	v_mfma_f32_16x16x32_bf16 v[92:95], v[146:149], v[228:231], v[92:95]
	v_mfma_f32_16x16x32_bf16 v[88:91], v[154:157], v[228:231], v[88:91]
	v_mfma_f32_16x16x32_bf16 v[88:91], v[150:153], v[224:227], v[88:91]
	v_mfma_f32_16x16x32_bf16 v[76:79], v[172:175], v[224:227], v[76:79]
	v_mfma_f32_16x16x32_bf16 v[76:79], v[176:179], v[228:231], v[76:79]
	v_mfma_f32_16x16x32_bf16 v[72:75], v[184:187], v[228:231], v[72:75]
	v_mfma_f32_16x16x32_bf16 v[72:75], v[180:183], v[224:227], v[72:75]
	v_mfma_f32_16x16x32_bf16 v[64:67], v[180:183], v[232:235], v[64:67]
	v_mfma_f32_16x16x32_bf16 v[64:67], v[184:187], v[236:239], v[64:67]
	v_mfma_f32_16x16x32_bf16 v[68:71], v[176:179], v[236:239], v[68:71]
	v_mfma_f32_16x16x32_bf16 v[68:71], v[172:175], v[232:235], v[68:71]
	v_mfma_f32_16x16x32_bf16 v[80:83], v[150:153], v[232:235], v[80:83]
	v_mfma_f32_16x16x32_bf16 v[80:83], v[154:157], v[236:239], v[80:83]
	s_setprio 3
	s_barrier
	v_mfma_f32_16x16x32_bf16 v[84:87], v[146:149], v[236:239], v[84:87]
	v_mfma_f32_16x16x32_bf16 v[84:87], v[134:137], v[232:235], v[84:87]
	s_setprio 0
	s_add_i32 s44, s68, s60
	v_lshl_add_u64 v[138:139], s[48:49], 0, v[160:161]
	s_mov_b32 m0, s44
	ds_read_b128 v[208:211], v145 offset:16384
	ds_read_b128 v[212:215], v145 offset:17408
	ds_read_b128 v[216:219], v145 offset:18432
	ds_read_b128 v[220:223], v145 offset:19456
	ds_read_b128 v[224:227], v145 offset:20480
	ds_read_b128 v[228:231], v145 offset:21504
	ds_read_b128 v[232:235], v145 offset:22528
	ds_read_b128 v[236:239], v145 offset:23552
	global_load_lds_dwordx4 v[138:139], off
	s_add_i32 m0, s44, 0x2000
	s_add_u32 s76, s48, 0x160000
	v_lshl_add_u64 v[158:159], s[48:49], 0, v[162:163]
	s_addc_u32 s77, s49, 0
	s_add_i32 s44, s69, s60
	global_load_lds_dwordx4 v[158:159], off
	v_lshl_add_u64 v[188:189], s[76:77], 0, v[160:161]
	s_mov_b32 m0, s44
	v_lshl_add_u64 v[200:201], s[52:53], 0, v[162:163]
	global_load_lds_dwordx4 v[188:189], off
	v_lshl_add_u64 v[188:189], s[76:77], 0, v[162:163]
	s_add_i32 m0, s44, 0x2000
	s_nop 0
	global_load_lds_dwordx4 v[188:189], off
	v_lshl_add_u64 v[188:189], s[52:53], 0, v[160:161]
	s_mov_b32 m0, s61
	s_nop 0
	global_load_lds_dwordx4 v[188:189], off
	s_mov_b32 m0, s62
	s_nop 0
	global_load_lds_dwordx4 v[200:201], off
	s_waitcnt vmcnt(8)
	s_waitcnt lgkmcnt(0)
	s_barrier
; #define PG8_STAGE(bufoff, gbase, voff) do { _Pragma("unroll") for (int _i = 0; _i < 2; ++_i) \
;         __builtin_amdgcn_global_load_lds((const unsigned*)((const char*)(gbase) + (voff)[_i]), (PG8_LAS unsigned*)(lds + (bufoff) + ldsw + _i * 8192), 16, 0, 0); } while (0)
; #define PG8_LDA(dst, b, h) do { _Pragma("unroll") for (int m = 0; m < 4; ++m) _Pragma("unroll") for (int k = 0; k < 2; ++k) dst[m][k] = *(const PG8_LAS bf16x8*)(lds + PG8_SA(b, h) + aoff + m * 2048 + k * 1024); } while (0)
; #define PG8_LDB(dst, b, h) do { _Pragma("unroll") for (int n = 0; n < 2; ++n) _Pragma("unroll") for (int k = 0; k < 2; ++k) dst[n][k] = *(const PG8_LAS bf16x8*)(lds + PG8_SB(b, h) + boff + n * 2048 + k * 1024); } while (0)
; #define PG8_MMA(ai, bj, At, Bt) do { __builtin_amdgcn_s_setprio(1); _Pragma("unroll") for (int m = 0; m < 4; ++m) _Pragma("unroll") for (int n = 0; n < 2; ++n) _Pragma("unroll") for (int k = 0; k < 2; ++k) \
;         acc[ai][bj][m][n] = __builtin_amdgcn_mfma_f32_16x16x32_bf16(Bt[n][k], At[m][k], acc[ai][bj][m][n], 0, 0, 0); __builtin_amdgcn_s_setprio(0); } while (0)
; #define PG8_WAIT_V(n) asm volatile("s_waitcnt vmcnt(" #n ")" ::: "memory")
; #define PG8_WAIT_L(n) asm volatile("s_waitcnt lgkmcnt(" #n ")" ::: "memory")
; #define PG8_BAR __builtin_amdgcn_s_barrier()
; #define PG8_SCHED __builtin_amdgcn_sched_barrier(0)
; template <class Epi, class Sched, bool ALIGN_EPI = false, bool SP2 = false>
; __device__ __forceinline__ void gemm_phase(PG8_LAS unsigned char* lds, const Gemm g, const Sched& S, const Epi& E) {
;     ...
;             PG8_WAIT_V(8); PG8_WAIT_L(0); PG8_BAR; PG8_MMA(1, 0, At, B0); PG8_MMA(1, 1, At, B1); PG8_BAR; PG8_SCHED;
;             PG8_LDB(B0, 1, 0); PG8_LDB(B1, 1, 1); PG8_SCHED; PG8_LDA(At, 1, 0); PG8_STAGE(PG8_SA(0, 1), a2 + hstep, voffA);
;             PG8_WAIT_V(8); PG8_WAIT_L(0); PG8_BAR; PG8_MMA(0, 0, At, B0); PG8_MMA(0, 1, At, B1); PG8_BAR; PG8_SCHED;
	s_setprio 1
	s_waitcnt lgkmcnt(0)
	v_mfma_f32_16x16x32_bf16 v[60:63], v[134:137], v[208:211], v[60:63]
	v_mfma_f32_16x16x32_bf16 v[60:63], v[146:149], v[212:215], v[60:63]
	v_mfma_f32_16x16x32_bf16 v[56:59], v[154:157], v[212:215], v[56:59]
	v_mfma_f32_16x16x32_bf16 v[56:59], v[150:153], v[208:211], v[56:59]
	v_mfma_f32_16x16x32_bf16 v[44:47], v[172:175], v[208:211], v[44:47]
	v_mfma_f32_16x16x32_bf16 v[44:47], v[176:179], v[212:215], v[44:47]
	v_mfma_f32_16x16x32_bf16 v[40:43], v[184:187], v[212:215], v[40:43]
	v_mfma_f32_16x16x32_bf16 v[40:43], v[180:183], v[208:211], v[40:43]
	v_mfma_f32_16x16x32_bf16 v[32:35], v[180:183], v[216:219], v[32:35]
	v_mfma_f32_16x16x32_bf16 v[32:35], v[184:187], v[220:223], v[32:35]
	v_mfma_f32_16x16x32_bf16 v[36:39], v[176:179], v[220:223], v[36:39]
	v_mfma_f32_16x16x32_bf16 v[36:39], v[172:175], v[216:219], v[36:39]
	v_mfma_f32_16x16x32_bf16 v[48:51], v[150:153], v[216:219], v[48:51]
	v_mfma_f32_16x16x32_bf16 v[48:51], v[154:157], v[220:223], v[48:51]
	v_mfma_f32_16x16x32_bf16 v[52:55], v[146:149], v[220:223], v[52:55]
	v_mfma_f32_16x16x32_bf16 v[52:55], v[134:137], v[216:219], v[52:55]
	s_setprio 0
	s_setprio 1
	v_mfma_f32_16x16x32_bf16 v[28:31], v[134:137], v[224:227], v[28:31]
	v_mfma_f32_16x16x32_bf16 v[28:31], v[146:149], v[228:231], v[28:31]
	v_mfma_f32_16x16x32_bf16 v[24:27], v[154:157], v[228:231], v[24:27]
	v_mfma_f32_16x16x32_bf16 v[24:27], v[150:153], v[224:227], v[24:27]
	v_mfma_f32_16x16x32_bf16 v[12:15], v[172:175], v[224:227], v[12:15]
	v_mfma_f32_16x16x32_bf16 v[12:15], v[176:179], v[228:231], v[12:15]
	v_mfma_f32_16x16x32_bf16 v[8:11], v[184:187], v[228:231], v[8:11]
	v_mfma_f32_16x16x32_bf16 v[8:11], v[180:183], v[224:227], v[8:11]
	v_mfma_f32_16x16x32_bf16 v[0:3], v[180:183], v[232:235], v[0:3]
	v_mfma_f32_16x16x32_bf16 v[0:3], v[184:187], v[236:239], v[0:3]
	v_mfma_f32_16x16x32_bf16 v[4:7], v[176:179], v[236:239], v[4:7]
	v_mfma_f32_16x16x32_bf16 v[4:7], v[172:175], v[232:235], v[4:7]
	v_mfma_f32_16x16x32_bf16 v[16:19], v[150:153], v[232:235], v[16:19]
	v_mfma_f32_16x16x32_bf16 v[16:19], v[154:157], v[236:239], v[16:19]
	s_setprio 3
	s_barrier
	v_mfma_f32_16x16x32_bf16 v[20:23], v[146:149], v[236:239], v[20:23]
	v_mfma_f32_16x16x32_bf16 v[20:23], v[134:137], v[232:235], v[20:23]
	s_setprio 0
	s_add_i32 s44, 0, 0x18000
	s_add_i32 s45, 0, 0x1c000
	v_add_u32_e32 v154, s44, v141
	v_add_u32_e32 v165, s45, v141
	ds_read_b128 v[134:137], v154
	ds_read_b128 v[146:149], v154 offset:1024
	ds_read_b128 v[150:153], v154 offset:2048
	ds_read_b128 v[154:157], v154 offset:3072
	ds_read_b128 v[172:175], v165
	ds_read_b128 v[176:179], v165 offset:1024
	ds_read_b128 v[180:183], v165 offset:2048
	ds_read_b128 v[184:187], v165 offset:3072
	s_add_u32 s52, s52, 0x160000
	s_addc_u32 s53, s53, 0
	s_mov_b32 m0, s63
	v_lshl_add_u64 v[240:241], s[52:53], 0, v[160:161]
	ds_read_b128 v[208:211], v145 offset:32768
	ds_read_b128 v[212:215], v145 offset:33792
	ds_read_b128 v[216:219], v145 offset:34816
	ds_read_b128 v[220:223], v145 offset:35840
	ds_read_b128 v[224:227], v145 offset:36864
	ds_read_b128 v[228:231], v145 offset:37888
	ds_read_b128 v[232:235], v145 offset:38912
	ds_read_b128 v[236:239], v145 offset:39936
	global_load_lds_dwordx4 v[240:241], off
	v_lshl_add_u64 v[240:241], s[52:53], 0, v[162:163]
	s_mov_b32 m0, s64
	s_nop 0
	global_load_lds_dwordx4 v[240:241], off
	s_waitcnt vmcnt(8)
	s_waitcnt lgkmcnt(0)
	s_barrier
	s_setprio 1
	s_waitcnt lgkmcnt(0)
	v_mfma_f32_16x16x32_bf16 v[124:127], v[134:137], v[208:211], v[124:127]
	v_mfma_f32_16x16x32_bf16 v[124:127], v[146:149], v[212:215], v[124:127]
	v_mfma_f32_16x16x32_bf16 v[120:123], v[154:157], v[212:215], v[120:123]
	v_mfma_f32_16x16x32_bf16 v[120:123], v[150:153], v[208:211], v[120:123]
	v_mfma_f32_16x16x32_bf16 v[108:111], v[172:175], v[208:211], v[108:111]
	v_mfma_f32_16x16x32_bf16 v[108:111], v[176:179], v[212:215], v[108:111]
	v_mfma_f32_16x16x32_bf16 v[104:107], v[184:187], v[212:215], v[104:107]
	v_mfma_f32_16x16x32_bf16 v[104:107], v[180:183], v[208:211], v[104:107]
	v_mfma_f32_16x16x32_bf16 v[96:99], v[180:183], v[216:219], v[96:99]
	v_mfma_f32_16x16x32_bf16 v[96:99], v[184:187], v[220:223], v[96:99]
	v_mfma_f32_16x16x32_bf16 v[100:103], v[176:179], v[220:223], v[100:103]
	v_mfma_f32_16x16x32_bf16 v[100:103], v[172:175], v[216:219], v[100:103]
	v_mfma_f32_16x16x32_bf16 v[112:115], v[150:153], v[216:219], v[112:115]
	v_mfma_f32_16x16x32_bf16 v[112:115], v[154:157], v[220:223], v[112:115]
	v_mfma_f32_16x16x32_bf16 v[116:119], v[146:149], v[220:223], v[116:119]
	v_mfma_f32_16x16x32_bf16 v[116:119], v[134:137], v[216:219], v[116:119]
	s_setprio 0
	s_setprio 1
	v_mfma_f32_16x16x32_bf16 v[92:95], v[134:137], v[224:227], v[92:95]
	v_mfma_f32_16x16x32_bf16 v[92:95], v[146:149], v[228:231], v[92:95]
	v_mfma_f32_16x16x32_bf16 v[88:91], v[154:157], v[228:231], v[88:91]
	v_mfma_f32_16x16x32_bf16 v[88:91], v[150:153], v[224:227], v[88:91]
	v_mfma_f32_16x16x32_bf16 v[76:79], v[172:175], v[224:227], v[76:79]
	v_mfma_f32_16x16x32_bf16 v[76:79], v[176:179], v[228:231], v[76:79]
	v_mfma_f32_16x16x32_bf16 v[72:75], v[184:187], v[228:231], v[72:75]
	v_mfma_f32_16x16x32_bf16 v[72:75], v[180:183], v[224:227], v[72:75]
	v_mfma_f32_16x16x32_bf16 v[64:67], v[180:183], v[232:235], v[64:67]
	v_mfma_f32_16x16x32_bf16 v[64:67], v[184:187], v[236:239], v[64:67]
	v_mfma_f32_16x16x32_bf16 v[68:71], v[176:179], v[236:239], v[68:71]
	v_mfma_f32_16x16x32_bf16 v[68:71], v[172:175], v[232:235], v[68:71]
	v_mfma_f32_16x16x32_bf16 v[80:83], v[150:153], v[232:235], v[80:83]
	v_mfma_f32_16x16x32_bf16 v[80:83], v[154:157], v[236:239], v[80:83]
	s_setprio 3
	s_barrier
; #define PG8_STAGE(bufoff, gbase, voff) do { _Pragma("unroll") for (int _i = 0; _i < 2; ++_i) \
;         __builtin_amdgcn_global_load_lds((const unsigned*)((const char*)(gbase) + (voff)[_i]), (PG8_LAS unsigned*)(lds + (bufoff) + ldsw + _i * 8192), 16, 0, 0); } while (0)
; #define PG8_LDA(dst, b, h) do { _Pragma("unroll") for (int m = 0; m < 4; ++m) _Pragma("unroll") for (int k = 0; k < 2; ++k) dst[m][k] = *(const PG8_LAS bf16x8*)(lds + PG8_SA(b, h) + aoff + m * 2048 + k * 1024); } while (0)
; #define PG8_MMA(ai, bj, At, Bt) do { __builtin_amdgcn_s_setprio(1); _Pragma("unroll") for (int m = 0; m < 4; ++m) _Pragma("unroll") for (int n = 0; n < 2; ++n) _Pragma("unroll") for (int k = 0; k < 2; ++k) \
;         acc[ai][bj][m][n] = __builtin_amdgcn_mfma_f32_16x16x32_bf16(Bt[n][k], At[m][k], acc[ai][bj][m][n], 0, 0, 0); __builtin_amdgcn_s_setprio(0); } while (0)
; #define PG8_WAIT_V(n) asm volatile("s_waitcnt vmcnt(" #n ")" ::: "memory")
; #define PG8_WAIT_L(n) asm volatile("s_waitcnt lgkmcnt(" #n ")" ::: "memory")
; #define PG8_BAR __builtin_amdgcn_s_barrier()
; #define PG8_SCHED __builtin_amdgcn_sched_barrier(0)
; template <class Epi, class Sched, bool ALIGN_EPI = false, bool SP2 = false>
; __device__ __forceinline__ void gemm_phase(PG8_LAS unsigned char* lds, const Gemm g, const Sched& S, const Epi& E) {
;     ...
;         for (int t = 0; t < nt; t += 2) {
;     ...
;             PG8_LDA(At, 1, 1); PG8_STAGE(PG8_SB(1, 0), b3, voffB); PG8_STAGE(PG8_SB(1, 1), b3 + hstep, voffB); PG8_STAGE(PG8_SA(1, 0), a3, voffA);
;             PG8_WAIT_V(8); PG8_WAIT_L(0); PG8_BAR; PG8_MMA(1, 0, At, B0); PG8_MMA(1, 1, At, B1); PG8_BAR; PG8_SCHED;
;     ...
;         if constexpr (ALIGN_EPI) { if (wr == 0) PG8_BAR; }
	v_mfma_f32_16x16x32_bf16 v[84:87], v[146:149], v[236:239], v[84:87]
	v_mfma_f32_16x16x32_bf16 v[84:87], v[134:137], v[232:235], v[84:87]
	s_setprio 0
	s_add_i32 s44, s44, s60
	v_lshl_add_u64 v[138:139], v[138:139], 0, s[16:17]
	s_mov_b32 m0, s44
	ds_read_b128 v[208:211], v145 offset:49152
	ds_read_b128 v[212:215], v145 offset:50176
	ds_read_b128 v[216:219], v145 offset:51200
	ds_read_b128 v[220:223], v145 offset:52224
	ds_read_b128 v[224:227], v145 offset:53248
	ds_read_b128 v[228:231], v145 offset:54272
	ds_read_b128 v[232:235], v145 offset:55296
	ds_read_b128 v[236:239], v145 offset:56320
	global_load_lds_dwordx4 v[138:139], off
	s_add_i32 m0, s44, 0x2000
	s_add_u32 s48, s48, 0x160080
	v_lshl_add_u64 v[138:139], v[158:159], 0, s[16:17]
	s_addc_u32 s49, s49, 0
	s_add_i32 s44, s45, s60
	global_load_lds_dwordx4 v[138:139], off
	v_lshl_add_u64 v[138:139], s[48:49], 0, v[160:161]
	s_mov_b32 m0, s44
	s_nop 0
	global_load_lds_dwordx4 v[138:139], off
	v_lshl_add_u64 v[138:139], s[48:49], 0, v[162:163]
	s_add_i32 m0, s44, 0x2000
	s_nop 0
	global_load_lds_dwordx4 v[138:139], off
	v_lshl_add_u64 v[138:139], v[188:189], 0, s[16:17]
	s_mov_b32 m0, s65
	s_nop 0
	global_load_lds_dwordx4 v[138:139], off
	v_lshl_add_u64 v[138:139], v[200:201], 0, s[16:17]
	s_mov_b32 m0, s66
	s_nop 0
	global_load_lds_dwordx4 v[138:139], off
	s_add_i32 s75, s75, 2
	s_add_u32 s42, s42, 0x100
	s_addc_u32 s43, s43, 0
	s_add_u32 s34, s34, 0x100
	s_addc_u32 s35, s35, 0
	s_waitcnt vmcnt(8)
	s_waitcnt lgkmcnt(0)
	s_barrier
	s_setprio 1
	s_waitcnt lgkmcnt(0)
	v_mfma_f32_16x16x32_bf16 v[60:63], v[134:137], v[208:211], v[60:63]
	v_mfma_f32_16x16x32_bf16 v[60:63], v[146:149], v[212:215], v[60:63]
	v_mfma_f32_16x16x32_bf16 v[56:59], v[154:157], v[212:215], v[56:59]
	v_mfma_f32_16x16x32_bf16 v[56:59], v[150:153], v[208:211], v[56:59]
	v_mfma_f32_16x16x32_bf16 v[44:47], v[172:175], v[208:211], v[44:47]
	v_mfma_f32_16x16x32_bf16 v[44:47], v[176:179], v[212:215], v[44:47]
	v_mfma_f32_16x16x32_bf16 v[40:43], v[184:187], v[212:215], v[40:43]
	v_mfma_f32_16x16x32_bf16 v[40:43], v[180:183], v[208:211], v[40:43]
	v_mfma_f32_16x16x32_bf16 v[32:35], v[180:183], v[216:219], v[32:35]
	v_mfma_f32_16x16x32_bf16 v[32:35], v[184:187], v[220:223], v[32:35]
	v_mfma_f32_16x16x32_bf16 v[36:39], v[176:179], v[220:223], v[36:39]
	v_mfma_f32_16x16x32_bf16 v[36:39], v[172:175], v[216:219], v[36:39]
	v_mfma_f32_16x16x32_bf16 v[48:51], v[150:153], v[216:219], v[48:51]
	v_mfma_f32_16x16x32_bf16 v[48:51], v[154:157], v[220:223], v[48:51]
	v_mfma_f32_16x16x32_bf16 v[52:55], v[146:149], v[220:223], v[52:55]
	v_mfma_f32_16x16x32_bf16 v[52:55], v[134:137], v[216:219], v[52:55]
	s_setprio 0
	s_setprio 1
	v_mfma_f32_16x16x32_bf16 v[28:31], v[134:137], v[224:227], v[28:31]
	v_mfma_f32_16x16x32_bf16 v[28:31], v[146:149], v[228:231], v[28:31]
	v_mfma_f32_16x16x32_bf16 v[24:27], v[154:157], v[228:231], v[24:27]
	v_mfma_f32_16x16x32_bf16 v[24:27], v[150:153], v[224:227], v[24:27]
	v_mfma_f32_16x16x32_bf16 v[12:15], v[172:175], v[224:227], v[12:15]
	v_mfma_f32_16x16x32_bf16 v[12:15], v[176:179], v[228:231], v[12:15]
	v_mfma_f32_16x16x32_bf16 v[8:11], v[184:187], v[228:231], v[8:11]
	v_mfma_f32_16x16x32_bf16 v[8:11], v[180:183], v[224:227], v[8:11]
	v_mfma_f32_16x16x32_bf16 v[0:3], v[180:183], v[232:235], v[0:3]
	v_mfma_f32_16x16x32_bf16 v[0:3], v[184:187], v[236:239], v[0:3]
	v_mfma_f32_16x16x32_bf16 v[4:7], v[176:179], v[236:239], v[4:7]
	v_mfma_f32_16x16x32_bf16 v[4:7], v[172:175], v[232:235], v[4:7]
	v_mfma_f32_16x16x32_bf16 v[16:19], v[150:153], v[232:235], v[16:19]
	v_mfma_f32_16x16x32_bf16 v[16:19], v[154:157], v[236:239], v[16:19]
	s_setprio 3
	s_barrier
	v_mfma_f32_16x16x32_bf16 v[20:23], v[146:149], v[236:239], v[20:23]
	v_mfma_f32_16x16x32_bf16 v[20:23], v[134:137], v[232:235], v[20:23]
	s_setprio 0
	s_cmpk_gt_u32 s75, 0x55
	s_cbranch_scc0 .LBB0_837
	s_and_b64 vcc, exec, s[18:19]
	s_cbranch_vccz .LBB0_840
	s_barrier

; #define PG8_STAGE(bufoff, gbase, voff) do { _Pragma("unroll") for (int _i = 0; _i < 2; ++_i) \
;         __builtin_amdgcn_global_load_lds((const unsigned*)((const char*)(gbase) + (voff)[_i]), (PG8_LAS unsigned*)(lds + (bufoff) + ldsw + _i * 8192), 16, 0, 0); } while (0)
; #define PG8_LDA(dst, b, h) do { _Pragma("unroll") for (int m = 0; m < 4; ++m) _Pragma("unroll") for (int k = 0; k < 2; ++k) dst[m][k] = *(const PG8_LAS bf16x8*)(lds + PG8_SA(b, h) + aoff + m * 2048 + k * 1024); } while (0)
; #define PG8_LDB(dst, b, h) do { _Pragma("unroll") for (int n = 0; n < 2; ++n) _Pragma("unroll") for (int k = 0; k < 2; ++k) dst[n][k] = *(const PG8_LAS bf16x8*)(lds + PG8_SB(b, h) + boff + n * 2048 + k * 1024); } while (0)
; #define PG8_MMA(ai, bj, At, Bt) do { __builtin_amdgcn_s_setprio(1); _Pragma("unroll") for (int m = 0; m < 4; ++m) _Pragma("unroll") for (int n = 0; n < 2; ++n) _Pragma("unroll") for (int k = 0; k < 2; ++k) \
;         acc[ai][bj][m][n] = __builtin_amdgcn_mfma_f32_16x16x32_bf16(Bt[n][k], At[m][k], acc[ai][bj][m][n], 0, 0, 0); __builtin_amdgcn_s_setprio(0); } while (0)
; #define PG8_WAIT_V(n) asm volatile("s_waitcnt vmcnt(" #n ")" ::: "memory")
; #define PG8_WAIT_L(n) asm volatile("s_waitcnt lgkmcnt(" #n ")" ::: "memory")
; #define PG8_BAR __builtin_amdgcn_s_barrier()
; template <class Epi, class Sched, bool ALIGN_EPI = false, bool SP2 = false>
; __device__ __forceinline__ void gemm_phase(PG8_LAS unsigned char* lds, const Gemm g, const Sched& S, const Epi& E) {
;     ...
;             const char* a1 = cA + (size_t)(t + 1) * kstep;
;             const char* a2 = last ? nA : cA + (size_t)(t + 2) * kstep; const char* b2 = last ? nB : cB + (size_t)(t + 2) * kstep;
;             const char* a3 = a2 + kstep; const char* b3 = b2 + kstep;
;             if (last && has_next) S.a_ready(nxt);
;             if constexpr (SP2) {
;             PG8_LDB(B0, 0, 0); PG8_LDB(B1, 0, 1); PG8_SCHED; PG8_LDA(At, 0, 0); PG8_STAGE(PG8_SA(1, 1), a1 + hstep, voffA);
;             PG8_WAIT_V(8); PG8_WAIT_L(0); PG8_BAR; PG8_MMA(0, 0, At, B0); PG8_MMA(0, 1, At, B1); PG8_BAR; PG8_SCHED;
;             PG8_LDA(At, 0, 1); PG8_STAGE(PG8_SB(0, 0), b2, voffB); PG8_STAGE(PG8_SB(0, 1), b2 + hstep, voffB); PG8_STAGE(PG8_SA(0, 0), a2, voffA);
;             PG8_WAIT_V(8); PG8_WAIT_L(0); PG8_BAR; PG8_MMA(1, 0, At, B0); PG8_MMA(1, 1, At, B1); PG8_BAR; PG8_SCHED;
.LBB0_880:
	ds_read_b128 v[136:139], v156
	ds_read_b128 v[140:143], v156 offset:1024
	ds_read_b128 v[172:175], v156 offset:2048
	ds_read_b128 v[176:179], v156 offset:3072
	ds_read_b128 v[180:183], v157
	ds_read_b128 v[184:187], v157 offset:1024
	ds_read_b128 v[196:199], v157 offset:2048
	ds_read_b128 v[208:211], v157 offset:3072
	s_add_u32 s40, s38, 0xfff80080
	s_addc_u32 s41, s39, -1
	s_cmp_eq_u32 s63, 28
	s_cselect_b32 s43, s19, s41
	s_cselect_b32 s42, s34, s40
	s_cselect_b32 s41, s21, s62
	s_cselect_b32 s40, s35, s61
	v_lshl_add_u64 v[188:189], s[38:39], 0, v[128:129]
	s_add_i32 m0, s7, 0xc000
	ds_read_b128 v[212:215], v158
	ds_read_b128 v[216:219], v158 offset:1024
	ds_read_b128 v[220:223], v158 offset:2048
	ds_read_b128 v[224:227], v158 offset:3072
	ds_read_b128 v[228:231], v158 offset:4096
	ds_read_b128 v[232:235], v158 offset:5120
	ds_read_b128 v[236:239], v158 offset:6144
	ds_read_b128 v[240:243], v158 offset:7168
	global_load_lds_dwordx4 v[188:189], off
	v_lshl_add_u64 v[188:189], s[38:39], 0, v[130:131]
	s_add_i32 m0, s7, 0xe000
	s_nop 0
	global_load_lds_dwordx4 v[188:189], off
	s_waitcnt vmcnt(8)
	s_waitcnt lgkmcnt(0)
	s_barrier
	s_setprio 1
	s_waitcnt lgkmcnt(0)
	v_mfma_f32_16x16x32_bf16 v[124:127], v[136:139], v[212:215], v[124:127]
	v_mfma_f32_16x16x32_bf16 v[124:127], v[140:143], v[216:219], v[124:127]
	v_mfma_f32_16x16x32_bf16 v[120:123], v[176:179], v[216:219], v[120:123]
	v_mfma_f32_16x16x32_bf16 v[120:123], v[172:175], v[212:215], v[120:123]
	v_mfma_f32_16x16x32_bf16 v[116:119], v[180:183], v[212:215], v[116:119]
	v_mfma_f32_16x16x32_bf16 v[116:119], v[184:187], v[216:219], v[116:119]
	v_mfma_f32_16x16x32_bf16 v[112:115], v[208:211], v[216:219], v[112:115]
	v_mfma_f32_16x16x32_bf16 v[112:115], v[196:199], v[212:215], v[112:115]
	v_mfma_f32_16x16x32_bf16 v[92:95], v[196:199], v[220:223], v[92:95]
	v_mfma_f32_16x16x32_bf16 v[92:95], v[208:211], v[224:227], v[92:95]
	v_mfma_f32_16x16x32_bf16 v[100:103], v[184:187], v[224:227], v[100:103]
	v_mfma_f32_16x16x32_bf16 v[100:103], v[180:183], v[220:223], v[100:103]
	v_mfma_f32_16x16x32_bf16 v[104:107], v[172:175], v[220:223], v[104:107]
	v_mfma_f32_16x16x32_bf16 v[104:107], v[176:179], v[224:227], v[104:107]
	v_mfma_f32_16x16x32_bf16 v[108:111], v[140:143], v[224:227], v[108:111]
	v_mfma_f32_16x16x32_bf16 v[108:111], v[136:139], v[220:223], v[108:111]
	s_setprio 0
	s_setprio 1
	v_mfma_f32_16x16x32_bf16 v[96:99], v[136:139], v[228:231], v[96:99]
	v_mfma_f32_16x16x32_bf16 v[96:99], v[140:143], v[232:235], v[96:99]
	v_mfma_f32_16x16x32_bf16 v[88:91], v[176:179], v[232:235], v[88:91]
	v_mfma_f32_16x16x32_bf16 v[88:91], v[172:175], v[228:231], v[88:91]
	v_mfma_f32_16x16x32_bf16 v[84:87], v[180:183], v[228:231], v[84:87]
	v_mfma_f32_16x16x32_bf16 v[84:87], v[184:187], v[232:235], v[84:87]
	v_mfma_f32_16x16x32_bf16 v[76:79], v[208:211], v[232:235], v[76:79]
	v_mfma_f32_16x16x32_bf16 v[76:79], v[196:199], v[228:231], v[76:79]
	v_mfma_f32_16x16x32_bf16 v[64:67], v[196:199], v[236:239], v[64:67]
	v_mfma_f32_16x16x32_bf16 v[64:67], v[208:211], v[240:243], v[64:67]
	v_mfma_f32_16x16x32_bf16 v[68:71], v[184:187], v[240:243], v[68:71]
	v_mfma_f32_16x16x32_bf16 v[68:71], v[180:183], v[236:239], v[68:71]
	v_mfma_f32_16x16x32_bf16 v[72:75], v[172:175], v[236:239], v[72:75]
	v_mfma_f32_16x16x32_bf16 v[72:75], v[176:179], v[240:243], v[72:75]
	s_setprio 3
	s_barrier
	v_mfma_f32_16x16x32_bf16 v[80:83], v[140:143], v[240:243], v[80:83]
	v_mfma_f32_16x16x32_bf16 v[80:83], v[136:139], v[236:239], v[80:83]
	s_setprio 0
	s_add_i32 s44, s52, s33
	v_lshl_add_u64 v[188:189], s[40:41], 0, v[166:167]
	s_mov_b32 m0, s44
	ds_read_b128 v[212:215], v158 offset:16384
	ds_read_b128 v[216:219], v158 offset:17408
	ds_read_b128 v[220:223], v158 offset:18432
	ds_read_b128 v[224:227], v158 offset:19456
	ds_read_b128 v[228:231], v158 offset:20480
	ds_read_b128 v[232:235], v158 offset:21504
	ds_read_b128 v[236:239], v158 offset:22528
	ds_read_b128 v[240:243], v158 offset:23552
	global_load_lds_dwordx4 v[188:189], off
	s_add_i32 m0, s44, 0x2000
	s_add_u32 s64, s40, 0x80000
	v_lshl_add_u64 v[200:201], s[40:41], 0, v[170:171]
	s_addc_u32 s65, s41, 0
	s_add_i32 s44, s53, s33
	global_load_lds_dwordx4 v[200:201], off
	v_lshl_add_u64 v[244:245], s[64:65], 0, v[166:167]
	s_mov_b32 m0, s44
	v_lshl_add_u64 v[246:247], s[42:43], 0, v[168:169]
	global_load_lds_dwordx4 v[244:245], off
	v_lshl_add_u64 v[244:245], s[64:65], 0, v[170:171]
	s_add_i32 m0, s44, 0x2000
	s_nop 0
	global_load_lds_dwordx4 v[244:245], off
	v_lshl_add_u64 v[244:245], s[42:43], 0, v[164:165]
	s_mov_b32 m0, s7
	s_nop 0
	global_load_lds_dwordx4 v[244:245], off
	s_mov_b32 m0, s37
	s_nop 0
	global_load_lds_dwordx4 v[246:247], off
	s_waitcnt vmcnt(8)
	s_waitcnt lgkmcnt(0)
	s_barrier
; #define PG8_STAGE(bufoff, gbase, voff) do { _Pragma("unroll") for (int _i = 0; _i < 2; ++_i) \
;         __builtin_amdgcn_global_load_lds((const unsigned*)((const char*)(gbase) + (voff)[_i]), (PG8_LAS unsigned*)(lds + (bufoff) + ldsw + _i * 8192), 16, 0, 0); } while (0)
; #define PG8_LDA(dst, b, h) do { _Pragma("unroll") for (int m = 0; m < 4; ++m) _Pragma("unroll") for (int k = 0; k < 2; ++k) dst[m][k] = *(const PG8_LAS bf16x8*)(lds + PG8_SA(b, h) + aoff + m * 2048 + k * 1024); } while (0)
; #define PG8_LDB(dst, b, h) do { _Pragma("unroll") for (int n = 0; n < 2; ++n) _Pragma("unroll") for (int k = 0; k < 2; ++k) dst[n][k] = *(const PG8_LAS bf16x8*)(lds + PG8_SB(b, h) + boff + n * 2048 + k * 1024); } while (0)
; #define PG8_MMA(ai, bj, At, Bt) do { __builtin_amdgcn_s_setprio(1); _Pragma("unroll") for (int m = 0; m < 4; ++m) _Pragma("unroll") for (int n = 0; n < 2; ++n) _Pragma("unroll") for (int k = 0; k < 2; ++k) \
;         acc[ai][bj][m][n] = __builtin_amdgcn_mfma_f32_16x16x32_bf16(Bt[n][k], At[m][k], acc[ai][bj][m][n], 0, 0, 0); __builtin_amdgcn_s_setprio(0); } while (0)
; #define PG8_WAIT_V(n) asm volatile("s_waitcnt vmcnt(" #n ")" ::: "memory")
; #define PG8_WAIT_L(n) asm volatile("s_waitcnt lgkmcnt(" #n ")" ::: "memory")
; #define PG8_BAR __builtin_amdgcn_s_barrier()
; #define PG8_SCHED __builtin_amdgcn_sched_barrier(0)
; template <class Epi, class Sched, bool ALIGN_EPI = false, bool SP2 = false>
; __device__ __forceinline__ void gemm_phase(PG8_LAS unsigned char* lds, const Gemm g, const Sched& S, const Epi& E) {
;     ...
;             PG8_WAIT_V(8); PG8_WAIT_L(0); PG8_BAR; PG8_MMA(1, 0, At, B0); PG8_MMA(1, 1, At, B1); PG8_BAR; PG8_SCHED;
;             PG8_LDB(B0, 1, 0); PG8_LDB(B1, 1, 1); PG8_SCHED; PG8_LDA(At, 1, 0); PG8_STAGE(PG8_SA(0, 1), a2 + hstep, voffA);
;             PG8_WAIT_V(8); PG8_WAIT_L(0); PG8_BAR; PG8_MMA(0, 0, At, B0); PG8_MMA(0, 1, At, B1); PG8_BAR; PG8_SCHED;
	s_setprio 1
	s_waitcnt lgkmcnt(0)
	v_mfma_f32_16x16x32_bf16 v[60:63], v[136:139], v[212:215], v[60:63]
	v_mfma_f32_16x16x32_bf16 v[60:63], v[140:143], v[216:219], v[60:63]
	v_mfma_f32_16x16x32_bf16 v[56:59], v[176:179], v[216:219], v[56:59]
	v_mfma_f32_16x16x32_bf16 v[56:59], v[172:175], v[212:215], v[56:59]
	v_mfma_f32_16x16x32_bf16 v[52:55], v[180:183], v[212:215], v[52:55]
	v_mfma_f32_16x16x32_bf16 v[52:55], v[184:187], v[216:219], v[52:55]
	v_mfma_f32_16x16x32_bf16 v[44:47], v[208:211], v[216:219], v[44:47]
	v_mfma_f32_16x16x32_bf16 v[44:47], v[196:199], v[212:215], v[44:47]
	v_mfma_f32_16x16x32_bf16 v[28:31], v[196:199], v[220:223], v[28:31]
	v_mfma_f32_16x16x32_bf16 v[28:31], v[208:211], v[224:227], v[28:31]
	v_mfma_f32_16x16x32_bf16 v[36:39], v[184:187], v[224:227], v[36:39]
	v_mfma_f32_16x16x32_bf16 v[36:39], v[180:183], v[220:223], v[36:39]
	v_mfma_f32_16x16x32_bf16 v[40:43], v[172:175], v[220:223], v[40:43]
	v_mfma_f32_16x16x32_bf16 v[40:43], v[176:179], v[224:227], v[40:43]
	v_mfma_f32_16x16x32_bf16 v[48:51], v[140:143], v[224:227], v[48:51]
	v_mfma_f32_16x16x32_bf16 v[48:51], v[136:139], v[220:223], v[48:51]
	s_setprio 0
	s_setprio 1
	v_mfma_f32_16x16x32_bf16 v[32:35], v[136:139], v[228:231], v[32:35]
	v_mfma_f32_16x16x32_bf16 v[32:35], v[140:143], v[232:235], v[32:35]
	v_mfma_f32_16x16x32_bf16 v[24:27], v[176:179], v[232:235], v[24:27]
	v_mfma_f32_16x16x32_bf16 v[24:27], v[172:175], v[228:231], v[24:27]
	v_mfma_f32_16x16x32_bf16 v[20:23], v[180:183], v[228:231], v[20:23]
	v_mfma_f32_16x16x32_bf16 v[20:23], v[184:187], v[232:235], v[20:23]
	v_mfma_f32_16x16x32_bf16 v[16:19], v[208:211], v[232:235], v[16:19]
	v_mfma_f32_16x16x32_bf16 v[16:19], v[196:199], v[228:231], v[16:19]
	v_mfma_f32_16x16x32_bf16 v[0:3], v[196:199], v[236:239], v[0:3]
	v_mfma_f32_16x16x32_bf16 v[0:3], v[208:211], v[240:243], v[0:3]
	v_mfma_f32_16x16x32_bf16 v[4:7], v[184:187], v[240:243], v[4:7]
	v_mfma_f32_16x16x32_bf16 v[4:7], v[180:183], v[236:239], v[4:7]
	v_mfma_f32_16x16x32_bf16 v[8:11], v[172:175], v[236:239], v[8:11]
	v_mfma_f32_16x16x32_bf16 v[8:11], v[176:179], v[240:243], v[8:11]
	s_setprio 3
	s_barrier
	v_mfma_f32_16x16x32_bf16 v[12:15], v[140:143], v[240:243], v[12:15]
	v_mfma_f32_16x16x32_bf16 v[12:15], v[136:139], v[236:239], v[12:15]
	s_setprio 0
	s_add_i32 s44, 0, 0x18000
	v_add_u32_e32 v144, s44, v146
	s_add_i32 s45, 0, 0x1c000
	ds_read_b128 v[136:139], v144
	ds_read_b128 v[140:143], v144 offset:1024
	ds_read_b128 v[172:175], v144 offset:2048
	ds_read_b128 v[176:179], v144 offset:3072
	v_add_u32_e32 v144, s45, v146
	ds_read_b128 v[180:183], v144
	ds_read_b128 v[184:187], v144 offset:1024
	ds_read_b128 v[196:199], v144 offset:2048
	ds_read_b128 v[208:211], v144 offset:3072
	s_add_u32 s42, s42, 0x80000
	s_addc_u32 s43, s43, 0
	s_mov_b32 m0, s48
	v_lshl_add_u64 v[248:249], s[42:43], 0, v[164:165]
	ds_read_b128 v[212:215], v158 offset:32768
	ds_read_b128 v[216:219], v158 offset:33792
	ds_read_b128 v[220:223], v158 offset:34816
	ds_read_b128 v[224:227], v158 offset:35840
	ds_read_b128 v[228:231], v158 offset:36864
	ds_read_b128 v[232:235], v158 offset:37888
	ds_read_b128 v[236:239], v158 offset:38912
	ds_read_b128 v[240:243], v158 offset:39936
	global_load_lds_dwordx4 v[248:249], off
	v_lshl_add_u64 v[248:249], s[42:43], 0, v[168:169]
	s_mov_b32 m0, s49
	s_nop 0
	global_load_lds_dwordx4 v[248:249], off
	s_waitcnt vmcnt(8)
	s_waitcnt lgkmcnt(0)
	s_barrier
	s_setprio 1
	s_waitcnt lgkmcnt(0)
	v_mfma_f32_16x16x32_bf16 v[124:127], v[136:139], v[212:215], v[124:127]
	v_mfma_f32_16x16x32_bf16 v[124:127], v[140:143], v[216:219], v[124:127]
	v_mfma_f32_16x16x32_bf16 v[120:123], v[176:179], v[216:219], v[120:123]
	v_mfma_f32_16x16x32_bf16 v[120:123], v[172:175], v[212:215], v[120:123]
	v_mfma_f32_16x16x32_bf16 v[116:119], v[180:183], v[212:215], v[116:119]
	v_mfma_f32_16x16x32_bf16 v[116:119], v[184:187], v[216:219], v[116:119]
	v_mfma_f32_16x16x32_bf16 v[112:115], v[208:211], v[216:219], v[112:115]
	v_mfma_f32_16x16x32_bf16 v[112:115], v[196:199], v[212:215], v[112:115]
	v_mfma_f32_16x16x32_bf16 v[92:95], v[196:199], v[220:223], v[92:95]
	v_mfma_f32_16x16x32_bf16 v[92:95], v[208:211], v[224:227], v[92:95]
	v_mfma_f32_16x16x32_bf16 v[100:103], v[184:187], v[224:227], v[100:103]
	v_mfma_f32_16x16x32_bf16 v[100:103], v[180:183], v[220:223], v[100:103]
	v_mfma_f32_16x16x32_bf16 v[104:107], v[172:175], v[220:223], v[104:107]
	v_mfma_f32_16x16x32_bf16 v[104:107], v[176:179], v[224:227], v[104:107]
	v_mfma_f32_16x16x32_bf16 v[108:111], v[140:143], v[224:227], v[108:111]
	v_mfma_f32_16x16x32_bf16 v[108:111], v[136:139], v[220:223], v[108:111]
	s_setprio 0
	s_setprio 1
	v_mfma_f32_16x16x32_bf16 v[96:99], v[136:139], v[228:231], v[96:99]
	v_mfma_f32_16x16x32_bf16 v[96:99], v[140:143], v[232:235], v[96:99]
	v_mfma_f32_16x16x32_bf16 v[88:91], v[176:179], v[232:235], v[88:91]
	v_mfma_f32_16x16x32_bf16 v[88:91], v[172:175], v[228:231], v[88:91]
	v_mfma_f32_16x16x32_bf16 v[84:87], v[180:183], v[228:231], v[84:87]
	v_mfma_f32_16x16x32_bf16 v[84:87], v[184:187], v[232:235], v[84:87]
	v_mfma_f32_16x16x32_bf16 v[76:79], v[208:211], v[232:235], v[76:79]
	v_mfma_f32_16x16x32_bf16 v[76:79], v[196:199], v[228:231], v[76:79]
	v_mfma_f32_16x16x32_bf16 v[64:67], v[196:199], v[236:239], v[64:67]
	v_mfma_f32_16x16x32_bf16 v[64:67], v[208:211], v[240:243], v[64:67]
	v_mfma_f32_16x16x32_bf16 v[68:71], v[184:187], v[240:243], v[68:71]
	v_mfma_f32_16x16x32_bf16 v[68:71], v[180:183], v[236:239], v[68:71]
	v_mfma_f32_16x16x32_bf16 v[72:75], v[172:175], v[236:239], v[72:75]
	v_mfma_f32_16x16x32_bf16 v[72:75], v[176:179], v[240:243], v[72:75]
	s_setprio 3
	s_barrier
; #define PG8_STAGE(bufoff, gbase, voff) do { _Pragma("unroll") for (int _i = 0; _i < 2; ++_i) \
;         __builtin_amdgcn_global_load_lds((const unsigned*)((const char*)(gbase) + (voff)[_i]), (PG8_LAS unsigned*)(lds + (bufoff) + ldsw + _i * 8192), 16, 0, 0); } while (0)
; #define PG8_LDA(dst, b, h) do { _Pragma("unroll") for (int m = 0; m < 4; ++m) _Pragma("unroll") for (int k = 0; k < 2; ++k) dst[m][k] = *(const PG8_LAS bf16x8*)(lds + PG8_SA(b, h) + aoff + m * 2048 + k * 1024); } while (0)
; #define PG8_MMA(ai, bj, At, Bt) do { __builtin_amdgcn_s_setprio(1); _Pragma("unroll") for (int m = 0; m < 4; ++m) _Pragma("unroll") for (int n = 0; n < 2; ++n) _Pragma("unroll") for (int k = 0; k < 2; ++k) \
;         acc[ai][bj][m][n] = __builtin_amdgcn_mfma_f32_16x16x32_bf16(Bt[n][k], At[m][k], acc[ai][bj][m][n], 0, 0, 0); __builtin_amdgcn_s_setprio(0); } while (0)
; #define PG8_WAIT_V(n) asm volatile("s_waitcnt vmcnt(" #n ")" ::: "memory")
; #define PG8_WAIT_L(n) asm volatile("s_waitcnt lgkmcnt(" #n ")" ::: "memory")
; #define PG8_BAR __builtin_amdgcn_s_barrier()
; #define PG8_SCHED __builtin_amdgcn_sched_barrier(0)
; template <class Epi, class Sched, bool ALIGN_EPI = false, bool SP2 = false>
; __device__ __forceinline__ void gemm_phase(PG8_LAS unsigned char* lds, const Gemm g, const Sched& S, const Epi& E) {
;     ...
;         for (int t = 0; t < nt; t += 2) {
;     ...
;             PG8_LDA(At, 1, 1); PG8_STAGE(PG8_SB(1, 0), b3, voffB); PG8_STAGE(PG8_SB(1, 1), b3 + hstep, voffB); PG8_STAGE(PG8_SA(1, 0), a3, voffA);
;             PG8_WAIT_V(8); PG8_WAIT_L(0); PG8_BAR; PG8_MMA(1, 0, At, B0); PG8_MMA(1, 1, At, B1); PG8_BAR; PG8_SCHED;
;     ...
;         if constexpr (ALIGN_EPI) { if (wr == 0) PG8_BAR; }
	v_mfma_f32_16x16x32_bf16 v[80:83], v[140:143], v[240:243], v[80:83]
	v_mfma_f32_16x16x32_bf16 v[80:83], v[136:139], v[236:239], v[80:83]
	s_setprio 0
	s_add_i32 s42, s44, s33
	v_lshl_add_u64 v[188:189], v[188:189], 0, s[14:15]
	s_mov_b32 m0, s42
	ds_read_b128 v[212:215], v158 offset:49152
	ds_read_b128 v[216:219], v158 offset:50176
	ds_read_b128 v[220:223], v158 offset:51200
	ds_read_b128 v[224:227], v158 offset:52224
	ds_read_b128 v[228:231], v158 offset:53248
	ds_read_b128 v[232:235], v158 offset:54272
	ds_read_b128 v[236:239], v158 offset:55296
	ds_read_b128 v[240:243], v158 offset:56320
	global_load_lds_dwordx4 v[188:189], off
	s_add_i32 m0, s42, 0x2000
	s_add_u32 s40, s40, 0x80080
	v_lshl_add_u64 v[188:189], v[200:201], 0, s[14:15]
	s_addc_u32 s41, s41, 0
	s_add_i32 s42, s45, s33
	global_load_lds_dwordx4 v[188:189], off
	v_lshl_add_u64 v[188:189], s[40:41], 0, v[166:167]
	s_mov_b32 m0, s42
	s_nop 0
	global_load_lds_dwordx4 v[188:189], off
	v_lshl_add_u64 v[188:189], s[40:41], 0, v[170:171]
	s_add_i32 m0, s42, 0x2000
	s_nop 0
	global_load_lds_dwordx4 v[188:189], off
	v_lshl_add_u64 v[188:189], v[244:245], 0, s[14:15]
	s_mov_b32 m0, s50
	s_nop 0
	global_load_lds_dwordx4 v[188:189], off
	v_lshl_add_u64 v[188:189], v[246:247], 0, s[14:15]
	s_mov_b32 m0, s51
	s_nop 0
	global_load_lds_dwordx4 v[188:189], off
	s_add_i32 s63, s63, 2
	s_add_u32 s38, s38, 0x100
	s_addc_u32 s39, s39, 0
	s_add_u32 s61, s61, 0x100
	s_addc_u32 s62, s62, 0
	s_waitcnt vmcnt(8)
	s_waitcnt lgkmcnt(0)
	s_barrier
	s_setprio 1
	s_waitcnt lgkmcnt(0)
	v_mfma_f32_16x16x32_bf16 v[60:63], v[136:139], v[212:215], v[60:63]
	v_mfma_f32_16x16x32_bf16 v[60:63], v[140:143], v[216:219], v[60:63]
	v_mfma_f32_16x16x32_bf16 v[56:59], v[176:179], v[216:219], v[56:59]
	v_mfma_f32_16x16x32_bf16 v[56:59], v[172:175], v[212:215], v[56:59]
	v_mfma_f32_16x16x32_bf16 v[52:55], v[180:183], v[212:215], v[52:55]
	v_mfma_f32_16x16x32_bf16 v[52:55], v[184:187], v[216:219], v[52:55]
	v_mfma_f32_16x16x32_bf16 v[44:47], v[208:211], v[216:219], v[44:47]
	v_mfma_f32_16x16x32_bf16 v[44:47], v[196:199], v[212:215], v[44:47]
	v_mfma_f32_16x16x32_bf16 v[28:31], v[196:199], v[220:223], v[28:31]
	v_mfma_f32_16x16x32_bf16 v[28:31], v[208:211], v[224:227], v[28:31]
	v_mfma_f32_16x16x32_bf16 v[36:39], v[184:187], v[224:227], v[36:39]
	v_mfma_f32_16x16x32_bf16 v[36:39], v[180:183], v[220:223], v[36:39]
	v_mfma_f32_16x16x32_bf16 v[40:43], v[172:175], v[220:223], v[40:43]
	v_mfma_f32_16x16x32_bf16 v[40:43], v[176:179], v[224:227], v[40:43]
	v_mfma_f32_16x16x32_bf16 v[48:51], v[140:143], v[224:227], v[48:51]
	v_mfma_f32_16x16x32_bf16 v[48:51], v[136:139], v[220:223], v[48:51]
	s_setprio 0
	s_setprio 1
	v_mfma_f32_16x16x32_bf16 v[32:35], v[136:139], v[228:231], v[32:35]
	v_mfma_f32_16x16x32_bf16 v[32:35], v[140:143], v[232:235], v[32:35]
	v_mfma_f32_16x16x32_bf16 v[24:27], v[176:179], v[232:235], v[24:27]
	v_mfma_f32_16x16x32_bf16 v[24:27], v[172:175], v[228:231], v[24:27]
	v_mfma_f32_16x16x32_bf16 v[20:23], v[180:183], v[228:231], v[20:23]
	v_mfma_f32_16x16x32_bf16 v[20:23], v[184:187], v[232:235], v[20:23]
	v_mfma_f32_16x16x32_bf16 v[16:19], v[208:211], v[232:235], v[16:19]
	v_mfma_f32_16x16x32_bf16 v[16:19], v[196:199], v[228:231], v[16:19]
	v_mfma_f32_16x16x32_bf16 v[0:3], v[196:199], v[236:239], v[0:3]
	v_mfma_f32_16x16x32_bf16 v[0:3], v[208:211], v[240:243], v[0:3]
	v_mfma_f32_16x16x32_bf16 v[4:7], v[184:187], v[240:243], v[4:7]
	v_mfma_f32_16x16x32_bf16 v[4:7], v[180:183], v[236:239], v[4:7]
	v_mfma_f32_16x16x32_bf16 v[8:11], v[172:175], v[236:239], v[8:11]
	v_mfma_f32_16x16x32_bf16 v[8:11], v[176:179], v[240:243], v[8:11]
	s_setprio 3
	s_barrier
	v_mfma_f32_16x16x32_bf16 v[12:15], v[140:143], v[240:243], v[12:15]
	v_mfma_f32_16x16x32_bf16 v[12:15], v[136:139], v[236:239], v[12:15]
	s_setprio 0
	s_cmp_gt_u32 s63, 29
	s_cbranch_scc0 .LBB0_880
	s_and_b64 vcc, exec, s[16:17]
	s_cbranch_vccz .LBB0_883
	s_barrier

; #define PG8_STAGE(bufoff, gbase, voff) do { _Pragma("unroll") for (int _i = 0; _i < 2; ++_i) \
;         __builtin_amdgcn_global_load_lds((const unsigned*)((const char*)(gbase) + (voff)[_i]), (PG8_LAS unsigned*)(lds + (bufoff) + ldsw + _i * 8192), 16, 0, 0); } while (0)
; #define PG8_LDA(dst, b, h) do { _Pragma("unroll") for (int m = 0; m < 4; ++m) _Pragma("unroll") for (int k = 0; k < 2; ++k) dst[m][k] = *(const PG8_LAS bf16x8*)(lds + PG8_SA(b, h) + aoff + m * 2048 + k * 1024); } while (0)
; #define PG8_LDB(dst, b, h) do { _Pragma("unroll") for (int n = 0; n < 2; ++n) _Pragma("unroll") for (int k = 0; k < 2; ++k) dst[n][k] = *(const PG8_LAS bf16x8*)(lds + PG8_SB(b, h) + boff + n * 2048 + k * 1024); } while (0)
; #define PG8_MMA(ai, bj, At, Bt) do { __builtin_amdgcn_s_setprio(1); _Pragma("unroll") for (int m = 0; m < 4; ++m) _Pragma("unroll") for (int n = 0; n < 2; ++n) _Pragma("unroll") for (int k = 0; k < 2; ++k) \
;         acc[ai][bj][m][n] = __builtin_amdgcn_mfma_f32_16x16x32_bf16(Bt[n][k], At[m][k], acc[ai][bj][m][n], 0, 0, 0); __builtin_amdgcn_s_setprio(0); } while (0)
; #define PG8_WAIT_V(n) asm volatile("s_waitcnt vmcnt(" #n ")" ::: "memory")
; #define PG8_WAIT_L(n) asm volatile("s_waitcnt lgkmcnt(" #n ")" ::: "memory")
; #define PG8_BAR __builtin_amdgcn_s_barrier()
; template <class Epi, class Sched, bool ALIGN_EPI = false, bool SP2 = false>
; __device__ __forceinline__ void gemm_phase(PG8_LAS unsigned char* lds, const Gemm g, const Sched& S, const Epi& E) {
;     ...
;             const char* a1 = cA + (size_t)(t + 1) * kstep;
;             const char* a2 = last ? nA : cA + (size_t)(t + 2) * kstep; const char* b2 = last ? nB : cB + (size_t)(t + 2) * kstep;
;             const char* a3 = a2 + kstep; const char* b3 = b2 + kstep;
;             if (last && has_next) S.a_ready(nxt);
;             if constexpr (SP2) {
;             PG8_LDB(B0, 0, 0); PG8_LDB(B1, 0, 1); PG8_SCHED; PG8_LDA(At, 0, 0); PG8_STAGE(PG8_SA(1, 1), a1 + hstep, voffA);
;             PG8_WAIT_V(8); PG8_WAIT_L(0); PG8_BAR; PG8_MMA(0, 0, At, B0); PG8_MMA(0, 1, At, B1); PG8_BAR; PG8_SCHED;
;             PG8_LDA(At, 0, 1); PG8_STAGE(PG8_SB(0, 0), b2, voffB); PG8_STAGE(PG8_SB(0, 1), b2 + hstep, voffB); PG8_STAGE(PG8_SA(0, 0), a2, voffA);
;             PG8_WAIT_V(8); PG8_WAIT_L(0); PG8_BAR; PG8_MMA(1, 0, At, B0); PG8_MMA(1, 1, At, B1); PG8_BAR; PG8_SCHED;
.LBB0_937:
	ds_read_b128 v[128:131], v199
	ds_read_b128 v[132:135], v199 offset:1024
	ds_read_b128 v[136:139], v199 offset:2048
	ds_read_b128 v[140:143], v199 offset:3072
	ds_read_b128 v[150:153], v200
	ds_read_b128 v[154:157], v200 offset:1024
	ds_read_b128 v[164:167], v200 offset:2048
	ds_read_b128 v[168:171], v200 offset:3072
	s_add_u32 s22, s20, 0xffea0080
	s_addc_u32 s23, s21, -1
	s_cmpk_eq_i32 s49, 0x54
	s_cselect_b32 s25, s17, s23
	s_cselect_b32 s24, s16, s22
	s_cselect_b32 s23, s19, s48
	s_cselect_b32 s22, s18, s47
	v_lshl_add_u64 v[158:159], s[20:21], 0, v[144:145]
	s_add_i32 m0, s31, 0xc000
	ds_read_b128 v[172:175], v201
	ds_read_b128 v[176:179], v201 offset:1024
	ds_read_b128 v[180:183], v201 offset:2048
	ds_read_b128 v[184:187], v201 offset:3072
	ds_read_b128 v[188:191], v201 offset:4096
	ds_read_b128 v[204:207], v201 offset:5120
	ds_read_b128 v[208:211], v201 offset:6144
	ds_read_b128 v[212:215], v201 offset:7168
	global_load_lds_dwordx4 v[158:159], off
	v_lshl_add_u64 v[158:159], s[20:21], 0, v[146:147]
	s_add_i32 m0, s31, 0xe000
	s_nop 0
	global_load_lds_dwordx4 v[158:159], off
	s_waitcnt vmcnt(8)
	s_waitcnt lgkmcnt(0)
	s_barrier
	s_setprio 1
	s_waitcnt lgkmcnt(0)
	v_mfma_f32_16x16x32_bf16 v[124:127], v[128:131], v[172:175], v[124:127]
	v_mfma_f32_16x16x32_bf16 v[124:127], v[132:135], v[176:179], v[124:127]
	v_mfma_f32_16x16x32_bf16 v[120:123], v[140:143], v[176:179], v[120:123]
	v_mfma_f32_16x16x32_bf16 v[120:123], v[136:139], v[172:175], v[120:123]
	v_mfma_f32_16x16x32_bf16 v[116:119], v[150:153], v[172:175], v[116:119]
	v_mfma_f32_16x16x32_bf16 v[116:119], v[154:157], v[176:179], v[116:119]
	v_mfma_f32_16x16x32_bf16 v[112:115], v[168:171], v[176:179], v[112:115]
	v_mfma_f32_16x16x32_bf16 v[112:115], v[164:167], v[172:175], v[112:115]
	v_mfma_f32_16x16x32_bf16 v[96:99], v[164:167], v[180:183], v[96:99]
	v_mfma_f32_16x16x32_bf16 v[96:99], v[168:171], v[184:187], v[96:99]
	v_mfma_f32_16x16x32_bf16 v[100:103], v[154:157], v[184:187], v[100:103]
	v_mfma_f32_16x16x32_bf16 v[100:103], v[150:153], v[180:183], v[100:103]
	v_mfma_f32_16x16x32_bf16 v[104:107], v[136:139], v[180:183], v[104:107]
	v_mfma_f32_16x16x32_bf16 v[104:107], v[140:143], v[184:187], v[104:107]
	v_mfma_f32_16x16x32_bf16 v[108:111], v[132:135], v[184:187], v[108:111]
	v_mfma_f32_16x16x32_bf16 v[108:111], v[128:131], v[180:183], v[108:111]
	s_setprio 0
	s_setprio 1
	v_mfma_f32_16x16x32_bf16 v[92:95], v[128:131], v[188:191], v[92:95]
	v_mfma_f32_16x16x32_bf16 v[92:95], v[132:135], v[204:207], v[92:95]
	v_mfma_f32_16x16x32_bf16 v[88:91], v[140:143], v[204:207], v[88:91]
	v_mfma_f32_16x16x32_bf16 v[88:91], v[136:139], v[188:191], v[88:91]
	v_mfma_f32_16x16x32_bf16 v[84:87], v[150:153], v[188:191], v[84:87]
	v_mfma_f32_16x16x32_bf16 v[84:87], v[154:157], v[204:207], v[84:87]
	v_mfma_f32_16x16x32_bf16 v[80:83], v[168:171], v[204:207], v[80:83]
	v_mfma_f32_16x16x32_bf16 v[80:83], v[164:167], v[188:191], v[80:83]
	v_mfma_f32_16x16x32_bf16 v[64:67], v[164:167], v[208:211], v[64:67]
	v_mfma_f32_16x16x32_bf16 v[64:67], v[168:171], v[212:215], v[64:67]
	v_mfma_f32_16x16x32_bf16 v[68:71], v[154:157], v[212:215], v[68:71]
	v_mfma_f32_16x16x32_bf16 v[68:71], v[150:153], v[208:211], v[68:71]
	v_mfma_f32_16x16x32_bf16 v[72:75], v[136:139], v[208:211], v[72:75]
	v_mfma_f32_16x16x32_bf16 v[72:75], v[140:143], v[212:215], v[72:75]
	s_setprio 3
	s_barrier
	v_mfma_f32_16x16x32_bf16 v[76:79], v[132:135], v[212:215], v[76:79]
	v_mfma_f32_16x16x32_bf16 v[76:79], v[128:131], v[208:211], v[76:79]
	s_setprio 0
	s_add_i32 s50, s41, s30
	v_lshl_add_u64 v[158:159], s[22:23], 0, v[160:161]
	s_mov_b32 m0, s50
	ds_read_b128 v[172:175], v201 offset:16384
	ds_read_b128 v[176:179], v201 offset:17408
	ds_read_b128 v[180:183], v201 offset:18432
	ds_read_b128 v[184:187], v201 offset:19456
	ds_read_b128 v[188:191], v201 offset:20480
	ds_read_b128 v[204:207], v201 offset:21504
	ds_read_b128 v[208:211], v201 offset:22528
	ds_read_b128 v[212:215], v201 offset:23552
	global_load_lds_dwordx4 v[158:159], off
	s_add_i32 m0, s50, 0x2000
	s_add_u32 s50, s22, 0x160000
	v_lshl_add_u64 v[192:193], s[22:23], 0, v[162:163]
	s_addc_u32 s51, s23, 0
	s_add_i32 s52, s42, s30
	global_load_lds_dwordx4 v[192:193], off
	v_lshl_add_u64 v[216:217], s[50:51], 0, v[160:161]
	s_mov_b32 m0, s52
	v_lshl_add_u64 v[218:219], s[24:25], 0, v[162:163]
	global_load_lds_dwordx4 v[216:217], off
	v_lshl_add_u64 v[216:217], s[50:51], 0, v[162:163]
	s_add_i32 m0, s52, 0x2000
	s_nop 0
	global_load_lds_dwordx4 v[216:217], off
	v_lshl_add_u64 v[216:217], s[24:25], 0, v[160:161]
	s_mov_b32 m0, s31
	s_nop 0
	global_load_lds_dwordx4 v[216:217], off
	s_mov_b32 m0, s33
	s_nop 0
	global_load_lds_dwordx4 v[218:219], off
	s_waitcnt vmcnt(8)
	s_waitcnt lgkmcnt(0)
	s_barrier
; #define PG8_STAGE(bufoff, gbase, voff) do { _Pragma("unroll") for (int _i = 0; _i < 2; ++_i) \
;         __builtin_amdgcn_global_load_lds((const unsigned*)((const char*)(gbase) + (voff)[_i]), (PG8_LAS unsigned*)(lds + (bufoff) + ldsw + _i * 8192), 16, 0, 0); } while (0)
; #define PG8_LDA(dst, b, h) do { _Pragma("unroll") for (int m = 0; m < 4; ++m) _Pragma("unroll") for (int k = 0; k < 2; ++k) dst[m][k] = *(const PG8_LAS bf16x8*)(lds + PG8_SA(b, h) + aoff + m * 2048 + k * 1024); } while (0)
; #define PG8_LDB(dst, b, h) do { _Pragma("unroll") for (int n = 0; n < 2; ++n) _Pragma("unroll") for (int k = 0; k < 2; ++k) dst[n][k] = *(const PG8_LAS bf16x8*)(lds + PG8_SB(b, h) + boff + n * 2048 + k * 1024); } while (0)
; #define PG8_MMA(ai, bj, At, Bt) do { __builtin_amdgcn_s_setprio(1); _Pragma("unroll") for (int m = 0; m < 4; ++m) _Pragma("unroll") for (int n = 0; n < 2; ++n) _Pragma("unroll") for (int k = 0; k < 2; ++k) \
;         acc[ai][bj][m][n] = __builtin_amdgcn_mfma_f32_16x16x32_bf16(Bt[n][k], At[m][k], acc[ai][bj][m][n], 0, 0, 0); __builtin_amdgcn_s_setprio(0); } while (0)
; #define PG8_WAIT_V(n) asm volatile("s_waitcnt vmcnt(" #n ")" ::: "memory")
; #define PG8_WAIT_L(n) asm volatile("s_waitcnt lgkmcnt(" #n ")" ::: "memory")
; #define PG8_BAR __builtin_amdgcn_s_barrier()
; #define PG8_SCHED __builtin_amdgcn_sched_barrier(0)
; template <class Epi, class Sched, bool ALIGN_EPI = false, bool SP2 = false>
; __device__ __forceinline__ void gemm_phase(PG8_LAS unsigned char* lds, const Gemm g, const Sched& S, const Epi& E) {
;     ...
;             PG8_WAIT_V(8); PG8_WAIT_L(0); PG8_BAR; PG8_MMA(1, 0, At, B0); PG8_MMA(1, 1, At, B1); PG8_BAR; PG8_SCHED;
;             PG8_LDB(B0, 1, 0); PG8_LDB(B1, 1, 1); PG8_SCHED; PG8_LDA(At, 1, 0); PG8_STAGE(PG8_SA(0, 1), a2 + hstep, voffA);
;             PG8_WAIT_V(8); PG8_WAIT_L(0); PG8_BAR; PG8_MMA(0, 0, At, B0); PG8_MMA(0, 1, At, B1); PG8_BAR; PG8_SCHED;
	s_setprio 1
	s_waitcnt lgkmcnt(0)
	v_mfma_f32_16x16x32_bf16 v[60:63], v[128:131], v[172:175], v[60:63]
	v_mfma_f32_16x16x32_bf16 v[60:63], v[132:135], v[176:179], v[60:63]
	v_mfma_f32_16x16x32_bf16 v[56:59], v[140:143], v[176:179], v[56:59]
	v_mfma_f32_16x16x32_bf16 v[56:59], v[136:139], v[172:175], v[56:59]
	v_mfma_f32_16x16x32_bf16 v[52:55], v[150:153], v[172:175], v[52:55]
	v_mfma_f32_16x16x32_bf16 v[52:55], v[154:157], v[176:179], v[52:55]
	v_mfma_f32_16x16x32_bf16 v[48:51], v[168:171], v[176:179], v[48:51]
	v_mfma_f32_16x16x32_bf16 v[48:51], v[164:167], v[172:175], v[48:51]
	v_mfma_f32_16x16x32_bf16 v[32:35], v[164:167], v[180:183], v[32:35]
	v_mfma_f32_16x16x32_bf16 v[32:35], v[168:171], v[184:187], v[32:35]
	v_mfma_f32_16x16x32_bf16 v[36:39], v[154:157], v[184:187], v[36:39]
	v_mfma_f32_16x16x32_bf16 v[36:39], v[150:153], v[180:183], v[36:39]
	v_mfma_f32_16x16x32_bf16 v[40:43], v[136:139], v[180:183], v[40:43]
	v_mfma_f32_16x16x32_bf16 v[40:43], v[140:143], v[184:187], v[40:43]
	v_mfma_f32_16x16x32_bf16 v[44:47], v[132:135], v[184:187], v[44:47]
	v_mfma_f32_16x16x32_bf16 v[44:47], v[128:131], v[180:183], v[44:47]
	s_setprio 0
	s_setprio 1
	v_mfma_f32_16x16x32_bf16 v[28:31], v[128:131], v[188:191], v[28:31]
	v_mfma_f32_16x16x32_bf16 v[28:31], v[132:135], v[204:207], v[28:31]
	v_mfma_f32_16x16x32_bf16 v[24:27], v[140:143], v[204:207], v[24:27]
	v_mfma_f32_16x16x32_bf16 v[24:27], v[136:139], v[188:191], v[24:27]
	v_mfma_f32_16x16x32_bf16 v[20:23], v[150:153], v[188:191], v[20:23]
	v_mfma_f32_16x16x32_bf16 v[20:23], v[154:157], v[204:207], v[20:23]
	v_mfma_f32_16x16x32_bf16 v[16:19], v[168:171], v[204:207], v[16:19]
	v_mfma_f32_16x16x32_bf16 v[16:19], v[164:167], v[188:191], v[16:19]
	v_mfma_f32_16x16x32_bf16 v[0:3], v[164:167], v[208:211], v[0:3]
	v_mfma_f32_16x16x32_bf16 v[0:3], v[168:171], v[212:215], v[0:3]
	v_mfma_f32_16x16x32_bf16 v[4:7], v[154:157], v[212:215], v[4:7]
	v_mfma_f32_16x16x32_bf16 v[4:7], v[150:153], v[208:211], v[4:7]
	v_mfma_f32_16x16x32_bf16 v[8:11], v[136:139], v[208:211], v[8:11]
	v_mfma_f32_16x16x32_bf16 v[8:11], v[140:143], v[212:215], v[8:11]
	s_setprio 3
	s_barrier
	v_mfma_f32_16x16x32_bf16 v[12:15], v[132:135], v[212:215], v[12:15]
	v_mfma_f32_16x16x32_bf16 v[12:15], v[128:131], v[208:211], v[12:15]
	s_setprio 0
	s_add_i32 s50, 0, 0x18000
	s_add_i32 s51, 0, 0x1c000
	v_add_u32_e32 v140, s50, v196
	v_add_u32_e32 v168, s51, v196
	ds_read_b128 v[128:131], v140
	ds_read_b128 v[132:135], v140 offset:1024
	ds_read_b128 v[136:139], v140 offset:2048
	ds_read_b128 v[140:143], v140 offset:3072
	ds_read_b128 v[150:153], v168
	ds_read_b128 v[154:157], v168 offset:1024
	ds_read_b128 v[164:167], v168 offset:2048
	ds_read_b128 v[168:171], v168 offset:3072
	s_add_u32 s24, s24, 0x160000
	s_addc_u32 s25, s25, 0
	s_mov_b32 m0, s34
	v_lshl_add_u64 v[220:221], s[24:25], 0, v[160:161]
	ds_read_b128 v[172:175], v201 offset:32768
	ds_read_b128 v[176:179], v201 offset:33792
	ds_read_b128 v[180:183], v201 offset:34816
	ds_read_b128 v[184:187], v201 offset:35840
	ds_read_b128 v[188:191], v201 offset:36864
	ds_read_b128 v[204:207], v201 offset:37888
	ds_read_b128 v[208:211], v201 offset:38912
	ds_read_b128 v[212:215], v201 offset:39936
	global_load_lds_dwordx4 v[220:221], off
	v_lshl_add_u64 v[220:221], s[24:25], 0, v[162:163]
	s_mov_b32 m0, s35
	s_nop 0
	global_load_lds_dwordx4 v[220:221], off
	s_waitcnt vmcnt(8)
	s_waitcnt lgkmcnt(0)
	s_barrier
	s_setprio 1
	s_waitcnt lgkmcnt(0)
	v_mfma_f32_16x16x32_bf16 v[124:127], v[128:131], v[172:175], v[124:127]
	v_mfma_f32_16x16x32_bf16 v[124:127], v[132:135], v[176:179], v[124:127]
	v_mfma_f32_16x16x32_bf16 v[120:123], v[140:143], v[176:179], v[120:123]
	v_mfma_f32_16x16x32_bf16 v[120:123], v[136:139], v[172:175], v[120:123]
	v_mfma_f32_16x16x32_bf16 v[116:119], v[150:153], v[172:175], v[116:119]
	v_mfma_f32_16x16x32_bf16 v[116:119], v[154:157], v[176:179], v[116:119]
	v_mfma_f32_16x16x32_bf16 v[112:115], v[168:171], v[176:179], v[112:115]
	v_mfma_f32_16x16x32_bf16 v[112:115], v[164:167], v[172:175], v[112:115]
	v_mfma_f32_16x16x32_bf16 v[96:99], v[164:167], v[180:183], v[96:99]
	v_mfma_f32_16x16x32_bf16 v[96:99], v[168:171], v[184:187], v[96:99]
	v_mfma_f32_16x16x32_bf16 v[100:103], v[154:157], v[184:187], v[100:103]
	v_mfma_f32_16x16x32_bf16 v[100:103], v[150:153], v[180:183], v[100:103]
	v_mfma_f32_16x16x32_bf16 v[104:107], v[136:139], v[180:183], v[104:107]
	v_mfma_f32_16x16x32_bf16 v[104:107], v[140:143], v[184:187], v[104:107]
	v_mfma_f32_16x16x32_bf16 v[108:111], v[132:135], v[184:187], v[108:111]
	v_mfma_f32_16x16x32_bf16 v[108:111], v[128:131], v[180:183], v[108:111]
	s_setprio 0
	s_setprio 1
	v_mfma_f32_16x16x32_bf16 v[92:95], v[128:131], v[188:191], v[92:95]
	v_mfma_f32_16x16x32_bf16 v[92:95], v[132:135], v[204:207], v[92:95]
	v_mfma_f32_16x16x32_bf16 v[88:91], v[140:143], v[204:207], v[88:91]
	v_mfma_f32_16x16x32_bf16 v[88:91], v[136:139], v[188:191], v[88:91]
	v_mfma_f32_16x16x32_bf16 v[84:87], v[150:153], v[188:191], v[84:87]
	v_mfma_f32_16x16x32_bf16 v[84:87], v[154:157], v[204:207], v[84:87]
	v_mfma_f32_16x16x32_bf16 v[80:83], v[168:171], v[204:207], v[80:83]
	v_mfma_f32_16x16x32_bf16 v[80:83], v[164:167], v[188:191], v[80:83]
	v_mfma_f32_16x16x32_bf16 v[64:67], v[164:167], v[208:211], v[64:67]
	v_mfma_f32_16x16x32_bf16 v[64:67], v[168:171], v[212:215], v[64:67]
	v_mfma_f32_16x16x32_bf16 v[68:71], v[154:157], v[212:215], v[68:71]
	v_mfma_f32_16x16x32_bf16 v[68:71], v[150:153], v[208:211], v[68:71]
	v_mfma_f32_16x16x32_bf16 v[72:75], v[136:139], v[208:211], v[72:75]
	v_mfma_f32_16x16x32_bf16 v[72:75], v[140:143], v[212:215], v[72:75]
	s_setprio 3
	s_barrier
; #define PG8_STAGE(bufoff, gbase, voff) do { _Pragma("unroll") for (int _i = 0; _i < 2; ++_i) \
;         __builtin_amdgcn_global_load_lds((const unsigned*)((const char*)(gbase) + (voff)[_i]), (PG8_LAS unsigned*)(lds + (bufoff) + ldsw + _i * 8192), 16, 0, 0); } while (0)
; #define PG8_LDA(dst, b, h) do { _Pragma("unroll") for (int m = 0; m < 4; ++m) _Pragma("unroll") for (int k = 0; k < 2; ++k) dst[m][k] = *(const PG8_LAS bf16x8*)(lds + PG8_SA(b, h) + aoff + m * 2048 + k * 1024); } while (0)
; #define PG8_MMA(ai, bj, At, Bt) do { __builtin_amdgcn_s_setprio(1); _Pragma("unroll") for (int m = 0; m < 4; ++m) _Pragma("unroll") for (int n = 0; n < 2; ++n) _Pragma("unroll") for (int k = 0; k < 2; ++k) \
;         acc[ai][bj][m][n] = __builtin_amdgcn_mfma_f32_16x16x32_bf16(Bt[n][k], At[m][k], acc[ai][bj][m][n], 0, 0, 0); __builtin_amdgcn_s_setprio(0); } while (0)
; #define PG8_WAIT_V(n) asm volatile("s_waitcnt vmcnt(" #n ")" ::: "memory")
; #define PG8_WAIT_L(n) asm volatile("s_waitcnt lgkmcnt(" #n ")" ::: "memory")
; #define PG8_BAR __builtin_amdgcn_s_barrier()
; #define PG8_SCHED __builtin_amdgcn_sched_barrier(0)
; template <class Epi, class Sched, bool ALIGN_EPI = false, bool SP2 = false>
; __device__ __forceinline__ void gemm_phase(PG8_LAS unsigned char* lds, const Gemm g, const Sched& S, const Epi& E) {
;     ...
;         for (int t = 0; t < nt; t += 2) {
;     ...
;             PG8_LDA(At, 1, 1); PG8_STAGE(PG8_SB(1, 0), b3, voffB); PG8_STAGE(PG8_SB(1, 1), b3 + hstep, voffB); PG8_STAGE(PG8_SA(1, 0), a3, voffA);
;             PG8_WAIT_V(8); PG8_WAIT_L(0); PG8_BAR; PG8_MMA(1, 0, At, B0); PG8_MMA(1, 1, At, B1); PG8_BAR; PG8_SCHED;
;     ...
;         if constexpr (ALIGN_EPI) { if (wr == 0) PG8_BAR; }
	v_mfma_f32_16x16x32_bf16 v[76:79], v[132:135], v[212:215], v[76:79]
	v_mfma_f32_16x16x32_bf16 v[76:79], v[128:131], v[208:211], v[76:79]
	s_setprio 0
	s_add_i32 s24, s50, s30
	v_lshl_add_u64 v[158:159], v[158:159], 0, s[12:13]
	s_mov_b32 m0, s24
	ds_read_b128 v[172:175], v201 offset:49152
	ds_read_b128 v[176:179], v201 offset:50176
	ds_read_b128 v[180:183], v201 offset:51200
	ds_read_b128 v[184:187], v201 offset:52224
	ds_read_b128 v[188:191], v201 offset:53248
	ds_read_b128 v[204:207], v201 offset:54272
	ds_read_b128 v[208:211], v201 offset:55296
	ds_read_b128 v[212:215], v201 offset:56320
	global_load_lds_dwordx4 v[158:159], off
	s_add_i32 m0, s24, 0x2000
	s_add_u32 s22, s22, 0x160080
	v_lshl_add_u64 v[158:159], v[192:193], 0, s[12:13]
	s_addc_u32 s23, s23, 0
	s_add_i32 s24, s51, s30
	global_load_lds_dwordx4 v[158:159], off
	v_lshl_add_u64 v[158:159], s[22:23], 0, v[160:161]
	s_mov_b32 m0, s24
	s_nop 0
	global_load_lds_dwordx4 v[158:159], off
	v_lshl_add_u64 v[158:159], s[22:23], 0, v[162:163]
	s_add_i32 m0, s24, 0x2000
	s_nop 0
	global_load_lds_dwordx4 v[158:159], off
	v_lshl_add_u64 v[158:159], v[216:217], 0, s[12:13]
	s_mov_b32 m0, s39
	s_nop 0
	global_load_lds_dwordx4 v[158:159], off
	v_lshl_add_u64 v[158:159], v[218:219], 0, s[12:13]
	s_mov_b32 m0, s40
	s_nop 0
	global_load_lds_dwordx4 v[158:159], off
	s_add_i32 s49, s49, 2
	s_add_u32 s20, s20, 0x100
	s_addc_u32 s21, s21, 0
	s_add_u32 s47, s47, 0x100
	s_addc_u32 s48, s48, 0
	s_waitcnt vmcnt(8)
	s_waitcnt lgkmcnt(0)
	s_barrier
	s_setprio 1
	s_waitcnt lgkmcnt(0)
	v_mfma_f32_16x16x32_bf16 v[60:63], v[128:131], v[172:175], v[60:63]
	v_mfma_f32_16x16x32_bf16 v[60:63], v[132:135], v[176:179], v[60:63]
	v_mfma_f32_16x16x32_bf16 v[56:59], v[140:143], v[176:179], v[56:59]
	v_mfma_f32_16x16x32_bf16 v[56:59], v[136:139], v[172:175], v[56:59]
	v_mfma_f32_16x16x32_bf16 v[52:55], v[150:153], v[172:175], v[52:55]
	v_mfma_f32_16x16x32_bf16 v[52:55], v[154:157], v[176:179], v[52:55]
	v_mfma_f32_16x16x32_bf16 v[48:51], v[168:171], v[176:179], v[48:51]
	v_mfma_f32_16x16x32_bf16 v[48:51], v[164:167], v[172:175], v[48:51]
	v_mfma_f32_16x16x32_bf16 v[32:35], v[164:167], v[180:183], v[32:35]
	v_mfma_f32_16x16x32_bf16 v[32:35], v[168:171], v[184:187], v[32:35]
	v_mfma_f32_16x16x32_bf16 v[36:39], v[154:157], v[184:187], v[36:39]
	v_mfma_f32_16x16x32_bf16 v[36:39], v[150:153], v[180:183], v[36:39]
	v_mfma_f32_16x16x32_bf16 v[40:43], v[136:139], v[180:183], v[40:43]
	v_mfma_f32_16x16x32_bf16 v[40:43], v[140:143], v[184:187], v[40:43]
	v_mfma_f32_16x16x32_bf16 v[44:47], v[132:135], v[184:187], v[44:47]
	v_mfma_f32_16x16x32_bf16 v[44:47], v[128:131], v[180:183], v[44:47]
	s_setprio 0
	s_setprio 1
	v_mfma_f32_16x16x32_bf16 v[28:31], v[128:131], v[188:191], v[28:31]
	v_mfma_f32_16x16x32_bf16 v[28:31], v[132:135], v[204:207], v[28:31]
	v_mfma_f32_16x16x32_bf16 v[24:27], v[140:143], v[204:207], v[24:27]
	v_mfma_f32_16x16x32_bf16 v[24:27], v[136:139], v[188:191], v[24:27]
	v_mfma_f32_16x16x32_bf16 v[20:23], v[150:153], v[188:191], v[20:23]
	v_mfma_f32_16x16x32_bf16 v[20:23], v[154:157], v[204:207], v[20:23]
	v_mfma_f32_16x16x32_bf16 v[16:19], v[168:171], v[204:207], v[16:19]
	v_mfma_f32_16x16x32_bf16 v[16:19], v[164:167], v[188:191], v[16:19]
	v_mfma_f32_16x16x32_bf16 v[0:3], v[164:167], v[208:211], v[0:3]
	v_mfma_f32_16x16x32_bf16 v[0:3], v[168:171], v[212:215], v[0:3]
	v_mfma_f32_16x16x32_bf16 v[4:7], v[154:157], v[212:215], v[4:7]
	v_mfma_f32_16x16x32_bf16 v[4:7], v[150:153], v[208:211], v[4:7]
	v_mfma_f32_16x16x32_bf16 v[8:11], v[136:139], v[208:211], v[8:11]
	v_mfma_f32_16x16x32_bf16 v[8:11], v[140:143], v[212:215], v[8:11]
	s_setprio 3
	s_barrier
	v_mfma_f32_16x16x32_bf16 v[12:15], v[132:135], v[212:215], v[12:15]
	v_mfma_f32_16x16x32_bf16 v[12:15], v[128:131], v[208:211], v[12:15]
	s_setprio 0
	s_cmpk_gt_u32 s49, 0x55
	s_cbranch_scc0 .LBB0_937
	s_and_b64 vcc, exec, s[14:15]
	s_cbranch_vccz .LBB0_940
	s_barrier
